# prep: hand-written adaLN item, the 34 conditioning + 128 weight loads of a lane all in flight (baseline waited vmcnt(0) after each load)
# speedup vs baseline: 1.0205x; 1.0195x over previous
.LBB0_263:
	s_barrier
	s_sub_i32 s4, 0x1025, s93
	s_cmp_ge_u32 s4, 0x60
	s_cselect_b32 s5, 1, 0
	s_mul_i32 s6, s5, 0x60
	s_sub_i32 s4, s4, s6
	s_lshl_b32 s6, s4, 8
	v_readlane_b32 s70, v254, 39
	v_readlane_b32 s71, v254, 40
	v_readlane_b32 s74, v254, 43
	v_readlane_b32 s75, v254, 44
	v_readlane_b32 s76, v254, 45
	v_readlane_b32 s77, v254, 46
	v_lshlrev_b32_e32 v16, 2, v222
	v_and_b32_e32 v17, 63, v222
	v_lshrrev_b32_e32 v18, 6, v222
	s_mov_b64 s[8:9], s[70:71]
	global_load_dword v212, v16, s[8:9]
	s_add_u32 s8, s8, 0x800
	s_addc_u32 s9, s9, 0
	global_load_dword v213, v16, s[8:9]
	s_add_u32 s8, s8, 0x800
	s_addc_u32 s9, s9, 0
	global_load_dword v214, v16, s[8:9]
	s_add_u32 s8, s8, 0x800
	s_addc_u32 s9, s9, 0
	global_load_dword v215, v16, s[8:9]
	s_add_u32 s8, s8, 0x800
	s_addc_u32 s9, s9, 0
	global_load_dword v216, v16, s[8:9]
	s_add_u32 s8, s8, 0x800
	s_addc_u32 s9, s9, 0
	global_load_dword v217, v16, s[8:9]
	s_add_u32 s8, s8, 0x800
	s_addc_u32 s9, s9, 0
	global_load_dword v218, v16, s[8:9]
	s_add_u32 s8, s8, 0x800
	s_addc_u32 s9, s9, 0
	global_load_dword v219, v16, s[8:9]
	s_add_u32 s8, s8, 0x800
	s_addc_u32 s9, s9, 0
	global_load_dword v220, v16, s[8:9]
	s_add_u32 s8, s8, 0x800
	s_addc_u32 s9, s9, 0
	global_load_dword v221, v16, s[8:9]
	s_add_u32 s8, s8, 0x800
	s_addc_u32 s9, s9, 0
	global_load_dword v229, v16, s[8:9]
	s_add_u32 s8, s8, 0x800
	s_addc_u32 s9, s9, 0
	global_load_dword v230, v16, s[8:9]
	s_add_u32 s8, s8, 0x800
	s_addc_u32 s9, s9, 0
	global_load_dword v231, v16, s[8:9]
	s_add_u32 s8, s8, 0x800
	s_addc_u32 s9, s9, 0
	global_load_dword v232, v16, s[8:9]
	s_add_u32 s8, s8, 0x800
	s_addc_u32 s9, s9, 0
	global_load_dword v233, v16, s[8:9]
	s_add_u32 s8, s8, 0x800
	s_addc_u32 s9, s9, 0
	global_load_dword v234, v16, s[8:9]
	s_add_u32 s8, s8, 0x800
	s_addc_u32 s9, s9, 0
	global_load_dword v235, v16, s[8:9]
	s_add_u32 s8, s8, 0x800
	s_addc_u32 s9, s9, 0
	global_load_dword v236, v16, s[8:9]
	s_add_u32 s8, s8, 0x800
	s_addc_u32 s9, s9, 0
	global_load_dword v237, v16, s[8:9]
	s_add_u32 s8, s8, 0x800
	s_addc_u32 s9, s9, 0
	global_load_dword v238, v16, s[8:9]
	s_add_u32 s8, s8, 0x800
	s_addc_u32 s9, s9, 0
	global_load_dword v239, v16, s[8:9]
	s_add_u32 s8, s8, 0x800
	s_addc_u32 s9, s9, 0
	global_load_dword v240, v16, s[8:9]
	s_add_u32 s8, s8, 0x800
	s_addc_u32 s9, s9, 0
	global_load_dword v241, v16, s[8:9]
	s_add_u32 s8, s8, 0x800
	s_addc_u32 s9, s9, 0
	global_load_dword v242, v16, s[8:9]
	s_add_u32 s8, s8, 0x800
	s_addc_u32 s9, s9, 0
	global_load_dword v243, v16, s[8:9]
	s_add_u32 s8, s8, 0x800
	s_addc_u32 s9, s9, 0
	global_load_dword v244, v16, s[8:9]
	s_add_u32 s8, s8, 0x800
	s_addc_u32 s9, s9, 0
	global_load_dword v245, v16, s[8:9]
	s_add_u32 s8, s8, 0x800
	s_addc_u32 s9, s9, 0
	global_load_dword v246, v16, s[8:9]
	s_add_u32 s8, s8, 0x800
	s_addc_u32 s9, s9, 0
	global_load_dword v247, v16, s[8:9]
	s_add_u32 s8, s8, 0x800
	s_addc_u32 s9, s9, 0
	global_load_dword v248, v16, s[8:9]
	s_add_u32 s8, s8, 0x800
	s_addc_u32 s9, s9, 0
	global_load_dword v249, v16, s[8:9]
	s_add_u32 s8, s8, 0x800
	s_addc_u32 s9, s9, 0
	global_load_dword v250, v16, s[8:9]
	global_load_dword v251, v16, s[74:75]
	global_load_dword v252, v16, s[74:75] offset:2048
	s_mul_i32 s7, s5, 0x1800000
	s_add_u32 s68, s76, s7
	s_addc_u32 s69, s77, 0
	s_add_u32 s68, s68, s6
	s_addc_u32 s69, s69, 0
	v_mul_u32_u24_e32 v14, 0xc0000, v18
	v_lshl_add_u32 v14, v17, 2, v14
	s_nop 1
	global_load_dword v84, v14, s[68:69]
	s_add_u32 s68, s68, 0x6000
	s_addc_u32 s69, s69, 0
	global_load_dword v85, v14, s[68:69]
	s_add_u32 s68, s68, 0x6000
	s_addc_u32 s69, s69, 0
	global_load_dword v86, v14, s[68:69]
	s_add_u32 s68, s68, 0x6000
	s_addc_u32 s69, s69, 0
	global_load_dword v87, v14, s[68:69]
	s_add_u32 s68, s68, 0x6000
	s_addc_u32 s69, s69, 0
	global_load_dword v88, v14, s[68:69]
	s_add_u32 s68, s68, 0x6000
	s_addc_u32 s69, s69, 0
	global_load_dword v89, v14, s[68:69]
	s_add_u32 s68, s68, 0x6000
	s_addc_u32 s69, s69, 0
	global_load_dword v90, v14, s[68:69]
	s_add_u32 s68, s68, 0x6000
	s_addc_u32 s69, s69, 0
	global_load_dword v91, v14, s[68:69]
	s_add_u32 s68, s68, 0x6000
	s_addc_u32 s69, s69, 0
	global_load_dword v92, v14, s[68:69]
	s_add_u32 s68, s68, 0x6000
	s_addc_u32 s69, s69, 0
	global_load_dword v93, v14, s[68:69]
	s_add_u32 s68, s68, 0x6000
	s_addc_u32 s69, s69, 0
	global_load_dword v94, v14, s[68:69]
	s_add_u32 s68, s68, 0x6000
	s_addc_u32 s69, s69, 0
	global_load_dword v95, v14, s[68:69]
	s_add_u32 s68, s68, 0x6000
	s_addc_u32 s69, s69, 0
	global_load_dword v96, v14, s[68:69]
	s_add_u32 s68, s68, 0x6000
	s_addc_u32 s69, s69, 0
	global_load_dword v97, v14, s[68:69]
	s_add_u32 s68, s68, 0x6000
	s_addc_u32 s69, s69, 0
	global_load_dword v98, v14, s[68:69]
	s_add_u32 s68, s68, 0x6000
	s_addc_u32 s69, s69, 0
	global_load_dword v99, v14, s[68:69]
	s_add_u32 s68, s68, 0x6000
	s_addc_u32 s69, s69, 0
	global_load_dword v100, v14, s[68:69]
	s_add_u32 s68, s68, 0x6000
	s_addc_u32 s69, s69, 0
	global_load_dword v101, v14, s[68:69]
	s_add_u32 s68, s68, 0x6000
	s_addc_u32 s69, s69, 0
	global_load_dword v102, v14, s[68:69]
	s_add_u32 s68, s68, 0x6000
	s_addc_u32 s69, s69, 0
	global_load_dword v103, v14, s[68:69]
	s_add_u32 s68, s68, 0x6000
	s_addc_u32 s69, s69, 0
	global_load_dword v104, v14, s[68:69]
	s_add_u32 s68, s68, 0x6000
	s_addc_u32 s69, s69, 0
	global_load_dword v105, v14, s[68:69]
	s_add_u32 s68, s68, 0x6000
	s_addc_u32 s69, s69, 0
	global_load_dword v106, v14, s[68:69]
	s_add_u32 s68, s68, 0x6000
	s_addc_u32 s69, s69, 0
	global_load_dword v107, v14, s[68:69]
	s_add_u32 s68, s68, 0x6000
	s_addc_u32 s69, s69, 0
	global_load_dword v108, v14, s[68:69]
	s_add_u32 s68, s68, 0x6000
	s_addc_u32 s69, s69, 0
	global_load_dword v109, v14, s[68:69]
	s_add_u32 s68, s68, 0x6000
	s_addc_u32 s69, s69, 0
	global_load_dword v110, v14, s[68:69]
	s_add_u32 s68, s68, 0x6000
	s_addc_u32 s69, s69, 0
	global_load_dword v111, v14, s[68:69]
	s_add_u32 s68, s68, 0x6000
	s_addc_u32 s69, s69, 0
	global_load_dword v112, v14, s[68:69]
	s_add_u32 s68, s68, 0x6000
	s_addc_u32 s69, s69, 0
	global_load_dword v113, v14, s[68:69]
	s_add_u32 s68, s68, 0x6000
	s_addc_u32 s69, s69, 0
	global_load_dword v114, v14, s[68:69]
	s_add_u32 s68, s68, 0x6000
	s_addc_u32 s69, s69, 0
	global_load_dword v115, v14, s[68:69]
	s_add_u32 s68, s68, 0x546000
	s_addc_u32 s69, s69, 0
	global_load_dword v116, v14, s[68:69]
	s_add_u32 s68, s68, 0x6000
	s_addc_u32 s69, s69, 0
	global_load_dword v117, v14, s[68:69]
	s_add_u32 s68, s68, 0x6000
	s_addc_u32 s69, s69, 0
	global_load_dword v118, v14, s[68:69]
	s_add_u32 s68, s68, 0x6000
	s_addc_u32 s69, s69, 0
	global_load_dword v119, v14, s[68:69]
	s_add_u32 s68, s68, 0x6000
	s_addc_u32 s69, s69, 0
	global_load_dword v120, v14, s[68:69]
	s_add_u32 s68, s68, 0x6000
	s_addc_u32 s69, s69, 0
	global_load_dword v121, v14, s[68:69]
	s_add_u32 s68, s68, 0x6000
	s_addc_u32 s69, s69, 0
	global_load_dword v122, v14, s[68:69]
	s_add_u32 s68, s68, 0x6000
	s_addc_u32 s69, s69, 0
	global_load_dword v123, v14, s[68:69]
	s_add_u32 s68, s68, 0x6000
	s_addc_u32 s69, s69, 0
	global_load_dword v124, v14, s[68:69]
	s_add_u32 s68, s68, 0x6000
	s_addc_u32 s69, s69, 0
	global_load_dword v125, v14, s[68:69]
	s_add_u32 s68, s68, 0x6000
	s_addc_u32 s69, s69, 0
	global_load_dword v126, v14, s[68:69]
	s_add_u32 s68, s68, 0x6000
	s_addc_u32 s69, s69, 0
	global_load_dword v127, v14, s[68:69]
	s_add_u32 s68, s68, 0x6000
	s_addc_u32 s69, s69, 0
	global_load_dword v128, v14, s[68:69]
	s_add_u32 s68, s68, 0x6000
	s_addc_u32 s69, s69, 0
	global_load_dword v129, v14, s[68:69]
	s_add_u32 s68, s68, 0x6000
	s_addc_u32 s69, s69, 0
	global_load_dword v130, v14, s[68:69]
	s_add_u32 s68, s68, 0x6000
	s_addc_u32 s69, s69, 0
	global_load_dword v131, v14, s[68:69]
	s_add_u32 s68, s68, 0x6000
	s_addc_u32 s69, s69, 0
	global_load_dword v132, v14, s[68:69]
	s_add_u32 s68, s68, 0x6000
	s_addc_u32 s69, s69, 0
	global_load_dword v133, v14, s[68:69]
	s_add_u32 s68, s68, 0x6000
	s_addc_u32 s69, s69, 0
	global_load_dword v134, v14, s[68:69]
	s_add_u32 s68, s68, 0x6000
	s_addc_u32 s69, s69, 0
	global_load_dword v135, v14, s[68:69]
	s_add_u32 s68, s68, 0x6000
	s_addc_u32 s69, s69, 0
	global_load_dword v136, v14, s[68:69]
	s_add_u32 s68, s68, 0x6000
	s_addc_u32 s69, s69, 0
	global_load_dword v137, v14, s[68:69]
	s_add_u32 s68, s68, 0x6000
	s_addc_u32 s69, s69, 0
	global_load_dword v138, v14, s[68:69]
	s_add_u32 s68, s68, 0x6000
	s_addc_u32 s69, s69, 0
	global_load_dword v139, v14, s[68:69]
	s_add_u32 s68, s68, 0x6000
	s_addc_u32 s69, s69, 0
	global_load_dword v140, v14, s[68:69]
	s_add_u32 s68, s68, 0x6000
	s_addc_u32 s69, s69, 0
	global_load_dword v141, v14, s[68:69]
	s_add_u32 s68, s68, 0x6000
	s_addc_u32 s69, s69, 0
	global_load_dword v142, v14, s[68:69]
	s_add_u32 s68, s68, 0x6000
	s_addc_u32 s69, s69, 0
	global_load_dword v143, v14, s[68:69]
	s_add_u32 s68, s68, 0x6000
	s_addc_u32 s69, s69, 0
	global_load_dword v144, v14, s[68:69]
	s_add_u32 s68, s68, 0x6000
	s_addc_u32 s69, s69, 0
	global_load_dword v145, v14, s[68:69]
	s_add_u32 s68, s68, 0x6000
	s_addc_u32 s69, s69, 0
	global_load_dword v146, v14, s[68:69]
	s_add_u32 s68, s68, 0x6000
	s_addc_u32 s69, s69, 0
	global_load_dword v147, v14, s[68:69]
	s_add_u32 s68, s68, 0x546000
	s_addc_u32 s69, s69, 0
	v_mov_b32_e32 v20, 0
	v_mov_b32_e32 v21, 0
	v_mov_b32_e32 v22, 0
	v_mov_b32_e32 v23, 0
	v_mov_b32_e32 v24, 0
	v_mov_b32_e32 v25, 0
	v_mov_b32_e32 v26, 0
	v_mov_b32_e32 v27, 0
	v_mov_b32_e32 v28, 0
	v_mov_b32_e32 v29, 0
	v_mov_b32_e32 v30, 0
	v_mov_b32_e32 v31, 0
	v_mov_b32_e32 v32, 0
	v_mov_b32_e32 v33, 0
	v_mov_b32_e32 v34, 0
	v_mov_b32_e32 v35, 0
	v_mov_b32_e32 v36, 0
	s_waitcnt vmcnt(63)
	v_mul_f32_e32 v2, 0xbfb8aa3b, v212
	v_exp_f32_e32 v2, v2
	s_nop 0
	v_add_f32_e32 v2, 1.0, v2
	v_rcp_f32_e32 v2, v2
	s_nop 0
	v_mul_f32_e32 v212, v212, v2
	v_mul_f32_e32 v3, 0xbfb8aa3b, v213
	v_exp_f32_e32 v3, v3
	s_nop 0
	v_add_f32_e32 v3, 1.0, v3
	v_rcp_f32_e32 v3, v3
	s_nop 0
	v_mul_f32_e32 v213, v213, v3
	v_mul_f32_e32 v4, 0xbfb8aa3b, v214
	v_exp_f32_e32 v4, v4
	s_nop 0
	v_add_f32_e32 v4, 1.0, v4
	v_rcp_f32_e32 v4, v4
	s_nop 0
	v_mul_f32_e32 v214, v214, v4
	v_mul_f32_e32 v5, 0xbfb8aa3b, v215
	v_exp_f32_e32 v5, v5
	s_nop 0
	v_add_f32_e32 v5, 1.0, v5
	v_rcp_f32_e32 v5, v5
	s_nop 0
	v_mul_f32_e32 v215, v215, v5
	v_mul_f32_e32 v2, 0xbfb8aa3b, v216
	v_exp_f32_e32 v2, v2
	s_nop 0
	v_add_f32_e32 v2, 1.0, v2
	v_rcp_f32_e32 v2, v2
	s_nop 0
	v_mul_f32_e32 v216, v216, v2
	v_mul_f32_e32 v3, 0xbfb8aa3b, v217
	v_exp_f32_e32 v3, v3
	s_nop 0
	v_add_f32_e32 v3, 1.0, v3
	v_rcp_f32_e32 v3, v3
	s_nop 0
	v_mul_f32_e32 v217, v217, v3
	v_mul_f32_e32 v4, 0xbfb8aa3b, v218
	v_exp_f32_e32 v4, v4
	s_nop 0
	v_add_f32_e32 v4, 1.0, v4
	v_rcp_f32_e32 v4, v4
	s_nop 0
	v_mul_f32_e32 v218, v218, v4
	v_mul_f32_e32 v5, 0xbfb8aa3b, v219
	v_exp_f32_e32 v5, v5
	s_nop 0
	v_add_f32_e32 v5, 1.0, v5
	v_rcp_f32_e32 v5, v5
	s_nop 0
	v_mul_f32_e32 v219, v219, v5
	v_mul_f32_e32 v2, 0xbfb8aa3b, v220
	v_exp_f32_e32 v2, v2
	s_nop 0
	v_add_f32_e32 v2, 1.0, v2
	v_rcp_f32_e32 v2, v2
	s_nop 0
	v_mul_f32_e32 v220, v220, v2
	v_mul_f32_e32 v3, 0xbfb8aa3b, v221
	v_exp_f32_e32 v3, v3
	s_nop 0
	v_add_f32_e32 v3, 1.0, v3
	v_rcp_f32_e32 v3, v3
	s_nop 0
	v_mul_f32_e32 v221, v221, v3
	v_mul_f32_e32 v4, 0xbfb8aa3b, v229
	v_exp_f32_e32 v4, v4
	s_nop 0
	v_add_f32_e32 v4, 1.0, v4
	v_rcp_f32_e32 v4, v4
	s_nop 0
	v_mul_f32_e32 v229, v229, v4
	v_mul_f32_e32 v5, 0xbfb8aa3b, v230
	v_exp_f32_e32 v5, v5
	s_nop 0
	v_add_f32_e32 v5, 1.0, v5
	v_rcp_f32_e32 v5, v5
	s_nop 0
	v_mul_f32_e32 v230, v230, v5
	v_mul_f32_e32 v2, 0xbfb8aa3b, v231
	v_exp_f32_e32 v2, v2
	s_nop 0
	v_add_f32_e32 v2, 1.0, v2
	v_rcp_f32_e32 v2, v2
	s_nop 0
	v_mul_f32_e32 v231, v231, v2
	v_mul_f32_e32 v3, 0xbfb8aa3b, v232
	v_exp_f32_e32 v3, v3
	s_nop 0
	v_add_f32_e32 v3, 1.0, v3
	v_rcp_f32_e32 v3, v3
	s_nop 0
	v_mul_f32_e32 v232, v232, v3
	v_mul_f32_e32 v4, 0xbfb8aa3b, v233
	v_exp_f32_e32 v4, v4
	s_nop 0
	v_add_f32_e32 v4, 1.0, v4
	v_rcp_f32_e32 v4, v4
	s_nop 0
	v_mul_f32_e32 v233, v233, v4
	v_mul_f32_e32 v5, 0xbfb8aa3b, v234
	v_exp_f32_e32 v5, v5
	s_nop 0
	v_add_f32_e32 v5, 1.0, v5
	v_rcp_f32_e32 v5, v5
	s_nop 0
	v_mul_f32_e32 v234, v234, v5
	v_mul_f32_e32 v2, 0xbfb8aa3b, v235
	v_exp_f32_e32 v2, v2
	s_nop 0
	v_add_f32_e32 v2, 1.0, v2
	v_rcp_f32_e32 v2, v2
	s_nop 0
	v_mul_f32_e32 v235, v235, v2
	v_mul_f32_e32 v3, 0xbfb8aa3b, v236
	v_exp_f32_e32 v3, v3
	s_nop 0
	v_add_f32_e32 v3, 1.0, v3
	v_rcp_f32_e32 v3, v3
	s_nop 0
	v_mul_f32_e32 v236, v236, v3
	v_mul_f32_e32 v4, 0xbfb8aa3b, v237
	v_exp_f32_e32 v4, v4
	s_nop 0
	v_add_f32_e32 v4, 1.0, v4
	v_rcp_f32_e32 v4, v4
	s_nop 0
	v_mul_f32_e32 v237, v237, v4
	v_mul_f32_e32 v5, 0xbfb8aa3b, v238
	v_exp_f32_e32 v5, v5
	s_nop 0
	v_add_f32_e32 v5, 1.0, v5
	v_rcp_f32_e32 v5, v5
	s_nop 0
	v_mul_f32_e32 v238, v238, v5
	v_mul_f32_e32 v2, 0xbfb8aa3b, v239
	v_exp_f32_e32 v2, v2
	s_nop 0
	v_add_f32_e32 v2, 1.0, v2
	v_rcp_f32_e32 v2, v2
	s_nop 0
	v_mul_f32_e32 v239, v239, v2
	v_mul_f32_e32 v3, 0xbfb8aa3b, v240
	v_exp_f32_e32 v3, v3
	s_nop 0
	v_add_f32_e32 v3, 1.0, v3
	v_rcp_f32_e32 v3, v3
	s_nop 0
	v_mul_f32_e32 v240, v240, v3
	v_mul_f32_e32 v4, 0xbfb8aa3b, v241
	v_exp_f32_e32 v4, v4
	s_nop 0
	v_add_f32_e32 v4, 1.0, v4
	v_rcp_f32_e32 v4, v4
	s_nop 0
	v_mul_f32_e32 v241, v241, v4
	v_mul_f32_e32 v5, 0xbfb8aa3b, v242
	v_exp_f32_e32 v5, v5
	s_nop 0
	v_add_f32_e32 v5, 1.0, v5
	v_rcp_f32_e32 v5, v5
	s_nop 0
	v_mul_f32_e32 v242, v242, v5
	v_mul_f32_e32 v2, 0xbfb8aa3b, v243
	v_exp_f32_e32 v2, v2
	s_nop 0
	v_add_f32_e32 v2, 1.0, v2
	v_rcp_f32_e32 v2, v2
	s_nop 0
	v_mul_f32_e32 v243, v243, v2
	v_mul_f32_e32 v3, 0xbfb8aa3b, v244
	v_exp_f32_e32 v3, v3
	s_nop 0
	v_add_f32_e32 v3, 1.0, v3
	v_rcp_f32_e32 v3, v3
	s_nop 0
	v_mul_f32_e32 v244, v244, v3
	v_mul_f32_e32 v4, 0xbfb8aa3b, v245
	v_exp_f32_e32 v4, v4
	s_nop 0
	v_add_f32_e32 v4, 1.0, v4
	v_rcp_f32_e32 v4, v4
	s_nop 0
	v_mul_f32_e32 v245, v245, v4
	v_mul_f32_e32 v5, 0xbfb8aa3b, v246
	v_exp_f32_e32 v5, v5
	s_nop 0
	v_add_f32_e32 v5, 1.0, v5
	v_rcp_f32_e32 v5, v5
	s_nop 0
	v_mul_f32_e32 v246, v246, v5
	v_mul_f32_e32 v2, 0xbfb8aa3b, v247
	v_exp_f32_e32 v2, v2
	s_nop 0
	v_add_f32_e32 v2, 1.0, v2
	v_rcp_f32_e32 v2, v2
	s_nop 0
	v_mul_f32_e32 v247, v247, v2
	v_mul_f32_e32 v3, 0xbfb8aa3b, v248
	v_exp_f32_e32 v3, v3
	s_nop 0
	v_add_f32_e32 v3, 1.0, v3
	v_rcp_f32_e32 v3, v3
	s_nop 0
	v_mul_f32_e32 v248, v248, v3
	v_mul_f32_e32 v4, 0xbfb8aa3b, v249
	v_exp_f32_e32 v4, v4
	s_nop 0
	v_add_f32_e32 v4, 1.0, v4
	v_rcp_f32_e32 v4, v4
	s_nop 0
	v_mul_f32_e32 v249, v249, v4
	v_mul_f32_e32 v5, 0xbfb8aa3b, v250
	v_exp_f32_e32 v5, v5
	s_nop 0
	v_add_f32_e32 v5, 1.0, v5
	v_rcp_f32_e32 v5, v5
	s_nop 0
	v_mul_f32_e32 v250, v250, v5
	v_mul_f32_e32 v2, 0xbfb8aa3b, v251
	v_exp_f32_e32 v2, v2
	s_nop 0
	v_add_f32_e32 v2, 1.0, v2
	v_rcp_f32_e32 v2, v2
	s_nop 0
	v_mul_f32_e32 v251, v251, v2
	v_mul_f32_e32 v3, 0xbfb8aa3b, v252
	v_exp_f32_e32 v3, v3
	s_nop 0
	v_add_f32_e32 v3, 1.0, v3
	v_rcp_f32_e32 v3, v3
	s_nop 0
	v_mul_f32_e32 v252, v252, v3
	v_add_u32_e32 v42, 0x10000, v16
	ds_write_b32 v16, v212 offset:0
	ds_write_b32 v16, v213 offset:2048
	ds_write_b32 v16, v214 offset:4096
	ds_write_b32 v16, v215 offset:6144
	ds_write_b32 v16, v216 offset:8192
	ds_write_b32 v16, v217 offset:10240
	ds_write_b32 v16, v218 offset:12288
	ds_write_b32 v16, v219 offset:14336
	ds_write_b32 v16, v220 offset:16384
	ds_write_b32 v16, v221 offset:18432
	ds_write_b32 v16, v229 offset:20480
	ds_write_b32 v16, v230 offset:22528
	ds_write_b32 v16, v231 offset:24576
	ds_write_b32 v16, v232 offset:26624
	ds_write_b32 v16, v233 offset:28672
	ds_write_b32 v16, v234 offset:30720
	ds_write_b32 v16, v235 offset:32768
	ds_write_b32 v16, v236 offset:34816
	ds_write_b32 v16, v237 offset:36864
	ds_write_b32 v16, v238 offset:38912
	ds_write_b32 v16, v239 offset:40960
	ds_write_b32 v16, v240 offset:43008
	ds_write_b32 v16, v241 offset:45056
	ds_write_b32 v16, v242 offset:47104
	ds_write_b32 v16, v243 offset:49152
	ds_write_b32 v16, v244 offset:51200
	ds_write_b32 v16, v245 offset:53248
	ds_write_b32 v16, v246 offset:55296
	ds_write_b32 v16, v247 offset:57344
	ds_write_b32 v16, v248 offset:59392
	ds_write_b32 v16, v249 offset:61440
	ds_write_b32 v16, v250 offset:63488
	ds_write_b32 v42, v251 offset:0
	ds_write_b32 v42, v252 offset:2048
	s_waitcnt lgkmcnt(0)
	s_barrier
	v_lshlrev_b32_e32 v43, 7, v18
	v_add_u32_e32 v37, 0x10000, v43
	ds_read_b128 v[2:5], v43 offset:0
	ds_read_b128 v[6:9], v43 offset:4096
	ds_read_b128 v[10:13], v43 offset:8192
	ds_read_b128 v[38:41], v43 offset:12288
	s_waitcnt vmcnt(60)
	s_waitcnt lgkmcnt(3)
	v_fmac_f32_e32 v20, v2, v84
	v_fmac_f32_e32 v20, v3, v85
	v_fmac_f32_e32 v20, v4, v86
	v_fmac_f32_e32 v20, v5, v87
	ds_read_b128 v[2:5], v43 offset:16384
	s_waitcnt lgkmcnt(3)
	v_fmac_f32_e32 v21, v6, v84
	v_fmac_f32_e32 v21, v7, v85
	v_fmac_f32_e32 v21, v8, v86
	v_fmac_f32_e32 v21, v9, v87
	ds_read_b128 v[6:9], v43 offset:20480
	s_waitcnt lgkmcnt(3)
	v_fmac_f32_e32 v22, v10, v84
	v_fmac_f32_e32 v22, v11, v85
	v_fmac_f32_e32 v22, v12, v86
	v_fmac_f32_e32 v22, v13, v87
	ds_read_b128 v[10:13], v43 offset:24576
	s_waitcnt lgkmcnt(3)
	v_fmac_f32_e32 v23, v38, v84
	v_fmac_f32_e32 v23, v39, v85
	v_fmac_f32_e32 v23, v40, v86
	v_fmac_f32_e32 v23, v41, v87
	ds_read_b128 v[38:41], v43 offset:28672
	s_waitcnt lgkmcnt(3)
	v_fmac_f32_e32 v24, v2, v84
	v_fmac_f32_e32 v24, v3, v85
	v_fmac_f32_e32 v24, v4, v86
	v_fmac_f32_e32 v24, v5, v87
	ds_read_b128 v[2:5], v43 offset:32768
	s_waitcnt lgkmcnt(3)
	v_fmac_f32_e32 v25, v6, v84
	v_fmac_f32_e32 v25, v7, v85
	v_fmac_f32_e32 v25, v8, v86
	v_fmac_f32_e32 v25, v9, v87
	ds_read_b128 v[6:9], v43 offset:36864
	s_waitcnt lgkmcnt(3)
	v_fmac_f32_e32 v26, v10, v84
	v_fmac_f32_e32 v26, v11, v85
	v_fmac_f32_e32 v26, v12, v86
	v_fmac_f32_e32 v26, v13, v87
	ds_read_b128 v[10:13], v43 offset:40960
	s_waitcnt lgkmcnt(3)
	v_fmac_f32_e32 v27, v38, v84
	v_fmac_f32_e32 v27, v39, v85
	v_fmac_f32_e32 v27, v40, v86
	v_fmac_f32_e32 v27, v41, v87
	ds_read_b128 v[38:41], v43 offset:45056
	s_waitcnt lgkmcnt(3)
	v_fmac_f32_e32 v28, v2, v84
	v_fmac_f32_e32 v28, v3, v85
	v_fmac_f32_e32 v28, v4, v86
	v_fmac_f32_e32 v28, v5, v87
	ds_read_b128 v[2:5], v43 offset:49152
	s_waitcnt lgkmcnt(3)
	v_fmac_f32_e32 v29, v6, v84
	v_fmac_f32_e32 v29, v7, v85
	v_fmac_f32_e32 v29, v8, v86
	v_fmac_f32_e32 v29, v9, v87
	ds_read_b128 v[6:9], v43 offset:53248
	s_waitcnt lgkmcnt(3)
	v_fmac_f32_e32 v30, v10, v84
	v_fmac_f32_e32 v30, v11, v85
	v_fmac_f32_e32 v30, v12, v86
	v_fmac_f32_e32 v30, v13, v87
	ds_read_b128 v[10:13], v43 offset:57344
	s_waitcnt lgkmcnt(3)
	v_fmac_f32_e32 v31, v38, v84
	v_fmac_f32_e32 v31, v39, v85
	v_fmac_f32_e32 v31, v40, v86
	v_fmac_f32_e32 v31, v41, v87
	ds_read_b128 v[38:41], v43 offset:61440
	s_waitcnt lgkmcnt(3)
	v_fmac_f32_e32 v32, v2, v84
	v_fmac_f32_e32 v32, v3, v85
	v_fmac_f32_e32 v32, v4, v86
	v_fmac_f32_e32 v32, v5, v87
	ds_read_b128 v[2:5], v37 offset:0
	s_waitcnt lgkmcnt(3)
	v_fmac_f32_e32 v33, v6, v84
	v_fmac_f32_e32 v33, v7, v85
	v_fmac_f32_e32 v33, v8, v86
	v_fmac_f32_e32 v33, v9, v87
	ds_read_b128 v[6:9], v43 offset:16
	s_waitcnt lgkmcnt(3)
	v_fmac_f32_e32 v34, v10, v84
	v_fmac_f32_e32 v34, v11, v85
	v_fmac_f32_e32 v34, v12, v86
	v_fmac_f32_e32 v34, v13, v87
	ds_read_b128 v[10:13], v43 offset:4112
	s_waitcnt lgkmcnt(3)
	v_fmac_f32_e32 v35, v38, v84
	v_fmac_f32_e32 v35, v39, v85
	v_fmac_f32_e32 v35, v40, v86
	v_fmac_f32_e32 v35, v41, v87
	ds_read_b128 v[38:41], v43 offset:8208
	s_waitcnt lgkmcnt(3)
	v_fmac_f32_e32 v36, v2, v84
	v_fmac_f32_e32 v36, v3, v85
	v_fmac_f32_e32 v36, v4, v86
	v_fmac_f32_e32 v36, v5, v87
	ds_read_b128 v[2:5], v43 offset:12304
	s_waitcnt vmcnt(56)
	s_waitcnt lgkmcnt(3)
	v_fmac_f32_e32 v20, v6, v88
	v_fmac_f32_e32 v20, v7, v89
	v_fmac_f32_e32 v20, v8, v90
	v_fmac_f32_e32 v20, v9, v91
	ds_read_b128 v[6:9], v43 offset:16400
	s_waitcnt lgkmcnt(3)
	v_fmac_f32_e32 v21, v10, v88
	v_fmac_f32_e32 v21, v11, v89
	v_fmac_f32_e32 v21, v12, v90
	v_fmac_f32_e32 v21, v13, v91
	ds_read_b128 v[10:13], v43 offset:20496
	s_waitcnt lgkmcnt(3)
	v_fmac_f32_e32 v22, v38, v88
	v_fmac_f32_e32 v22, v39, v89
	v_fmac_f32_e32 v22, v40, v90
	v_fmac_f32_e32 v22, v41, v91
	ds_read_b128 v[38:41], v43 offset:24592
	s_waitcnt lgkmcnt(3)
	v_fmac_f32_e32 v23, v2, v88
	v_fmac_f32_e32 v23, v3, v89
	v_fmac_f32_e32 v23, v4, v90
	v_fmac_f32_e32 v23, v5, v91
	ds_read_b128 v[2:5], v43 offset:28688
	s_waitcnt lgkmcnt(3)
	v_fmac_f32_e32 v24, v6, v88
	v_fmac_f32_e32 v24, v7, v89
	v_fmac_f32_e32 v24, v8, v90
	v_fmac_f32_e32 v24, v9, v91
	ds_read_b128 v[6:9], v43 offset:32784
	s_waitcnt lgkmcnt(3)
	v_fmac_f32_e32 v25, v10, v88
	v_fmac_f32_e32 v25, v11, v89
	v_fmac_f32_e32 v25, v12, v90
	v_fmac_f32_e32 v25, v13, v91
	ds_read_b128 v[10:13], v43 offset:36880
	s_waitcnt lgkmcnt(3)
	v_fmac_f32_e32 v26, v38, v88
	v_fmac_f32_e32 v26, v39, v89
	v_fmac_f32_e32 v26, v40, v90
	v_fmac_f32_e32 v26, v41, v91
	ds_read_b128 v[38:41], v43 offset:40976
	s_waitcnt lgkmcnt(3)
	v_fmac_f32_e32 v27, v2, v88
	v_fmac_f32_e32 v27, v3, v89
	v_fmac_f32_e32 v27, v4, v90
	v_fmac_f32_e32 v27, v5, v91
	ds_read_b128 v[2:5], v43 offset:45072
	s_waitcnt lgkmcnt(3)
	v_fmac_f32_e32 v28, v6, v88
	v_fmac_f32_e32 v28, v7, v89
	v_fmac_f32_e32 v28, v8, v90
	v_fmac_f32_e32 v28, v9, v91
	ds_read_b128 v[6:9], v43 offset:49168
	s_waitcnt lgkmcnt(3)
	v_fmac_f32_e32 v29, v10, v88
	v_fmac_f32_e32 v29, v11, v89
	v_fmac_f32_e32 v29, v12, v90
	v_fmac_f32_e32 v29, v13, v91
	ds_read_b128 v[10:13], v43 offset:53264
	s_waitcnt lgkmcnt(3)
	v_fmac_f32_e32 v30, v38, v88
	v_fmac_f32_e32 v30, v39, v89
	v_fmac_f32_e32 v30, v40, v90
	v_fmac_f32_e32 v30, v41, v91
	ds_read_b128 v[38:41], v43 offset:57360
	s_waitcnt lgkmcnt(3)
	v_fmac_f32_e32 v31, v2, v88
	v_fmac_f32_e32 v31, v3, v89
	v_fmac_f32_e32 v31, v4, v90
	v_fmac_f32_e32 v31, v5, v91
	ds_read_b128 v[2:5], v43 offset:61456
	s_waitcnt lgkmcnt(3)
	v_fmac_f32_e32 v32, v6, v88
	v_fmac_f32_e32 v32, v7, v89
	v_fmac_f32_e32 v32, v8, v90
	v_fmac_f32_e32 v32, v9, v91
	ds_read_b128 v[6:9], v37 offset:16
	s_waitcnt lgkmcnt(3)
	v_fmac_f32_e32 v33, v10, v88
	v_fmac_f32_e32 v33, v11, v89
	v_fmac_f32_e32 v33, v12, v90
	v_fmac_f32_e32 v33, v13, v91
	ds_read_b128 v[10:13], v43 offset:32
	s_waitcnt lgkmcnt(3)
	v_fmac_f32_e32 v34, v38, v88
	v_fmac_f32_e32 v34, v39, v89
	v_fmac_f32_e32 v34, v40, v90
	v_fmac_f32_e32 v34, v41, v91
	ds_read_b128 v[38:41], v43 offset:4128
	s_waitcnt lgkmcnt(3)
	v_fmac_f32_e32 v35, v2, v88
	v_fmac_f32_e32 v35, v3, v89
	v_fmac_f32_e32 v35, v4, v90
	v_fmac_f32_e32 v35, v5, v91
	ds_read_b128 v[2:5], v43 offset:8224
	s_waitcnt lgkmcnt(3)
	v_fmac_f32_e32 v36, v6, v88
	v_fmac_f32_e32 v36, v7, v89
	v_fmac_f32_e32 v36, v8, v90
	v_fmac_f32_e32 v36, v9, v91
	ds_read_b128 v[6:9], v43 offset:12320
	s_waitcnt vmcnt(52)
	s_waitcnt lgkmcnt(3)
	v_fmac_f32_e32 v20, v10, v92
	v_fmac_f32_e32 v20, v11, v93
	v_fmac_f32_e32 v20, v12, v94
	v_fmac_f32_e32 v20, v13, v95
	ds_read_b128 v[10:13], v43 offset:16416
	s_waitcnt lgkmcnt(3)
	v_fmac_f32_e32 v21, v38, v92
	v_fmac_f32_e32 v21, v39, v93
	v_fmac_f32_e32 v21, v40, v94
	v_fmac_f32_e32 v21, v41, v95
	ds_read_b128 v[38:41], v43 offset:20512
	s_waitcnt lgkmcnt(3)
	v_fmac_f32_e32 v22, v2, v92
	v_fmac_f32_e32 v22, v3, v93
	v_fmac_f32_e32 v22, v4, v94
	v_fmac_f32_e32 v22, v5, v95
	ds_read_b128 v[2:5], v43 offset:24608
	s_waitcnt lgkmcnt(3)
	v_fmac_f32_e32 v23, v6, v92
	v_fmac_f32_e32 v23, v7, v93
	v_fmac_f32_e32 v23, v8, v94
	v_fmac_f32_e32 v23, v9, v95
	ds_read_b128 v[6:9], v43 offset:28704
	s_waitcnt lgkmcnt(3)
	v_fmac_f32_e32 v24, v10, v92
	v_fmac_f32_e32 v24, v11, v93
	v_fmac_f32_e32 v24, v12, v94
	v_fmac_f32_e32 v24, v13, v95
	ds_read_b128 v[10:13], v43 offset:32800
	s_waitcnt lgkmcnt(3)
	v_fmac_f32_e32 v25, v38, v92
	v_fmac_f32_e32 v25, v39, v93
	v_fmac_f32_e32 v25, v40, v94
	v_fmac_f32_e32 v25, v41, v95
	ds_read_b128 v[38:41], v43 offset:36896
	s_waitcnt lgkmcnt(3)
	v_fmac_f32_e32 v26, v2, v92
	v_fmac_f32_e32 v26, v3, v93
	v_fmac_f32_e32 v26, v4, v94
	v_fmac_f32_e32 v26, v5, v95
	ds_read_b128 v[2:5], v43 offset:40992
	s_waitcnt lgkmcnt(3)
	v_fmac_f32_e32 v27, v6, v92
	v_fmac_f32_e32 v27, v7, v93
	v_fmac_f32_e32 v27, v8, v94
	v_fmac_f32_e32 v27, v9, v95
	ds_read_b128 v[6:9], v43 offset:45088
	s_waitcnt lgkmcnt(3)
	v_fmac_f32_e32 v28, v10, v92
	v_fmac_f32_e32 v28, v11, v93
	v_fmac_f32_e32 v28, v12, v94
	v_fmac_f32_e32 v28, v13, v95
	ds_read_b128 v[10:13], v43 offset:49184
	s_waitcnt lgkmcnt(3)
	v_fmac_f32_e32 v29, v38, v92
	v_fmac_f32_e32 v29, v39, v93
	v_fmac_f32_e32 v29, v40, v94
	v_fmac_f32_e32 v29, v41, v95
	ds_read_b128 v[38:41], v43 offset:53280
	s_waitcnt lgkmcnt(3)
	v_fmac_f32_e32 v30, v2, v92
	v_fmac_f32_e32 v30, v3, v93
	v_fmac_f32_e32 v30, v4, v94
	v_fmac_f32_e32 v30, v5, v95
	ds_read_b128 v[2:5], v43 offset:57376
	s_waitcnt lgkmcnt(3)
	v_fmac_f32_e32 v31, v6, v92
	v_fmac_f32_e32 v31, v7, v93
	v_fmac_f32_e32 v31, v8, v94
	v_fmac_f32_e32 v31, v9, v95
	ds_read_b128 v[6:9], v43 offset:61472
	s_waitcnt lgkmcnt(3)
	v_fmac_f32_e32 v32, v10, v92
	v_fmac_f32_e32 v32, v11, v93
	v_fmac_f32_e32 v32, v12, v94
	v_fmac_f32_e32 v32, v13, v95
	ds_read_b128 v[10:13], v37 offset:32
	s_waitcnt lgkmcnt(3)
	v_fmac_f32_e32 v33, v38, v92
	v_fmac_f32_e32 v33, v39, v93
	v_fmac_f32_e32 v33, v40, v94
	v_fmac_f32_e32 v33, v41, v95
	ds_read_b128 v[38:41], v43 offset:48
	s_waitcnt lgkmcnt(3)
	v_fmac_f32_e32 v34, v2, v92
	v_fmac_f32_e32 v34, v3, v93
	v_fmac_f32_e32 v34, v4, v94
	v_fmac_f32_e32 v34, v5, v95
	ds_read_b128 v[2:5], v43 offset:4144
	s_waitcnt lgkmcnt(3)
	v_fmac_f32_e32 v35, v6, v92
	v_fmac_f32_e32 v35, v7, v93
	v_fmac_f32_e32 v35, v8, v94
	v_fmac_f32_e32 v35, v9, v95
	ds_read_b128 v[6:9], v43 offset:8240
	s_waitcnt lgkmcnt(3)
	v_fmac_f32_e32 v36, v10, v92
	v_fmac_f32_e32 v36, v11, v93
	v_fmac_f32_e32 v36, v12, v94
	v_fmac_f32_e32 v36, v13, v95
	ds_read_b128 v[10:13], v43 offset:12336
	s_waitcnt vmcnt(48)
	s_waitcnt lgkmcnt(3)
	v_fmac_f32_e32 v20, v38, v96
	v_fmac_f32_e32 v20, v39, v97
	v_fmac_f32_e32 v20, v40, v98
	v_fmac_f32_e32 v20, v41, v99
	ds_read_b128 v[38:41], v43 offset:16432
	s_waitcnt lgkmcnt(3)
	v_fmac_f32_e32 v21, v2, v96
	v_fmac_f32_e32 v21, v3, v97
	v_fmac_f32_e32 v21, v4, v98
	v_fmac_f32_e32 v21, v5, v99
	ds_read_b128 v[2:5], v43 offset:20528
	s_waitcnt lgkmcnt(3)
	v_fmac_f32_e32 v22, v6, v96
	v_fmac_f32_e32 v22, v7, v97
	v_fmac_f32_e32 v22, v8, v98
	v_fmac_f32_e32 v22, v9, v99
	ds_read_b128 v[6:9], v43 offset:24624
	s_waitcnt lgkmcnt(3)
	v_fmac_f32_e32 v23, v10, v96
	v_fmac_f32_e32 v23, v11, v97
	v_fmac_f32_e32 v23, v12, v98
	v_fmac_f32_e32 v23, v13, v99
	ds_read_b128 v[10:13], v43 offset:28720
	s_waitcnt lgkmcnt(3)
	v_fmac_f32_e32 v24, v38, v96
	v_fmac_f32_e32 v24, v39, v97
	v_fmac_f32_e32 v24, v40, v98
	v_fmac_f32_e32 v24, v41, v99
	ds_read_b128 v[38:41], v43 offset:32816
	s_waitcnt lgkmcnt(3)
	v_fmac_f32_e32 v25, v2, v96
	v_fmac_f32_e32 v25, v3, v97
	v_fmac_f32_e32 v25, v4, v98
	v_fmac_f32_e32 v25, v5, v99
	ds_read_b128 v[2:5], v43 offset:36912
	s_waitcnt lgkmcnt(3)
	v_fmac_f32_e32 v26, v6, v96
	v_fmac_f32_e32 v26, v7, v97
	v_fmac_f32_e32 v26, v8, v98
	v_fmac_f32_e32 v26, v9, v99
	ds_read_b128 v[6:9], v43 offset:41008
	s_waitcnt lgkmcnt(3)
	v_fmac_f32_e32 v27, v10, v96
	v_fmac_f32_e32 v27, v11, v97
	v_fmac_f32_e32 v27, v12, v98
	v_fmac_f32_e32 v27, v13, v99
	ds_read_b128 v[10:13], v43 offset:45104
	s_waitcnt lgkmcnt(3)
	v_fmac_f32_e32 v28, v38, v96
	v_fmac_f32_e32 v28, v39, v97
	v_fmac_f32_e32 v28, v40, v98
	v_fmac_f32_e32 v28, v41, v99
	ds_read_b128 v[38:41], v43 offset:49200
	s_waitcnt lgkmcnt(3)
	v_fmac_f32_e32 v29, v2, v96
	v_fmac_f32_e32 v29, v3, v97
	v_fmac_f32_e32 v29, v4, v98
	v_fmac_f32_e32 v29, v5, v99
	ds_read_b128 v[2:5], v43 offset:53296
	s_waitcnt lgkmcnt(3)
	v_fmac_f32_e32 v30, v6, v96
	v_fmac_f32_e32 v30, v7, v97
	v_fmac_f32_e32 v30, v8, v98
	v_fmac_f32_e32 v30, v9, v99
	ds_read_b128 v[6:9], v43 offset:57392
	s_waitcnt lgkmcnt(3)
	v_fmac_f32_e32 v31, v10, v96
	v_fmac_f32_e32 v31, v11, v97
	v_fmac_f32_e32 v31, v12, v98
	v_fmac_f32_e32 v31, v13, v99
	ds_read_b128 v[10:13], v43 offset:61488
	s_waitcnt lgkmcnt(3)
	v_fmac_f32_e32 v32, v38, v96
	v_fmac_f32_e32 v32, v39, v97
	v_fmac_f32_e32 v32, v40, v98
	v_fmac_f32_e32 v32, v41, v99
	ds_read_b128 v[38:41], v37 offset:48
	s_waitcnt lgkmcnt(3)
	v_fmac_f32_e32 v33, v2, v96
	v_fmac_f32_e32 v33, v3, v97
	v_fmac_f32_e32 v33, v4, v98
	v_fmac_f32_e32 v33, v5, v99
	ds_read_b128 v[2:5], v43 offset:64
	s_waitcnt lgkmcnt(3)
	v_fmac_f32_e32 v34, v6, v96
	v_fmac_f32_e32 v34, v7, v97
	v_fmac_f32_e32 v34, v8, v98
	v_fmac_f32_e32 v34, v9, v99
	ds_read_b128 v[6:9], v43 offset:4160
	s_waitcnt lgkmcnt(3)
	v_fmac_f32_e32 v35, v10, v96
	v_fmac_f32_e32 v35, v11, v97
	v_fmac_f32_e32 v35, v12, v98
	v_fmac_f32_e32 v35, v13, v99
	ds_read_b128 v[10:13], v43 offset:8256
	s_waitcnt lgkmcnt(3)
	v_fmac_f32_e32 v36, v38, v96
	v_fmac_f32_e32 v36, v39, v97
	v_fmac_f32_e32 v36, v40, v98
	v_fmac_f32_e32 v36, v41, v99
	ds_read_b128 v[38:41], v43 offset:12352
	s_waitcnt vmcnt(44)
	s_waitcnt lgkmcnt(3)
	v_fmac_f32_e32 v20, v2, v100
	v_fmac_f32_e32 v20, v3, v101
	v_fmac_f32_e32 v20, v4, v102
	v_fmac_f32_e32 v20, v5, v103
	ds_read_b128 v[2:5], v43 offset:16448
	s_waitcnt lgkmcnt(3)
	v_fmac_f32_e32 v21, v6, v100
	v_fmac_f32_e32 v21, v7, v101
	v_fmac_f32_e32 v21, v8, v102
	v_fmac_f32_e32 v21, v9, v103
	ds_read_b128 v[6:9], v43 offset:20544
	s_waitcnt lgkmcnt(3)
	v_fmac_f32_e32 v22, v10, v100
	v_fmac_f32_e32 v22, v11, v101
	v_fmac_f32_e32 v22, v12, v102
	v_fmac_f32_e32 v22, v13, v103
	ds_read_b128 v[10:13], v43 offset:24640
	s_waitcnt lgkmcnt(3)
	v_fmac_f32_e32 v23, v38, v100
	v_fmac_f32_e32 v23, v39, v101
	v_fmac_f32_e32 v23, v40, v102
	v_fmac_f32_e32 v23, v41, v103
	ds_read_b128 v[38:41], v43 offset:28736
	s_waitcnt lgkmcnt(3)
	v_fmac_f32_e32 v24, v2, v100
	v_fmac_f32_e32 v24, v3, v101
	v_fmac_f32_e32 v24, v4, v102
	v_fmac_f32_e32 v24, v5, v103
	ds_read_b128 v[2:5], v43 offset:32832
	s_waitcnt lgkmcnt(3)
	v_fmac_f32_e32 v25, v6, v100
	v_fmac_f32_e32 v25, v7, v101
	v_fmac_f32_e32 v25, v8, v102
	v_fmac_f32_e32 v25, v9, v103
	ds_read_b128 v[6:9], v43 offset:36928
	s_waitcnt lgkmcnt(3)
	v_fmac_f32_e32 v26, v10, v100
	v_fmac_f32_e32 v26, v11, v101
	v_fmac_f32_e32 v26, v12, v102
	v_fmac_f32_e32 v26, v13, v103
	ds_read_b128 v[10:13], v43 offset:41024
	s_waitcnt lgkmcnt(3)
	v_fmac_f32_e32 v27, v38, v100
	v_fmac_f32_e32 v27, v39, v101
	v_fmac_f32_e32 v27, v40, v102
	v_fmac_f32_e32 v27, v41, v103
	ds_read_b128 v[38:41], v43 offset:45120
	s_waitcnt lgkmcnt(3)
	v_fmac_f32_e32 v28, v2, v100
	v_fmac_f32_e32 v28, v3, v101
	v_fmac_f32_e32 v28, v4, v102
	v_fmac_f32_e32 v28, v5, v103
	ds_read_b128 v[2:5], v43 offset:49216
	s_waitcnt lgkmcnt(3)
	v_fmac_f32_e32 v29, v6, v100
	v_fmac_f32_e32 v29, v7, v101
	v_fmac_f32_e32 v29, v8, v102
	v_fmac_f32_e32 v29, v9, v103
	ds_read_b128 v[6:9], v43 offset:53312
	s_waitcnt lgkmcnt(3)
	v_fmac_f32_e32 v30, v10, v100
	v_fmac_f32_e32 v30, v11, v101
	v_fmac_f32_e32 v30, v12, v102
	v_fmac_f32_e32 v30, v13, v103
	ds_read_b128 v[10:13], v43 offset:57408
	s_waitcnt lgkmcnt(3)
	v_fmac_f32_e32 v31, v38, v100
	v_fmac_f32_e32 v31, v39, v101
	v_fmac_f32_e32 v31, v40, v102
	v_fmac_f32_e32 v31, v41, v103
	ds_read_b128 v[38:41], v43 offset:61504
	s_waitcnt lgkmcnt(3)
	v_fmac_f32_e32 v32, v2, v100
	v_fmac_f32_e32 v32, v3, v101
	v_fmac_f32_e32 v32, v4, v102
	v_fmac_f32_e32 v32, v5, v103
	ds_read_b128 v[2:5], v37 offset:64
	s_waitcnt lgkmcnt(3)
	v_fmac_f32_e32 v33, v6, v100
	v_fmac_f32_e32 v33, v7, v101
	v_fmac_f32_e32 v33, v8, v102
	v_fmac_f32_e32 v33, v9, v103
	ds_read_b128 v[6:9], v43 offset:80
	s_waitcnt lgkmcnt(3)
	v_fmac_f32_e32 v34, v10, v100
	v_fmac_f32_e32 v34, v11, v101
	v_fmac_f32_e32 v34, v12, v102
	v_fmac_f32_e32 v34, v13, v103
	ds_read_b128 v[10:13], v43 offset:4176
	s_waitcnt lgkmcnt(3)
	v_fmac_f32_e32 v35, v38, v100
	v_fmac_f32_e32 v35, v39, v101
	v_fmac_f32_e32 v35, v40, v102
	v_fmac_f32_e32 v35, v41, v103
	ds_read_b128 v[38:41], v43 offset:8272
	s_waitcnt lgkmcnt(3)
	v_fmac_f32_e32 v36, v2, v100
	v_fmac_f32_e32 v36, v3, v101
	v_fmac_f32_e32 v36, v4, v102
	v_fmac_f32_e32 v36, v5, v103
	ds_read_b128 v[2:5], v43 offset:12368
	s_waitcnt vmcnt(40)
	s_waitcnt lgkmcnt(3)
	v_fmac_f32_e32 v20, v6, v104
	v_fmac_f32_e32 v20, v7, v105
	v_fmac_f32_e32 v20, v8, v106
	v_fmac_f32_e32 v20, v9, v107
	ds_read_b128 v[6:9], v43 offset:16464
	s_waitcnt lgkmcnt(3)
	v_fmac_f32_e32 v21, v10, v104
	v_fmac_f32_e32 v21, v11, v105
	v_fmac_f32_e32 v21, v12, v106
	v_fmac_f32_e32 v21, v13, v107
	ds_read_b128 v[10:13], v43 offset:20560
	s_waitcnt lgkmcnt(3)
	v_fmac_f32_e32 v22, v38, v104
	v_fmac_f32_e32 v22, v39, v105
	v_fmac_f32_e32 v22, v40, v106
	v_fmac_f32_e32 v22, v41, v107
	ds_read_b128 v[38:41], v43 offset:24656
	s_waitcnt lgkmcnt(3)
	v_fmac_f32_e32 v23, v2, v104
	v_fmac_f32_e32 v23, v3, v105
	v_fmac_f32_e32 v23, v4, v106
	v_fmac_f32_e32 v23, v5, v107
	ds_read_b128 v[2:5], v43 offset:28752
	s_waitcnt lgkmcnt(3)
	v_fmac_f32_e32 v24, v6, v104
	v_fmac_f32_e32 v24, v7, v105
	v_fmac_f32_e32 v24, v8, v106
	v_fmac_f32_e32 v24, v9, v107
	ds_read_b128 v[6:9], v43 offset:32848
	s_waitcnt lgkmcnt(3)
	v_fmac_f32_e32 v25, v10, v104
	v_fmac_f32_e32 v25, v11, v105
	v_fmac_f32_e32 v25, v12, v106
	v_fmac_f32_e32 v25, v13, v107
	ds_read_b128 v[10:13], v43 offset:36944
	s_waitcnt lgkmcnt(3)
	v_fmac_f32_e32 v26, v38, v104
	v_fmac_f32_e32 v26, v39, v105
	v_fmac_f32_e32 v26, v40, v106
	v_fmac_f32_e32 v26, v41, v107
	ds_read_b128 v[38:41], v43 offset:41040
	s_waitcnt lgkmcnt(3)
	v_fmac_f32_e32 v27, v2, v104
	v_fmac_f32_e32 v27, v3, v105
	v_fmac_f32_e32 v27, v4, v106
	v_fmac_f32_e32 v27, v5, v107
	ds_read_b128 v[2:5], v43 offset:45136
	s_waitcnt lgkmcnt(3)
	v_fmac_f32_e32 v28, v6, v104
	v_fmac_f32_e32 v28, v7, v105
	v_fmac_f32_e32 v28, v8, v106
	v_fmac_f32_e32 v28, v9, v107
	ds_read_b128 v[6:9], v43 offset:49232
	s_waitcnt lgkmcnt(3)
	v_fmac_f32_e32 v29, v10, v104
	v_fmac_f32_e32 v29, v11, v105
	v_fmac_f32_e32 v29, v12, v106
	v_fmac_f32_e32 v29, v13, v107
	ds_read_b128 v[10:13], v43 offset:53328
	s_waitcnt lgkmcnt(3)
	v_fmac_f32_e32 v30, v38, v104
	v_fmac_f32_e32 v30, v39, v105
	v_fmac_f32_e32 v30, v40, v106
	v_fmac_f32_e32 v30, v41, v107
	ds_read_b128 v[38:41], v43 offset:57424
	s_waitcnt lgkmcnt(3)
	v_fmac_f32_e32 v31, v2, v104
	v_fmac_f32_e32 v31, v3, v105
	v_fmac_f32_e32 v31, v4, v106
	v_fmac_f32_e32 v31, v5, v107
	ds_read_b128 v[2:5], v43 offset:61520
	s_waitcnt lgkmcnt(3)
	v_fmac_f32_e32 v32, v6, v104
	v_fmac_f32_e32 v32, v7, v105
	v_fmac_f32_e32 v32, v8, v106
	v_fmac_f32_e32 v32, v9, v107
	ds_read_b128 v[6:9], v37 offset:80
	s_waitcnt lgkmcnt(3)
	v_fmac_f32_e32 v33, v10, v104
	v_fmac_f32_e32 v33, v11, v105
	v_fmac_f32_e32 v33, v12, v106
	v_fmac_f32_e32 v33, v13, v107
	ds_read_b128 v[10:13], v43 offset:96
	s_waitcnt lgkmcnt(3)
	v_fmac_f32_e32 v34, v38, v104
	v_fmac_f32_e32 v34, v39, v105
	v_fmac_f32_e32 v34, v40, v106
	v_fmac_f32_e32 v34, v41, v107
	ds_read_b128 v[38:41], v43 offset:4192
	s_waitcnt lgkmcnt(3)
	v_fmac_f32_e32 v35, v2, v104
	v_fmac_f32_e32 v35, v3, v105
	v_fmac_f32_e32 v35, v4, v106
	v_fmac_f32_e32 v35, v5, v107
	ds_read_b128 v[2:5], v43 offset:8288
	s_waitcnt lgkmcnt(3)
	v_fmac_f32_e32 v36, v6, v104
	v_fmac_f32_e32 v36, v7, v105
	v_fmac_f32_e32 v36, v8, v106
	v_fmac_f32_e32 v36, v9, v107
	ds_read_b128 v[6:9], v43 offset:12384
	s_waitcnt vmcnt(36)
	s_waitcnt lgkmcnt(3)
	v_fmac_f32_e32 v20, v10, v108
	v_fmac_f32_e32 v20, v11, v109
	v_fmac_f32_e32 v20, v12, v110
	v_fmac_f32_e32 v20, v13, v111
	ds_read_b128 v[10:13], v43 offset:16480
	s_waitcnt lgkmcnt(3)
	v_fmac_f32_e32 v21, v38, v108
	v_fmac_f32_e32 v21, v39, v109
	v_fmac_f32_e32 v21, v40, v110
	v_fmac_f32_e32 v21, v41, v111
	ds_read_b128 v[38:41], v43 offset:20576
	s_waitcnt lgkmcnt(3)
	v_fmac_f32_e32 v22, v2, v108
	v_fmac_f32_e32 v22, v3, v109
	v_fmac_f32_e32 v22, v4, v110
	v_fmac_f32_e32 v22, v5, v111
	ds_read_b128 v[2:5], v43 offset:24672
	s_waitcnt lgkmcnt(3)
	v_fmac_f32_e32 v23, v6, v108
	v_fmac_f32_e32 v23, v7, v109
	v_fmac_f32_e32 v23, v8, v110
	v_fmac_f32_e32 v23, v9, v111
	ds_read_b128 v[6:9], v43 offset:28768
	s_waitcnt lgkmcnt(3)
	v_fmac_f32_e32 v24, v10, v108
	v_fmac_f32_e32 v24, v11, v109
	v_fmac_f32_e32 v24, v12, v110
	v_fmac_f32_e32 v24, v13, v111
	ds_read_b128 v[10:13], v43 offset:32864
	s_waitcnt lgkmcnt(3)
	v_fmac_f32_e32 v25, v38, v108
	v_fmac_f32_e32 v25, v39, v109
	v_fmac_f32_e32 v25, v40, v110
	v_fmac_f32_e32 v25, v41, v111
	ds_read_b128 v[38:41], v43 offset:36960
	s_waitcnt lgkmcnt(3)
	v_fmac_f32_e32 v26, v2, v108
	v_fmac_f32_e32 v26, v3, v109
	v_fmac_f32_e32 v26, v4, v110
	v_fmac_f32_e32 v26, v5, v111
	ds_read_b128 v[2:5], v43 offset:41056
	s_waitcnt lgkmcnt(3)
	v_fmac_f32_e32 v27, v6, v108
	v_fmac_f32_e32 v27, v7, v109
	v_fmac_f32_e32 v27, v8, v110
	v_fmac_f32_e32 v27, v9, v111
	ds_read_b128 v[6:9], v43 offset:45152
	s_waitcnt lgkmcnt(3)
	v_fmac_f32_e32 v28, v10, v108
	v_fmac_f32_e32 v28, v11, v109
	v_fmac_f32_e32 v28, v12, v110
	v_fmac_f32_e32 v28, v13, v111
	ds_read_b128 v[10:13], v43 offset:49248
	s_waitcnt lgkmcnt(3)
	v_fmac_f32_e32 v29, v38, v108
	v_fmac_f32_e32 v29, v39, v109
	v_fmac_f32_e32 v29, v40, v110
	v_fmac_f32_e32 v29, v41, v111
	ds_read_b128 v[38:41], v43 offset:53344
	s_waitcnt lgkmcnt(3)
	v_fmac_f32_e32 v30, v2, v108
	v_fmac_f32_e32 v30, v3, v109
	v_fmac_f32_e32 v30, v4, v110
	v_fmac_f32_e32 v30, v5, v111
	ds_read_b128 v[2:5], v43 offset:57440
	s_waitcnt lgkmcnt(3)
	v_fmac_f32_e32 v31, v6, v108
	v_fmac_f32_e32 v31, v7, v109
	v_fmac_f32_e32 v31, v8, v110
	v_fmac_f32_e32 v31, v9, v111
	ds_read_b128 v[6:9], v43 offset:61536
	s_waitcnt lgkmcnt(3)
	v_fmac_f32_e32 v32, v10, v108
	v_fmac_f32_e32 v32, v11, v109
	v_fmac_f32_e32 v32, v12, v110
	v_fmac_f32_e32 v32, v13, v111
	ds_read_b128 v[10:13], v37 offset:96
	s_waitcnt lgkmcnt(3)
	v_fmac_f32_e32 v33, v38, v108
	v_fmac_f32_e32 v33, v39, v109
	v_fmac_f32_e32 v33, v40, v110
	v_fmac_f32_e32 v33, v41, v111
	ds_read_b128 v[38:41], v43 offset:112
	s_waitcnt lgkmcnt(3)
	v_fmac_f32_e32 v34, v2, v108
	v_fmac_f32_e32 v34, v3, v109
	v_fmac_f32_e32 v34, v4, v110
	v_fmac_f32_e32 v34, v5, v111
	ds_read_b128 v[2:5], v43 offset:4208
	s_waitcnt lgkmcnt(3)
	v_fmac_f32_e32 v35, v6, v108
	v_fmac_f32_e32 v35, v7, v109
	v_fmac_f32_e32 v35, v8, v110
	v_fmac_f32_e32 v35, v9, v111
	ds_read_b128 v[6:9], v43 offset:8304
	s_waitcnt lgkmcnt(3)
	v_fmac_f32_e32 v36, v10, v108
	v_fmac_f32_e32 v36, v11, v109
	v_fmac_f32_e32 v36, v12, v110
	v_fmac_f32_e32 v36, v13, v111
	ds_read_b128 v[10:13], v43 offset:12400
	s_waitcnt vmcnt(32)
	s_waitcnt lgkmcnt(3)
	v_fmac_f32_e32 v20, v38, v112
	v_fmac_f32_e32 v20, v39, v113
	v_fmac_f32_e32 v20, v40, v114
	v_fmac_f32_e32 v20, v41, v115
	ds_read_b128 v[38:41], v43 offset:16496
	s_waitcnt lgkmcnt(3)
	v_fmac_f32_e32 v21, v2, v112
	v_fmac_f32_e32 v21, v3, v113
	v_fmac_f32_e32 v21, v4, v114
	v_fmac_f32_e32 v21, v5, v115
	ds_read_b128 v[2:5], v43 offset:20592
	s_waitcnt lgkmcnt(3)
	v_fmac_f32_e32 v22, v6, v112
	v_fmac_f32_e32 v22, v7, v113
	v_fmac_f32_e32 v22, v8, v114
	v_fmac_f32_e32 v22, v9, v115
	ds_read_b128 v[6:9], v43 offset:24688
	s_waitcnt lgkmcnt(3)
	v_fmac_f32_e32 v23, v10, v112
	v_fmac_f32_e32 v23, v11, v113
	v_fmac_f32_e32 v23, v12, v114
	v_fmac_f32_e32 v23, v13, v115
	ds_read_b128 v[10:13], v43 offset:28784
	s_waitcnt lgkmcnt(3)
	v_fmac_f32_e32 v24, v38, v112
	v_fmac_f32_e32 v24, v39, v113
	v_fmac_f32_e32 v24, v40, v114
	v_fmac_f32_e32 v24, v41, v115
	ds_read_b128 v[38:41], v43 offset:32880
	s_waitcnt lgkmcnt(3)
	v_fmac_f32_e32 v25, v2, v112
	v_fmac_f32_e32 v25, v3, v113
	v_fmac_f32_e32 v25, v4, v114
	v_fmac_f32_e32 v25, v5, v115
	ds_read_b128 v[2:5], v43 offset:36976
	s_waitcnt lgkmcnt(3)
	v_fmac_f32_e32 v26, v6, v112
	v_fmac_f32_e32 v26, v7, v113
	v_fmac_f32_e32 v26, v8, v114
	v_fmac_f32_e32 v26, v9, v115
	ds_read_b128 v[6:9], v43 offset:41072
	s_waitcnt lgkmcnt(3)
	v_fmac_f32_e32 v27, v10, v112
	v_fmac_f32_e32 v27, v11, v113
	v_fmac_f32_e32 v27, v12, v114
	v_fmac_f32_e32 v27, v13, v115
	ds_read_b128 v[10:13], v43 offset:45168
	s_waitcnt lgkmcnt(3)
	v_fmac_f32_e32 v28, v38, v112
	v_fmac_f32_e32 v28, v39, v113
	v_fmac_f32_e32 v28, v40, v114
	v_fmac_f32_e32 v28, v41, v115
	ds_read_b128 v[38:41], v43 offset:49264
	s_waitcnt lgkmcnt(3)
	v_fmac_f32_e32 v29, v2, v112
	v_fmac_f32_e32 v29, v3, v113
	v_fmac_f32_e32 v29, v4, v114
	v_fmac_f32_e32 v29, v5, v115
	ds_read_b128 v[2:5], v43 offset:53360
	s_waitcnt lgkmcnt(3)
	v_fmac_f32_e32 v30, v6, v112
	v_fmac_f32_e32 v30, v7, v113
	v_fmac_f32_e32 v30, v8, v114
	v_fmac_f32_e32 v30, v9, v115
	ds_read_b128 v[6:9], v43 offset:57456
	s_waitcnt lgkmcnt(3)
	v_fmac_f32_e32 v31, v10, v112
	v_fmac_f32_e32 v31, v11, v113
	v_fmac_f32_e32 v31, v12, v114
	v_fmac_f32_e32 v31, v13, v115
	ds_read_b128 v[10:13], v43 offset:61552
	s_waitcnt lgkmcnt(3)
	v_fmac_f32_e32 v32, v38, v112
	v_fmac_f32_e32 v32, v39, v113
	v_fmac_f32_e32 v32, v40, v114
	v_fmac_f32_e32 v32, v41, v115
	ds_read_b128 v[38:41], v37 offset:112
	s_waitcnt lgkmcnt(3)
	v_fmac_f32_e32 v33, v2, v112
	v_fmac_f32_e32 v33, v3, v113
	v_fmac_f32_e32 v33, v4, v114
	v_fmac_f32_e32 v33, v5, v115
	ds_read_b128 v[2:5], v43 offset:1024
	s_waitcnt lgkmcnt(3)
	v_fmac_f32_e32 v34, v6, v112
	v_fmac_f32_e32 v34, v7, v113
	v_fmac_f32_e32 v34, v8, v114
	v_fmac_f32_e32 v34, v9, v115
	ds_read_b128 v[6:9], v43 offset:5120
	s_waitcnt lgkmcnt(3)
	v_fmac_f32_e32 v35, v10, v112
	v_fmac_f32_e32 v35, v11, v113
	v_fmac_f32_e32 v35, v12, v114
	v_fmac_f32_e32 v35, v13, v115
	ds_read_b128 v[10:13], v43 offset:9216
	s_waitcnt lgkmcnt(3)
	v_fmac_f32_e32 v36, v38, v112
	v_fmac_f32_e32 v36, v39, v113
	v_fmac_f32_e32 v36, v40, v114
	v_fmac_f32_e32 v36, v41, v115
	global_load_dword v148, v14, s[68:69]
	s_add_u32 s68, s68, 0x6000
	s_addc_u32 s69, s69, 0
	global_load_dword v149, v14, s[68:69]
	s_add_u32 s68, s68, 0x6000
	s_addc_u32 s69, s69, 0
	global_load_dword v150, v14, s[68:69]
	s_add_u32 s68, s68, 0x6000
	s_addc_u32 s69, s69, 0
	global_load_dword v151, v14, s[68:69]
	s_add_u32 s68, s68, 0x6000
	s_addc_u32 s69, s69, 0
	global_load_dword v152, v14, s[68:69]
	s_add_u32 s68, s68, 0x6000
	s_addc_u32 s69, s69, 0
	global_load_dword v153, v14, s[68:69]
	s_add_u32 s68, s68, 0x6000
	s_addc_u32 s69, s69, 0
	global_load_dword v154, v14, s[68:69]
	s_add_u32 s68, s68, 0x6000
	s_addc_u32 s69, s69, 0
	global_load_dword v155, v14, s[68:69]
	s_add_u32 s68, s68, 0x6000
	s_addc_u32 s69, s69, 0
	global_load_dword v156, v14, s[68:69]
	s_add_u32 s68, s68, 0x6000
	s_addc_u32 s69, s69, 0
	global_load_dword v157, v14, s[68:69]
	s_add_u32 s68, s68, 0x6000
	s_addc_u32 s69, s69, 0
	global_load_dword v158, v14, s[68:69]
	s_add_u32 s68, s68, 0x6000
	s_addc_u32 s69, s69, 0
	global_load_dword v159, v14, s[68:69]
	s_add_u32 s68, s68, 0x6000
	s_addc_u32 s69, s69, 0
	global_load_dword v160, v14, s[68:69]
	s_add_u32 s68, s68, 0x6000
	s_addc_u32 s69, s69, 0
	global_load_dword v161, v14, s[68:69]
	s_add_u32 s68, s68, 0x6000
	s_addc_u32 s69, s69, 0
	global_load_dword v162, v14, s[68:69]
	s_add_u32 s68, s68, 0x6000
	s_addc_u32 s69, s69, 0
	global_load_dword v163, v14, s[68:69]
	s_add_u32 s68, s68, 0x6000
	s_addc_u32 s69, s69, 0
	global_load_dword v164, v14, s[68:69]
	s_add_u32 s68, s68, 0x6000
	s_addc_u32 s69, s69, 0
	global_load_dword v165, v14, s[68:69]
	s_add_u32 s68, s68, 0x6000
	s_addc_u32 s69, s69, 0
	global_load_dword v166, v14, s[68:69]
	s_add_u32 s68, s68, 0x6000
	s_addc_u32 s69, s69, 0
	global_load_dword v167, v14, s[68:69]
	s_add_u32 s68, s68, 0x6000
	s_addc_u32 s69, s69, 0
	global_load_dword v168, v14, s[68:69]
	s_add_u32 s68, s68, 0x6000
	s_addc_u32 s69, s69, 0
	global_load_dword v169, v14, s[68:69]
	s_add_u32 s68, s68, 0x6000
	s_addc_u32 s69, s69, 0
	global_load_dword v170, v14, s[68:69]
	s_add_u32 s68, s68, 0x6000
	s_addc_u32 s69, s69, 0
	global_load_dword v171, v14, s[68:69]
	s_add_u32 s68, s68, 0x6000
	s_addc_u32 s69, s69, 0
	global_load_dword v172, v14, s[68:69]
	s_add_u32 s68, s68, 0x6000
	s_addc_u32 s69, s69, 0
	global_load_dword v173, v14, s[68:69]
	s_add_u32 s68, s68, 0x6000
	s_addc_u32 s69, s69, 0
	global_load_dword v174, v14, s[68:69]
	s_add_u32 s68, s68, 0x6000
	s_addc_u32 s69, s69, 0
	global_load_dword v175, v14, s[68:69]
	s_add_u32 s68, s68, 0x6000
	s_addc_u32 s69, s69, 0
	global_load_dword v176, v14, s[68:69]
	s_add_u32 s68, s68, 0x6000
	s_addc_u32 s69, s69, 0
	global_load_dword v177, v14, s[68:69]
	s_add_u32 s68, s68, 0x6000
	s_addc_u32 s69, s69, 0
	global_load_dword v178, v14, s[68:69]
	s_add_u32 s68, s68, 0x6000
	s_addc_u32 s69, s69, 0
	global_load_dword v179, v14, s[68:69]
	s_add_u32 s68, s68, 0x546000
	s_addc_u32 s69, s69, 0
	ds_read_b128 v[38:41], v43 offset:13312
	s_waitcnt vmcnt(60)
	s_waitcnt lgkmcnt(3)
	v_fmac_f32_e32 v20, v2, v116
	v_fmac_f32_e32 v20, v3, v117
	v_fmac_f32_e32 v20, v4, v118
	v_fmac_f32_e32 v20, v5, v119
	ds_read_b128 v[2:5], v43 offset:17408
	s_waitcnt lgkmcnt(3)
	v_fmac_f32_e32 v21, v6, v116
	v_fmac_f32_e32 v21, v7, v117
	v_fmac_f32_e32 v21, v8, v118
	v_fmac_f32_e32 v21, v9, v119
	ds_read_b128 v[6:9], v43 offset:21504
	s_waitcnt lgkmcnt(3)
	v_fmac_f32_e32 v22, v10, v116
	v_fmac_f32_e32 v22, v11, v117
	v_fmac_f32_e32 v22, v12, v118
	v_fmac_f32_e32 v22, v13, v119
	ds_read_b128 v[10:13], v43 offset:25600
	s_waitcnt lgkmcnt(3)
	v_fmac_f32_e32 v23, v38, v116
	v_fmac_f32_e32 v23, v39, v117
	v_fmac_f32_e32 v23, v40, v118
	v_fmac_f32_e32 v23, v41, v119
	ds_read_b128 v[38:41], v43 offset:29696
	s_waitcnt lgkmcnt(3)
	v_fmac_f32_e32 v24, v2, v116
	v_fmac_f32_e32 v24, v3, v117
	v_fmac_f32_e32 v24, v4, v118
	v_fmac_f32_e32 v24, v5, v119
	ds_read_b128 v[2:5], v43 offset:33792
	s_waitcnt lgkmcnt(3)
	v_fmac_f32_e32 v25, v6, v116
	v_fmac_f32_e32 v25, v7, v117
	v_fmac_f32_e32 v25, v8, v118
	v_fmac_f32_e32 v25, v9, v119
	ds_read_b128 v[6:9], v43 offset:37888
	s_waitcnt lgkmcnt(3)
	v_fmac_f32_e32 v26, v10, v116
	v_fmac_f32_e32 v26, v11, v117
	v_fmac_f32_e32 v26, v12, v118
	v_fmac_f32_e32 v26, v13, v119
	ds_read_b128 v[10:13], v43 offset:41984
	s_waitcnt lgkmcnt(3)
	v_fmac_f32_e32 v27, v38, v116
	v_fmac_f32_e32 v27, v39, v117
	v_fmac_f32_e32 v27, v40, v118
	v_fmac_f32_e32 v27, v41, v119
	ds_read_b128 v[38:41], v43 offset:46080
	s_waitcnt lgkmcnt(3)
	v_fmac_f32_e32 v28, v2, v116
	v_fmac_f32_e32 v28, v3, v117
	v_fmac_f32_e32 v28, v4, v118
	v_fmac_f32_e32 v28, v5, v119
	ds_read_b128 v[2:5], v43 offset:50176
	s_waitcnt lgkmcnt(3)
	v_fmac_f32_e32 v29, v6, v116
	v_fmac_f32_e32 v29, v7, v117
	v_fmac_f32_e32 v29, v8, v118
	v_fmac_f32_e32 v29, v9, v119
	ds_read_b128 v[6:9], v43 offset:54272
	s_waitcnt lgkmcnt(3)
	v_fmac_f32_e32 v30, v10, v116
	v_fmac_f32_e32 v30, v11, v117
	v_fmac_f32_e32 v30, v12, v118
	v_fmac_f32_e32 v30, v13, v119
	ds_read_b128 v[10:13], v43 offset:58368
	s_waitcnt lgkmcnt(3)
	v_fmac_f32_e32 v31, v38, v116
	v_fmac_f32_e32 v31, v39, v117
	v_fmac_f32_e32 v31, v40, v118
	v_fmac_f32_e32 v31, v41, v119
	ds_read_b128 v[38:41], v43 offset:62464
	s_waitcnt lgkmcnt(3)
	v_fmac_f32_e32 v32, v2, v116
	v_fmac_f32_e32 v32, v3, v117
	v_fmac_f32_e32 v32, v4, v118
	v_fmac_f32_e32 v32, v5, v119
	ds_read_b128 v[2:5], v37 offset:1024
	s_waitcnt lgkmcnt(3)
	v_fmac_f32_e32 v33, v6, v116
	v_fmac_f32_e32 v33, v7, v117
	v_fmac_f32_e32 v33, v8, v118
	v_fmac_f32_e32 v33, v9, v119
	ds_read_b128 v[6:9], v43 offset:1040
	s_waitcnt lgkmcnt(3)
	v_fmac_f32_e32 v34, v10, v116
	v_fmac_f32_e32 v34, v11, v117
	v_fmac_f32_e32 v34, v12, v118
	v_fmac_f32_e32 v34, v13, v119
	ds_read_b128 v[10:13], v43 offset:5136
	s_waitcnt lgkmcnt(3)
	v_fmac_f32_e32 v35, v38, v116
	v_fmac_f32_e32 v35, v39, v117
	v_fmac_f32_e32 v35, v40, v118
	v_fmac_f32_e32 v35, v41, v119
	ds_read_b128 v[38:41], v43 offset:9232
	s_waitcnt lgkmcnt(3)
	v_fmac_f32_e32 v36, v2, v116
	v_fmac_f32_e32 v36, v3, v117
	v_fmac_f32_e32 v36, v4, v118
	v_fmac_f32_e32 v36, v5, v119
	ds_read_b128 v[2:5], v43 offset:13328
	s_waitcnt vmcnt(56)
	s_waitcnt lgkmcnt(3)
	v_fmac_f32_e32 v20, v6, v120
	v_fmac_f32_e32 v20, v7, v121
	v_fmac_f32_e32 v20, v8, v122
	v_fmac_f32_e32 v20, v9, v123
	ds_read_b128 v[6:9], v43 offset:17424
	s_waitcnt lgkmcnt(3)
	v_fmac_f32_e32 v21, v10, v120
	v_fmac_f32_e32 v21, v11, v121
	v_fmac_f32_e32 v21, v12, v122
	v_fmac_f32_e32 v21, v13, v123
	ds_read_b128 v[10:13], v43 offset:21520
	s_waitcnt lgkmcnt(3)
	v_fmac_f32_e32 v22, v38, v120
	v_fmac_f32_e32 v22, v39, v121
	v_fmac_f32_e32 v22, v40, v122
	v_fmac_f32_e32 v22, v41, v123
	ds_read_b128 v[38:41], v43 offset:25616
	s_waitcnt lgkmcnt(3)
	v_fmac_f32_e32 v23, v2, v120
	v_fmac_f32_e32 v23, v3, v121
	v_fmac_f32_e32 v23, v4, v122
	v_fmac_f32_e32 v23, v5, v123
	ds_read_b128 v[2:5], v43 offset:29712
	s_waitcnt lgkmcnt(3)
	v_fmac_f32_e32 v24, v6, v120
	v_fmac_f32_e32 v24, v7, v121
	v_fmac_f32_e32 v24, v8, v122
	v_fmac_f32_e32 v24, v9, v123
	ds_read_b128 v[6:9], v43 offset:33808
	s_waitcnt lgkmcnt(3)
	v_fmac_f32_e32 v25, v10, v120
	v_fmac_f32_e32 v25, v11, v121
	v_fmac_f32_e32 v25, v12, v122
	v_fmac_f32_e32 v25, v13, v123
	ds_read_b128 v[10:13], v43 offset:37904
	s_waitcnt lgkmcnt(3)
	v_fmac_f32_e32 v26, v38, v120
	v_fmac_f32_e32 v26, v39, v121
	v_fmac_f32_e32 v26, v40, v122
	v_fmac_f32_e32 v26, v41, v123
	ds_read_b128 v[38:41], v43 offset:42000
	s_waitcnt lgkmcnt(3)
	v_fmac_f32_e32 v27, v2, v120
	v_fmac_f32_e32 v27, v3, v121
	v_fmac_f32_e32 v27, v4, v122
	v_fmac_f32_e32 v27, v5, v123
	ds_read_b128 v[2:5], v43 offset:46096
	s_waitcnt lgkmcnt(3)
	v_fmac_f32_e32 v28, v6, v120
	v_fmac_f32_e32 v28, v7, v121
	v_fmac_f32_e32 v28, v8, v122
	v_fmac_f32_e32 v28, v9, v123
	ds_read_b128 v[6:9], v43 offset:50192
	s_waitcnt lgkmcnt(3)
	v_fmac_f32_e32 v29, v10, v120
	v_fmac_f32_e32 v29, v11, v121
	v_fmac_f32_e32 v29, v12, v122
	v_fmac_f32_e32 v29, v13, v123
	ds_read_b128 v[10:13], v43 offset:54288
	s_waitcnt lgkmcnt(3)
	v_fmac_f32_e32 v30, v38, v120
	v_fmac_f32_e32 v30, v39, v121
	v_fmac_f32_e32 v30, v40, v122
	v_fmac_f32_e32 v30, v41, v123
	ds_read_b128 v[38:41], v43 offset:58384
	s_waitcnt lgkmcnt(3)
	v_fmac_f32_e32 v31, v2, v120
	v_fmac_f32_e32 v31, v3, v121
	v_fmac_f32_e32 v31, v4, v122
	v_fmac_f32_e32 v31, v5, v123
	ds_read_b128 v[2:5], v43 offset:62480
	s_waitcnt lgkmcnt(3)
	v_fmac_f32_e32 v32, v6, v120
	v_fmac_f32_e32 v32, v7, v121
	v_fmac_f32_e32 v32, v8, v122
	v_fmac_f32_e32 v32, v9, v123
	ds_read_b128 v[6:9], v37 offset:1040
	s_waitcnt lgkmcnt(3)
	v_fmac_f32_e32 v33, v10, v120
	v_fmac_f32_e32 v33, v11, v121
	v_fmac_f32_e32 v33, v12, v122
	v_fmac_f32_e32 v33, v13, v123
	ds_read_b128 v[10:13], v43 offset:1056
	s_waitcnt lgkmcnt(3)
	v_fmac_f32_e32 v34, v38, v120
	v_fmac_f32_e32 v34, v39, v121
	v_fmac_f32_e32 v34, v40, v122
	v_fmac_f32_e32 v34, v41, v123
	ds_read_b128 v[38:41], v43 offset:5152
	s_waitcnt lgkmcnt(3)
	v_fmac_f32_e32 v35, v2, v120
	v_fmac_f32_e32 v35, v3, v121
	v_fmac_f32_e32 v35, v4, v122
	v_fmac_f32_e32 v35, v5, v123
	ds_read_b128 v[2:5], v43 offset:9248
	s_waitcnt lgkmcnt(3)
	v_fmac_f32_e32 v36, v6, v120
	v_fmac_f32_e32 v36, v7, v121
	v_fmac_f32_e32 v36, v8, v122
	v_fmac_f32_e32 v36, v9, v123
	ds_read_b128 v[6:9], v43 offset:13344
	s_waitcnt vmcnt(52)
	s_waitcnt lgkmcnt(3)
	v_fmac_f32_e32 v20, v10, v124
	v_fmac_f32_e32 v20, v11, v125
	v_fmac_f32_e32 v20, v12, v126
	v_fmac_f32_e32 v20, v13, v127
	ds_read_b128 v[10:13], v43 offset:17440
	s_waitcnt lgkmcnt(3)
	v_fmac_f32_e32 v21, v38, v124
	v_fmac_f32_e32 v21, v39, v125
	v_fmac_f32_e32 v21, v40, v126
	v_fmac_f32_e32 v21, v41, v127
	ds_read_b128 v[38:41], v43 offset:21536
	s_waitcnt lgkmcnt(3)
	v_fmac_f32_e32 v22, v2, v124
	v_fmac_f32_e32 v22, v3, v125
	v_fmac_f32_e32 v22, v4, v126
	v_fmac_f32_e32 v22, v5, v127
	ds_read_b128 v[2:5], v43 offset:25632
	s_waitcnt lgkmcnt(3)
	v_fmac_f32_e32 v23, v6, v124
	v_fmac_f32_e32 v23, v7, v125
	v_fmac_f32_e32 v23, v8, v126
	v_fmac_f32_e32 v23, v9, v127
	ds_read_b128 v[6:9], v43 offset:29728
	s_waitcnt lgkmcnt(3)
	v_fmac_f32_e32 v24, v10, v124
	v_fmac_f32_e32 v24, v11, v125
	v_fmac_f32_e32 v24, v12, v126
	v_fmac_f32_e32 v24, v13, v127
	ds_read_b128 v[10:13], v43 offset:33824
	s_waitcnt lgkmcnt(3)
	v_fmac_f32_e32 v25, v38, v124
	v_fmac_f32_e32 v25, v39, v125
	v_fmac_f32_e32 v25, v40, v126
	v_fmac_f32_e32 v25, v41, v127
	ds_read_b128 v[38:41], v43 offset:37920
	s_waitcnt lgkmcnt(3)
	v_fmac_f32_e32 v26, v2, v124
	v_fmac_f32_e32 v26, v3, v125
	v_fmac_f32_e32 v26, v4, v126
	v_fmac_f32_e32 v26, v5, v127
	ds_read_b128 v[2:5], v43 offset:42016
	s_waitcnt lgkmcnt(3)
	v_fmac_f32_e32 v27, v6, v124
	v_fmac_f32_e32 v27, v7, v125
	v_fmac_f32_e32 v27, v8, v126
	v_fmac_f32_e32 v27, v9, v127
	ds_read_b128 v[6:9], v43 offset:46112
	s_waitcnt lgkmcnt(3)
	v_fmac_f32_e32 v28, v10, v124
	v_fmac_f32_e32 v28, v11, v125
	v_fmac_f32_e32 v28, v12, v126
	v_fmac_f32_e32 v28, v13, v127
	ds_read_b128 v[10:13], v43 offset:50208
	s_waitcnt lgkmcnt(3)
	v_fmac_f32_e32 v29, v38, v124
	v_fmac_f32_e32 v29, v39, v125
	v_fmac_f32_e32 v29, v40, v126
	v_fmac_f32_e32 v29, v41, v127
	ds_read_b128 v[38:41], v43 offset:54304
	s_waitcnt lgkmcnt(3)
	v_fmac_f32_e32 v30, v2, v124
	v_fmac_f32_e32 v30, v3, v125
	v_fmac_f32_e32 v30, v4, v126
	v_fmac_f32_e32 v30, v5, v127
	ds_read_b128 v[2:5], v43 offset:58400
	s_waitcnt lgkmcnt(3)
	v_fmac_f32_e32 v31, v6, v124
	v_fmac_f32_e32 v31, v7, v125
	v_fmac_f32_e32 v31, v8, v126
	v_fmac_f32_e32 v31, v9, v127
	ds_read_b128 v[6:9], v43 offset:62496
	s_waitcnt lgkmcnt(3)
	v_fmac_f32_e32 v32, v10, v124
	v_fmac_f32_e32 v32, v11, v125
	v_fmac_f32_e32 v32, v12, v126
	v_fmac_f32_e32 v32, v13, v127
	ds_read_b128 v[10:13], v37 offset:1056
	s_waitcnt lgkmcnt(3)
	v_fmac_f32_e32 v33, v38, v124
	v_fmac_f32_e32 v33, v39, v125
	v_fmac_f32_e32 v33, v40, v126
	v_fmac_f32_e32 v33, v41, v127
	ds_read_b128 v[38:41], v43 offset:1072
	s_waitcnt lgkmcnt(3)
	v_fmac_f32_e32 v34, v2, v124
	v_fmac_f32_e32 v34, v3, v125
	v_fmac_f32_e32 v34, v4, v126
	v_fmac_f32_e32 v34, v5, v127
	ds_read_b128 v[2:5], v43 offset:5168
	s_waitcnt lgkmcnt(3)
	v_fmac_f32_e32 v35, v6, v124
	v_fmac_f32_e32 v35, v7, v125
	v_fmac_f32_e32 v35, v8, v126
	v_fmac_f32_e32 v35, v9, v127
	ds_read_b128 v[6:9], v43 offset:9264
	s_waitcnt lgkmcnt(3)
	v_fmac_f32_e32 v36, v10, v124
	v_fmac_f32_e32 v36, v11, v125
	v_fmac_f32_e32 v36, v12, v126
	v_fmac_f32_e32 v36, v13, v127
	ds_read_b128 v[10:13], v43 offset:13360
	s_waitcnt vmcnt(48)
	s_waitcnt lgkmcnt(3)
	v_fmac_f32_e32 v20, v38, v128
	v_fmac_f32_e32 v20, v39, v129
	v_fmac_f32_e32 v20, v40, v130
	v_fmac_f32_e32 v20, v41, v131
	ds_read_b128 v[38:41], v43 offset:17456
	s_waitcnt lgkmcnt(3)
	v_fmac_f32_e32 v21, v2, v128
	v_fmac_f32_e32 v21, v3, v129
	v_fmac_f32_e32 v21, v4, v130
	v_fmac_f32_e32 v21, v5, v131
	ds_read_b128 v[2:5], v43 offset:21552
	s_waitcnt lgkmcnt(3)
	v_fmac_f32_e32 v22, v6, v128
	v_fmac_f32_e32 v22, v7, v129
	v_fmac_f32_e32 v22, v8, v130
	v_fmac_f32_e32 v22, v9, v131
	ds_read_b128 v[6:9], v43 offset:25648
	s_waitcnt lgkmcnt(3)
	v_fmac_f32_e32 v23, v10, v128
	v_fmac_f32_e32 v23, v11, v129
	v_fmac_f32_e32 v23, v12, v130
	v_fmac_f32_e32 v23, v13, v131
	ds_read_b128 v[10:13], v43 offset:29744
	s_waitcnt lgkmcnt(3)
	v_fmac_f32_e32 v24, v38, v128
	v_fmac_f32_e32 v24, v39, v129
	v_fmac_f32_e32 v24, v40, v130
	v_fmac_f32_e32 v24, v41, v131
	ds_read_b128 v[38:41], v43 offset:33840
	s_waitcnt lgkmcnt(3)
	v_fmac_f32_e32 v25, v2, v128
	v_fmac_f32_e32 v25, v3, v129
	v_fmac_f32_e32 v25, v4, v130
	v_fmac_f32_e32 v25, v5, v131
	ds_read_b128 v[2:5], v43 offset:37936
	s_waitcnt lgkmcnt(3)
	v_fmac_f32_e32 v26, v6, v128
	v_fmac_f32_e32 v26, v7, v129
	v_fmac_f32_e32 v26, v8, v130
	v_fmac_f32_e32 v26, v9, v131
	ds_read_b128 v[6:9], v43 offset:42032
	s_waitcnt lgkmcnt(3)
	v_fmac_f32_e32 v27, v10, v128
	v_fmac_f32_e32 v27, v11, v129
	v_fmac_f32_e32 v27, v12, v130
	v_fmac_f32_e32 v27, v13, v131
	ds_read_b128 v[10:13], v43 offset:46128
	s_waitcnt lgkmcnt(3)
	v_fmac_f32_e32 v28, v38, v128
	v_fmac_f32_e32 v28, v39, v129
	v_fmac_f32_e32 v28, v40, v130
	v_fmac_f32_e32 v28, v41, v131
	ds_read_b128 v[38:41], v43 offset:50224
	s_waitcnt lgkmcnt(3)
	v_fmac_f32_e32 v29, v2, v128
	v_fmac_f32_e32 v29, v3, v129
	v_fmac_f32_e32 v29, v4, v130
	v_fmac_f32_e32 v29, v5, v131
	ds_read_b128 v[2:5], v43 offset:54320
	s_waitcnt lgkmcnt(3)
	v_fmac_f32_e32 v30, v6, v128
	v_fmac_f32_e32 v30, v7, v129
	v_fmac_f32_e32 v30, v8, v130
	v_fmac_f32_e32 v30, v9, v131
	ds_read_b128 v[6:9], v43 offset:58416
	s_waitcnt lgkmcnt(3)
	v_fmac_f32_e32 v31, v10, v128
	v_fmac_f32_e32 v31, v11, v129
	v_fmac_f32_e32 v31, v12, v130
	v_fmac_f32_e32 v31, v13, v131
	ds_read_b128 v[10:13], v43 offset:62512
	s_waitcnt lgkmcnt(3)
	v_fmac_f32_e32 v32, v38, v128
	v_fmac_f32_e32 v32, v39, v129
	v_fmac_f32_e32 v32, v40, v130
	v_fmac_f32_e32 v32, v41, v131
	ds_read_b128 v[38:41], v37 offset:1072
	s_waitcnt lgkmcnt(3)
	v_fmac_f32_e32 v33, v2, v128
	v_fmac_f32_e32 v33, v3, v129
	v_fmac_f32_e32 v33, v4, v130
	v_fmac_f32_e32 v33, v5, v131
	ds_read_b128 v[2:5], v43 offset:1088
	s_waitcnt lgkmcnt(3)
	v_fmac_f32_e32 v34, v6, v128
	v_fmac_f32_e32 v34, v7, v129
	v_fmac_f32_e32 v34, v8, v130
	v_fmac_f32_e32 v34, v9, v131
	ds_read_b128 v[6:9], v43 offset:5184
	s_waitcnt lgkmcnt(3)
	v_fmac_f32_e32 v35, v10, v128
	v_fmac_f32_e32 v35, v11, v129
	v_fmac_f32_e32 v35, v12, v130
	v_fmac_f32_e32 v35, v13, v131
	ds_read_b128 v[10:13], v43 offset:9280
	s_waitcnt lgkmcnt(3)
	v_fmac_f32_e32 v36, v38, v128
	v_fmac_f32_e32 v36, v39, v129
	v_fmac_f32_e32 v36, v40, v130
	v_fmac_f32_e32 v36, v41, v131
	ds_read_b128 v[38:41], v43 offset:13376
	s_waitcnt vmcnt(44)
	s_waitcnt lgkmcnt(3)
	v_fmac_f32_e32 v20, v2, v132
	v_fmac_f32_e32 v20, v3, v133
	v_fmac_f32_e32 v20, v4, v134
	v_fmac_f32_e32 v20, v5, v135
	ds_read_b128 v[2:5], v43 offset:17472
	s_waitcnt lgkmcnt(3)
	v_fmac_f32_e32 v21, v6, v132
	v_fmac_f32_e32 v21, v7, v133
	v_fmac_f32_e32 v21, v8, v134
	v_fmac_f32_e32 v21, v9, v135
	ds_read_b128 v[6:9], v43 offset:21568
	s_waitcnt lgkmcnt(3)
	v_fmac_f32_e32 v22, v10, v132
	v_fmac_f32_e32 v22, v11, v133
	v_fmac_f32_e32 v22, v12, v134
	v_fmac_f32_e32 v22, v13, v135
	ds_read_b128 v[10:13], v43 offset:25664
	s_waitcnt lgkmcnt(3)
	v_fmac_f32_e32 v23, v38, v132
	v_fmac_f32_e32 v23, v39, v133
	v_fmac_f32_e32 v23, v40, v134
	v_fmac_f32_e32 v23, v41, v135
	ds_read_b128 v[38:41], v43 offset:29760
	s_waitcnt lgkmcnt(3)
	v_fmac_f32_e32 v24, v2, v132
	v_fmac_f32_e32 v24, v3, v133
	v_fmac_f32_e32 v24, v4, v134
	v_fmac_f32_e32 v24, v5, v135
	ds_read_b128 v[2:5], v43 offset:33856
	s_waitcnt lgkmcnt(3)
	v_fmac_f32_e32 v25, v6, v132
	v_fmac_f32_e32 v25, v7, v133
	v_fmac_f32_e32 v25, v8, v134
	v_fmac_f32_e32 v25, v9, v135
	ds_read_b128 v[6:9], v43 offset:37952
	s_waitcnt lgkmcnt(3)
	v_fmac_f32_e32 v26, v10, v132
	v_fmac_f32_e32 v26, v11, v133
	v_fmac_f32_e32 v26, v12, v134
	v_fmac_f32_e32 v26, v13, v135
	ds_read_b128 v[10:13], v43 offset:42048
	s_waitcnt lgkmcnt(3)
	v_fmac_f32_e32 v27, v38, v132
	v_fmac_f32_e32 v27, v39, v133
	v_fmac_f32_e32 v27, v40, v134
	v_fmac_f32_e32 v27, v41, v135
	ds_read_b128 v[38:41], v43 offset:46144
	s_waitcnt lgkmcnt(3)
	v_fmac_f32_e32 v28, v2, v132
	v_fmac_f32_e32 v28, v3, v133
	v_fmac_f32_e32 v28, v4, v134
	v_fmac_f32_e32 v28, v5, v135
	ds_read_b128 v[2:5], v43 offset:50240
	s_waitcnt lgkmcnt(3)
	v_fmac_f32_e32 v29, v6, v132
	v_fmac_f32_e32 v29, v7, v133
	v_fmac_f32_e32 v29, v8, v134
	v_fmac_f32_e32 v29, v9, v135
	ds_read_b128 v[6:9], v43 offset:54336
	s_waitcnt lgkmcnt(3)
	v_fmac_f32_e32 v30, v10, v132
	v_fmac_f32_e32 v30, v11, v133
	v_fmac_f32_e32 v30, v12, v134
	v_fmac_f32_e32 v30, v13, v135
	ds_read_b128 v[10:13], v43 offset:58432
	s_waitcnt lgkmcnt(3)
	v_fmac_f32_e32 v31, v38, v132
	v_fmac_f32_e32 v31, v39, v133
	v_fmac_f32_e32 v31, v40, v134
	v_fmac_f32_e32 v31, v41, v135
	ds_read_b128 v[38:41], v43 offset:62528
	s_waitcnt lgkmcnt(3)
	v_fmac_f32_e32 v32, v2, v132
	v_fmac_f32_e32 v32, v3, v133
	v_fmac_f32_e32 v32, v4, v134
	v_fmac_f32_e32 v32, v5, v135
	ds_read_b128 v[2:5], v37 offset:1088
	s_waitcnt lgkmcnt(3)
	v_fmac_f32_e32 v33, v6, v132
	v_fmac_f32_e32 v33, v7, v133
	v_fmac_f32_e32 v33, v8, v134
	v_fmac_f32_e32 v33, v9, v135
	ds_read_b128 v[6:9], v43 offset:1104
	s_waitcnt lgkmcnt(3)
	v_fmac_f32_e32 v34, v10, v132
	v_fmac_f32_e32 v34, v11, v133
	v_fmac_f32_e32 v34, v12, v134
	v_fmac_f32_e32 v34, v13, v135
	ds_read_b128 v[10:13], v43 offset:5200
	s_waitcnt lgkmcnt(3)
	v_fmac_f32_e32 v35, v38, v132
	v_fmac_f32_e32 v35, v39, v133
	v_fmac_f32_e32 v35, v40, v134
	v_fmac_f32_e32 v35, v41, v135
	ds_read_b128 v[38:41], v43 offset:9296
	s_waitcnt lgkmcnt(3)
	v_fmac_f32_e32 v36, v2, v132
	v_fmac_f32_e32 v36, v3, v133
	v_fmac_f32_e32 v36, v4, v134
	v_fmac_f32_e32 v36, v5, v135
	ds_read_b128 v[2:5], v43 offset:13392
	s_waitcnt vmcnt(40)
	s_waitcnt lgkmcnt(3)
	v_fmac_f32_e32 v20, v6, v136
	v_fmac_f32_e32 v20, v7, v137
	v_fmac_f32_e32 v20, v8, v138
	v_fmac_f32_e32 v20, v9, v139
	ds_read_b128 v[6:9], v43 offset:17488
	s_waitcnt lgkmcnt(3)
	v_fmac_f32_e32 v21, v10, v136
	v_fmac_f32_e32 v21, v11, v137
	v_fmac_f32_e32 v21, v12, v138
	v_fmac_f32_e32 v21, v13, v139
	ds_read_b128 v[10:13], v43 offset:21584
	s_waitcnt lgkmcnt(3)
	v_fmac_f32_e32 v22, v38, v136
	v_fmac_f32_e32 v22, v39, v137
	v_fmac_f32_e32 v22, v40, v138
	v_fmac_f32_e32 v22, v41, v139
	ds_read_b128 v[38:41], v43 offset:25680
	s_waitcnt lgkmcnt(3)
	v_fmac_f32_e32 v23, v2, v136
	v_fmac_f32_e32 v23, v3, v137
	v_fmac_f32_e32 v23, v4, v138
	v_fmac_f32_e32 v23, v5, v139
	ds_read_b128 v[2:5], v43 offset:29776
	s_waitcnt lgkmcnt(3)
	v_fmac_f32_e32 v24, v6, v136
	v_fmac_f32_e32 v24, v7, v137
	v_fmac_f32_e32 v24, v8, v138
	v_fmac_f32_e32 v24, v9, v139
	ds_read_b128 v[6:9], v43 offset:33872
	s_waitcnt lgkmcnt(3)
	v_fmac_f32_e32 v25, v10, v136
	v_fmac_f32_e32 v25, v11, v137
	v_fmac_f32_e32 v25, v12, v138
	v_fmac_f32_e32 v25, v13, v139
	ds_read_b128 v[10:13], v43 offset:37968
	s_waitcnt lgkmcnt(3)
	v_fmac_f32_e32 v26, v38, v136
	v_fmac_f32_e32 v26, v39, v137
	v_fmac_f32_e32 v26, v40, v138
	v_fmac_f32_e32 v26, v41, v139
	ds_read_b128 v[38:41], v43 offset:42064
	s_waitcnt lgkmcnt(3)
	v_fmac_f32_e32 v27, v2, v136
	v_fmac_f32_e32 v27, v3, v137
	v_fmac_f32_e32 v27, v4, v138
	v_fmac_f32_e32 v27, v5, v139
	ds_read_b128 v[2:5], v43 offset:46160
	s_waitcnt lgkmcnt(3)
	v_fmac_f32_e32 v28, v6, v136
	v_fmac_f32_e32 v28, v7, v137
	v_fmac_f32_e32 v28, v8, v138
	v_fmac_f32_e32 v28, v9, v139
	ds_read_b128 v[6:9], v43 offset:50256
	s_waitcnt lgkmcnt(3)
	v_fmac_f32_e32 v29, v10, v136
	v_fmac_f32_e32 v29, v11, v137
	v_fmac_f32_e32 v29, v12, v138
	v_fmac_f32_e32 v29, v13, v139
	ds_read_b128 v[10:13], v43 offset:54352
	s_waitcnt lgkmcnt(3)
	v_fmac_f32_e32 v30, v38, v136
	v_fmac_f32_e32 v30, v39, v137
	v_fmac_f32_e32 v30, v40, v138
	v_fmac_f32_e32 v30, v41, v139
	ds_read_b128 v[38:41], v43 offset:58448
	s_waitcnt lgkmcnt(3)
	v_fmac_f32_e32 v31, v2, v136
	v_fmac_f32_e32 v31, v3, v137
	v_fmac_f32_e32 v31, v4, v138
	v_fmac_f32_e32 v31, v5, v139
	ds_read_b128 v[2:5], v43 offset:62544
	s_waitcnt lgkmcnt(3)
	v_fmac_f32_e32 v32, v6, v136
	v_fmac_f32_e32 v32, v7, v137
	v_fmac_f32_e32 v32, v8, v138
	v_fmac_f32_e32 v32, v9, v139
	ds_read_b128 v[6:9], v37 offset:1104
	s_waitcnt lgkmcnt(3)
	v_fmac_f32_e32 v33, v10, v136
	v_fmac_f32_e32 v33, v11, v137
	v_fmac_f32_e32 v33, v12, v138
	v_fmac_f32_e32 v33, v13, v139
	ds_read_b128 v[10:13], v43 offset:1120
	s_waitcnt lgkmcnt(3)
	v_fmac_f32_e32 v34, v38, v136
	v_fmac_f32_e32 v34, v39, v137
	v_fmac_f32_e32 v34, v40, v138
	v_fmac_f32_e32 v34, v41, v139
	ds_read_b128 v[38:41], v43 offset:5216
	s_waitcnt lgkmcnt(3)
	v_fmac_f32_e32 v35, v2, v136
	v_fmac_f32_e32 v35, v3, v137
	v_fmac_f32_e32 v35, v4, v138
	v_fmac_f32_e32 v35, v5, v139
	ds_read_b128 v[2:5], v43 offset:9312
	s_waitcnt lgkmcnt(3)
	v_fmac_f32_e32 v36, v6, v136
	v_fmac_f32_e32 v36, v7, v137
	v_fmac_f32_e32 v36, v8, v138
	v_fmac_f32_e32 v36, v9, v139
	ds_read_b128 v[6:9], v43 offset:13408
	s_waitcnt vmcnt(36)
	s_waitcnt lgkmcnt(3)
	v_fmac_f32_e32 v20, v10, v140
	v_fmac_f32_e32 v20, v11, v141
	v_fmac_f32_e32 v20, v12, v142
	v_fmac_f32_e32 v20, v13, v143
	ds_read_b128 v[10:13], v43 offset:17504
	s_waitcnt lgkmcnt(3)
	v_fmac_f32_e32 v21, v38, v140
	v_fmac_f32_e32 v21, v39, v141
	v_fmac_f32_e32 v21, v40, v142
	v_fmac_f32_e32 v21, v41, v143
	ds_read_b128 v[38:41], v43 offset:21600
	s_waitcnt lgkmcnt(3)
	v_fmac_f32_e32 v22, v2, v140
	v_fmac_f32_e32 v22, v3, v141
	v_fmac_f32_e32 v22, v4, v142
	v_fmac_f32_e32 v22, v5, v143
	ds_read_b128 v[2:5], v43 offset:25696
	s_waitcnt lgkmcnt(3)
	v_fmac_f32_e32 v23, v6, v140
	v_fmac_f32_e32 v23, v7, v141
	v_fmac_f32_e32 v23, v8, v142
	v_fmac_f32_e32 v23, v9, v143
	ds_read_b128 v[6:9], v43 offset:29792
	s_waitcnt lgkmcnt(3)
	v_fmac_f32_e32 v24, v10, v140
	v_fmac_f32_e32 v24, v11, v141
	v_fmac_f32_e32 v24, v12, v142
	v_fmac_f32_e32 v24, v13, v143
	ds_read_b128 v[10:13], v43 offset:33888
	s_waitcnt lgkmcnt(3)
	v_fmac_f32_e32 v25, v38, v140
	v_fmac_f32_e32 v25, v39, v141
	v_fmac_f32_e32 v25, v40, v142
	v_fmac_f32_e32 v25, v41, v143
	ds_read_b128 v[38:41], v43 offset:37984
	s_waitcnt lgkmcnt(3)
	v_fmac_f32_e32 v26, v2, v140
	v_fmac_f32_e32 v26, v3, v141
	v_fmac_f32_e32 v26, v4, v142
	v_fmac_f32_e32 v26, v5, v143
	ds_read_b128 v[2:5], v43 offset:42080
	s_waitcnt lgkmcnt(3)
	v_fmac_f32_e32 v27, v6, v140
	v_fmac_f32_e32 v27, v7, v141
	v_fmac_f32_e32 v27, v8, v142
	v_fmac_f32_e32 v27, v9, v143
	ds_read_b128 v[6:9], v43 offset:46176
	s_waitcnt lgkmcnt(3)
	v_fmac_f32_e32 v28, v10, v140
	v_fmac_f32_e32 v28, v11, v141
	v_fmac_f32_e32 v28, v12, v142
	v_fmac_f32_e32 v28, v13, v143
	ds_read_b128 v[10:13], v43 offset:50272
	s_waitcnt lgkmcnt(3)
	v_fmac_f32_e32 v29, v38, v140
	v_fmac_f32_e32 v29, v39, v141
	v_fmac_f32_e32 v29, v40, v142
	v_fmac_f32_e32 v29, v41, v143
	ds_read_b128 v[38:41], v43 offset:54368
	s_waitcnt lgkmcnt(3)
	v_fmac_f32_e32 v30, v2, v140
	v_fmac_f32_e32 v30, v3, v141
	v_fmac_f32_e32 v30, v4, v142
	v_fmac_f32_e32 v30, v5, v143
	ds_read_b128 v[2:5], v43 offset:58464
	s_waitcnt lgkmcnt(3)
	v_fmac_f32_e32 v31, v6, v140
	v_fmac_f32_e32 v31, v7, v141
	v_fmac_f32_e32 v31, v8, v142
	v_fmac_f32_e32 v31, v9, v143
	ds_read_b128 v[6:9], v43 offset:62560
	s_waitcnt lgkmcnt(3)
	v_fmac_f32_e32 v32, v10, v140
	v_fmac_f32_e32 v32, v11, v141
	v_fmac_f32_e32 v32, v12, v142
	v_fmac_f32_e32 v32, v13, v143
	ds_read_b128 v[10:13], v37 offset:1120
	s_waitcnt lgkmcnt(3)
	v_fmac_f32_e32 v33, v38, v140
	v_fmac_f32_e32 v33, v39, v141
	v_fmac_f32_e32 v33, v40, v142
	v_fmac_f32_e32 v33, v41, v143
	ds_read_b128 v[38:41], v43 offset:1136
	s_waitcnt lgkmcnt(3)
	v_fmac_f32_e32 v34, v2, v140
	v_fmac_f32_e32 v34, v3, v141
	v_fmac_f32_e32 v34, v4, v142
	v_fmac_f32_e32 v34, v5, v143
	ds_read_b128 v[2:5], v43 offset:5232
	s_waitcnt lgkmcnt(3)
	v_fmac_f32_e32 v35, v6, v140
	v_fmac_f32_e32 v35, v7, v141
	v_fmac_f32_e32 v35, v8, v142
	v_fmac_f32_e32 v35, v9, v143
	ds_read_b128 v[6:9], v43 offset:9328
	s_waitcnt lgkmcnt(3)
	v_fmac_f32_e32 v36, v10, v140
	v_fmac_f32_e32 v36, v11, v141
	v_fmac_f32_e32 v36, v12, v142
	v_fmac_f32_e32 v36, v13, v143
	ds_read_b128 v[10:13], v43 offset:13424
	s_waitcnt vmcnt(32)
	s_waitcnt lgkmcnt(3)
	v_fmac_f32_e32 v20, v38, v144
	v_fmac_f32_e32 v20, v39, v145
	v_fmac_f32_e32 v20, v40, v146
	v_fmac_f32_e32 v20, v41, v147
	ds_read_b128 v[38:41], v43 offset:17520
	s_waitcnt lgkmcnt(3)
	v_fmac_f32_e32 v21, v2, v144
	v_fmac_f32_e32 v21, v3, v145
	v_fmac_f32_e32 v21, v4, v146
	v_fmac_f32_e32 v21, v5, v147
	ds_read_b128 v[2:5], v43 offset:21616
	s_waitcnt lgkmcnt(3)
	v_fmac_f32_e32 v22, v6, v144
	v_fmac_f32_e32 v22, v7, v145
	v_fmac_f32_e32 v22, v8, v146
	v_fmac_f32_e32 v22, v9, v147
	ds_read_b128 v[6:9], v43 offset:25712
	s_waitcnt lgkmcnt(3)
	v_fmac_f32_e32 v23, v10, v144
	v_fmac_f32_e32 v23, v11, v145
	v_fmac_f32_e32 v23, v12, v146
	v_fmac_f32_e32 v23, v13, v147
	ds_read_b128 v[10:13], v43 offset:29808
	s_waitcnt lgkmcnt(3)
	v_fmac_f32_e32 v24, v38, v144
	v_fmac_f32_e32 v24, v39, v145
	v_fmac_f32_e32 v24, v40, v146
	v_fmac_f32_e32 v24, v41, v147
	ds_read_b128 v[38:41], v43 offset:33904
	s_waitcnt lgkmcnt(3)
	v_fmac_f32_e32 v25, v2, v144
	v_fmac_f32_e32 v25, v3, v145
	v_fmac_f32_e32 v25, v4, v146
	v_fmac_f32_e32 v25, v5, v147
	ds_read_b128 v[2:5], v43 offset:38000
	s_waitcnt lgkmcnt(3)
	v_fmac_f32_e32 v26, v6, v144
	v_fmac_f32_e32 v26, v7, v145
	v_fmac_f32_e32 v26, v8, v146
	v_fmac_f32_e32 v26, v9, v147
	ds_read_b128 v[6:9], v43 offset:42096
	s_waitcnt lgkmcnt(3)
	v_fmac_f32_e32 v27, v10, v144
	v_fmac_f32_e32 v27, v11, v145
	v_fmac_f32_e32 v27, v12, v146
	v_fmac_f32_e32 v27, v13, v147
	ds_read_b128 v[10:13], v43 offset:46192
	s_waitcnt lgkmcnt(3)
	v_fmac_f32_e32 v28, v38, v144
	v_fmac_f32_e32 v28, v39, v145
	v_fmac_f32_e32 v28, v40, v146
	v_fmac_f32_e32 v28, v41, v147
	ds_read_b128 v[38:41], v43 offset:50288
	s_waitcnt lgkmcnt(3)
	v_fmac_f32_e32 v29, v2, v144
	v_fmac_f32_e32 v29, v3, v145
	v_fmac_f32_e32 v29, v4, v146
	v_fmac_f32_e32 v29, v5, v147
	ds_read_b128 v[2:5], v43 offset:54384
	s_waitcnt lgkmcnt(3)
	v_fmac_f32_e32 v30, v6, v144
	v_fmac_f32_e32 v30, v7, v145
	v_fmac_f32_e32 v30, v8, v146
	v_fmac_f32_e32 v30, v9, v147
	ds_read_b128 v[6:9], v43 offset:58480
	s_waitcnt lgkmcnt(3)
	v_fmac_f32_e32 v31, v10, v144
	v_fmac_f32_e32 v31, v11, v145
	v_fmac_f32_e32 v31, v12, v146
	v_fmac_f32_e32 v31, v13, v147
	ds_read_b128 v[10:13], v43 offset:62576
	s_waitcnt lgkmcnt(3)
	v_fmac_f32_e32 v32, v38, v144
	v_fmac_f32_e32 v32, v39, v145
	v_fmac_f32_e32 v32, v40, v146
	v_fmac_f32_e32 v32, v41, v147
	ds_read_b128 v[38:41], v37 offset:1136
	s_waitcnt lgkmcnt(3)
	v_fmac_f32_e32 v33, v2, v144
	v_fmac_f32_e32 v33, v3, v145
	v_fmac_f32_e32 v33, v4, v146
	v_fmac_f32_e32 v33, v5, v147
	ds_read_b128 v[2:5], v43 offset:2048
	s_waitcnt lgkmcnt(3)
	v_fmac_f32_e32 v34, v6, v144
	v_fmac_f32_e32 v34, v7, v145
	v_fmac_f32_e32 v34, v8, v146
	v_fmac_f32_e32 v34, v9, v147
	ds_read_b128 v[6:9], v43 offset:6144
	s_waitcnt lgkmcnt(3)
	v_fmac_f32_e32 v35, v10, v144
	v_fmac_f32_e32 v35, v11, v145
	v_fmac_f32_e32 v35, v12, v146
	v_fmac_f32_e32 v35, v13, v147
	ds_read_b128 v[10:13], v43 offset:10240
	s_waitcnt lgkmcnt(3)
	v_fmac_f32_e32 v36, v38, v144
	v_fmac_f32_e32 v36, v39, v145
	v_fmac_f32_e32 v36, v40, v146
	v_fmac_f32_e32 v36, v41, v147
	global_load_dword v180, v14, s[68:69]
	s_add_u32 s68, s68, 0x6000
	s_addc_u32 s69, s69, 0
	global_load_dword v181, v14, s[68:69]
	s_add_u32 s68, s68, 0x6000
	s_addc_u32 s69, s69, 0
	global_load_dword v182, v14, s[68:69]
	s_add_u32 s68, s68, 0x6000
	s_addc_u32 s69, s69, 0
	global_load_dword v183, v14, s[68:69]
	s_add_u32 s68, s68, 0x6000
	s_addc_u32 s69, s69, 0
	global_load_dword v184, v14, s[68:69]
	s_add_u32 s68, s68, 0x6000
	s_addc_u32 s69, s69, 0
	global_load_dword v185, v14, s[68:69]
	s_add_u32 s68, s68, 0x6000
	s_addc_u32 s69, s69, 0
	global_load_dword v186, v14, s[68:69]
	s_add_u32 s68, s68, 0x6000
	s_addc_u32 s69, s69, 0
	global_load_dword v187, v14, s[68:69]
	s_add_u32 s68, s68, 0x6000
	s_addc_u32 s69, s69, 0
	global_load_dword v188, v14, s[68:69]
	s_add_u32 s68, s68, 0x6000
	s_addc_u32 s69, s69, 0
	global_load_dword v189, v14, s[68:69]
	s_add_u32 s68, s68, 0x6000
	s_addc_u32 s69, s69, 0
	global_load_dword v190, v14, s[68:69]
	s_add_u32 s68, s68, 0x6000
	s_addc_u32 s69, s69, 0
	global_load_dword v191, v14, s[68:69]
	s_add_u32 s68, s68, 0x6000
	s_addc_u32 s69, s69, 0
	global_load_dword v192, v14, s[68:69]
	s_add_u32 s68, s68, 0x6000
	s_addc_u32 s69, s69, 0
	global_load_dword v193, v14, s[68:69]
	s_add_u32 s68, s68, 0x6000
	s_addc_u32 s69, s69, 0
	global_load_dword v194, v14, s[68:69]
	s_add_u32 s68, s68, 0x6000
	s_addc_u32 s69, s69, 0
	global_load_dword v195, v14, s[68:69]
	s_add_u32 s68, s68, 0x6000
	s_addc_u32 s69, s69, 0
	global_load_dword v196, v14, s[68:69]
	s_add_u32 s68, s68, 0x6000
	s_addc_u32 s69, s69, 0
	global_load_dword v197, v14, s[68:69]
	s_add_u32 s68, s68, 0x6000
	s_addc_u32 s69, s69, 0
	global_load_dword v198, v14, s[68:69]
	s_add_u32 s68, s68, 0x6000
	s_addc_u32 s69, s69, 0
	global_load_dword v199, v14, s[68:69]
	s_add_u32 s68, s68, 0x6000
	s_addc_u32 s69, s69, 0
	global_load_dword v200, v14, s[68:69]
	s_add_u32 s68, s68, 0x6000
	s_addc_u32 s69, s69, 0
	global_load_dword v201, v14, s[68:69]
	s_add_u32 s68, s68, 0x6000
	s_addc_u32 s69, s69, 0
	global_load_dword v202, v14, s[68:69]
	s_add_u32 s68, s68, 0x6000
	s_addc_u32 s69, s69, 0
	global_load_dword v203, v14, s[68:69]
	s_add_u32 s68, s68, 0x6000
	s_addc_u32 s69, s69, 0
	global_load_dword v204, v14, s[68:69]
	s_add_u32 s68, s68, 0x6000
	s_addc_u32 s69, s69, 0
	global_load_dword v205, v14, s[68:69]
	s_add_u32 s68, s68, 0x6000
	s_addc_u32 s69, s69, 0
	global_load_dword v206, v14, s[68:69]
	s_add_u32 s68, s68, 0x6000
	s_addc_u32 s69, s69, 0
	global_load_dword v207, v14, s[68:69]
	s_add_u32 s68, s68, 0x6000
	s_addc_u32 s69, s69, 0
	global_load_dword v208, v14, s[68:69]
	s_add_u32 s68, s68, 0x6000
	s_addc_u32 s69, s69, 0
	global_load_dword v209, v14, s[68:69]
	s_add_u32 s68, s68, 0x6000
	s_addc_u32 s69, s69, 0
	global_load_dword v210, v14, s[68:69]
	s_add_u32 s68, s68, 0x6000
	s_addc_u32 s69, s69, 0
	global_load_dword v211, v14, s[68:69]
	ds_read_b128 v[38:41], v43 offset:14336
	s_waitcnt vmcnt(60)
	s_waitcnt lgkmcnt(3)
	v_fmac_f32_e32 v20, v2, v148
	v_fmac_f32_e32 v20, v3, v149
	v_fmac_f32_e32 v20, v4, v150
	v_fmac_f32_e32 v20, v5, v151
	ds_read_b128 v[2:5], v43 offset:18432
	s_waitcnt lgkmcnt(3)
	v_fmac_f32_e32 v21, v6, v148
	v_fmac_f32_e32 v21, v7, v149
	v_fmac_f32_e32 v21, v8, v150
	v_fmac_f32_e32 v21, v9, v151
	ds_read_b128 v[6:9], v43 offset:22528
	s_waitcnt lgkmcnt(3)
	v_fmac_f32_e32 v22, v10, v148
	v_fmac_f32_e32 v22, v11, v149
	v_fmac_f32_e32 v22, v12, v150
	v_fmac_f32_e32 v22, v13, v151
	ds_read_b128 v[10:13], v43 offset:26624
	s_waitcnt lgkmcnt(3)
	v_fmac_f32_e32 v23, v38, v148
	v_fmac_f32_e32 v23, v39, v149
	v_fmac_f32_e32 v23, v40, v150
	v_fmac_f32_e32 v23, v41, v151
	ds_read_b128 v[38:41], v43 offset:30720
	s_waitcnt lgkmcnt(3)
	v_fmac_f32_e32 v24, v2, v148
	v_fmac_f32_e32 v24, v3, v149
	v_fmac_f32_e32 v24, v4, v150
	v_fmac_f32_e32 v24, v5, v151
	ds_read_b128 v[2:5], v43 offset:34816
	s_waitcnt lgkmcnt(3)
	v_fmac_f32_e32 v25, v6, v148
	v_fmac_f32_e32 v25, v7, v149
	v_fmac_f32_e32 v25, v8, v150
	v_fmac_f32_e32 v25, v9, v151
	ds_read_b128 v[6:9], v43 offset:38912
	s_waitcnt lgkmcnt(3)
	v_fmac_f32_e32 v26, v10, v148
	v_fmac_f32_e32 v26, v11, v149
	v_fmac_f32_e32 v26, v12, v150
	v_fmac_f32_e32 v26, v13, v151
	ds_read_b128 v[10:13], v43 offset:43008
	s_waitcnt lgkmcnt(3)
	v_fmac_f32_e32 v27, v38, v148
	v_fmac_f32_e32 v27, v39, v149
	v_fmac_f32_e32 v27, v40, v150
	v_fmac_f32_e32 v27, v41, v151
	ds_read_b128 v[38:41], v43 offset:47104
	s_waitcnt lgkmcnt(3)
	v_fmac_f32_e32 v28, v2, v148
	v_fmac_f32_e32 v28, v3, v149
	v_fmac_f32_e32 v28, v4, v150
	v_fmac_f32_e32 v28, v5, v151
	ds_read_b128 v[2:5], v43 offset:51200
	s_waitcnt lgkmcnt(3)
	v_fmac_f32_e32 v29, v6, v148
	v_fmac_f32_e32 v29, v7, v149
	v_fmac_f32_e32 v29, v8, v150
	v_fmac_f32_e32 v29, v9, v151
	ds_read_b128 v[6:9], v43 offset:55296
	s_waitcnt lgkmcnt(3)
	v_fmac_f32_e32 v30, v10, v148
	v_fmac_f32_e32 v30, v11, v149
	v_fmac_f32_e32 v30, v12, v150
	v_fmac_f32_e32 v30, v13, v151
	ds_read_b128 v[10:13], v43 offset:59392
	s_waitcnt lgkmcnt(3)
	v_fmac_f32_e32 v31, v38, v148
	v_fmac_f32_e32 v31, v39, v149
	v_fmac_f32_e32 v31, v40, v150
	v_fmac_f32_e32 v31, v41, v151
	ds_read_b128 v[38:41], v43 offset:63488
	s_waitcnt lgkmcnt(3)
	v_fmac_f32_e32 v32, v2, v148
	v_fmac_f32_e32 v32, v3, v149
	v_fmac_f32_e32 v32, v4, v150
	v_fmac_f32_e32 v32, v5, v151
	ds_read_b128 v[2:5], v37 offset:2048
	s_waitcnt lgkmcnt(3)
	v_fmac_f32_e32 v33, v6, v148
	v_fmac_f32_e32 v33, v7, v149
	v_fmac_f32_e32 v33, v8, v150
	v_fmac_f32_e32 v33, v9, v151
	ds_read_b128 v[6:9], v43 offset:2064
	s_waitcnt lgkmcnt(3)
	v_fmac_f32_e32 v34, v10, v148
	v_fmac_f32_e32 v34, v11, v149
	v_fmac_f32_e32 v34, v12, v150
	v_fmac_f32_e32 v34, v13, v151
	ds_read_b128 v[10:13], v43 offset:6160
	s_waitcnt lgkmcnt(3)
	v_fmac_f32_e32 v35, v38, v148
	v_fmac_f32_e32 v35, v39, v149
	v_fmac_f32_e32 v35, v40, v150
	v_fmac_f32_e32 v35, v41, v151
	ds_read_b128 v[38:41], v43 offset:10256
	s_waitcnt lgkmcnt(3)
	v_fmac_f32_e32 v36, v2, v148
	v_fmac_f32_e32 v36, v3, v149
	v_fmac_f32_e32 v36, v4, v150
	v_fmac_f32_e32 v36, v5, v151
	ds_read_b128 v[2:5], v43 offset:14352
	s_waitcnt vmcnt(56)
	s_waitcnt lgkmcnt(3)
	v_fmac_f32_e32 v20, v6, v152
	v_fmac_f32_e32 v20, v7, v153
	v_fmac_f32_e32 v20, v8, v154
	v_fmac_f32_e32 v20, v9, v155
	ds_read_b128 v[6:9], v43 offset:18448
	s_waitcnt lgkmcnt(3)
	v_fmac_f32_e32 v21, v10, v152
	v_fmac_f32_e32 v21, v11, v153
	v_fmac_f32_e32 v21, v12, v154
	v_fmac_f32_e32 v21, v13, v155
	ds_read_b128 v[10:13], v43 offset:22544
	s_waitcnt lgkmcnt(3)
	v_fmac_f32_e32 v22, v38, v152
	v_fmac_f32_e32 v22, v39, v153
	v_fmac_f32_e32 v22, v40, v154
	v_fmac_f32_e32 v22, v41, v155
	ds_read_b128 v[38:41], v43 offset:26640
	s_waitcnt lgkmcnt(3)
	v_fmac_f32_e32 v23, v2, v152
	v_fmac_f32_e32 v23, v3, v153
	v_fmac_f32_e32 v23, v4, v154
	v_fmac_f32_e32 v23, v5, v155
	ds_read_b128 v[2:5], v43 offset:30736
	s_waitcnt lgkmcnt(3)
	v_fmac_f32_e32 v24, v6, v152
	v_fmac_f32_e32 v24, v7, v153
	v_fmac_f32_e32 v24, v8, v154
	v_fmac_f32_e32 v24, v9, v155
	ds_read_b128 v[6:9], v43 offset:34832
	s_waitcnt lgkmcnt(3)
	v_fmac_f32_e32 v25, v10, v152
	v_fmac_f32_e32 v25, v11, v153
	v_fmac_f32_e32 v25, v12, v154
	v_fmac_f32_e32 v25, v13, v155
	ds_read_b128 v[10:13], v43 offset:38928
	s_waitcnt lgkmcnt(3)
	v_fmac_f32_e32 v26, v38, v152
	v_fmac_f32_e32 v26, v39, v153
	v_fmac_f32_e32 v26, v40, v154
	v_fmac_f32_e32 v26, v41, v155
	ds_read_b128 v[38:41], v43 offset:43024
	s_waitcnt lgkmcnt(3)
	v_fmac_f32_e32 v27, v2, v152
	v_fmac_f32_e32 v27, v3, v153
	v_fmac_f32_e32 v27, v4, v154
	v_fmac_f32_e32 v27, v5, v155
	ds_read_b128 v[2:5], v43 offset:47120
	s_waitcnt lgkmcnt(3)
	v_fmac_f32_e32 v28, v6, v152
	v_fmac_f32_e32 v28, v7, v153
	v_fmac_f32_e32 v28, v8, v154
	v_fmac_f32_e32 v28, v9, v155
	ds_read_b128 v[6:9], v43 offset:51216
	s_waitcnt lgkmcnt(3)
	v_fmac_f32_e32 v29, v10, v152
	v_fmac_f32_e32 v29, v11, v153
	v_fmac_f32_e32 v29, v12, v154
	v_fmac_f32_e32 v29, v13, v155
	ds_read_b128 v[10:13], v43 offset:55312
	s_waitcnt lgkmcnt(3)
	v_fmac_f32_e32 v30, v38, v152
	v_fmac_f32_e32 v30, v39, v153
	v_fmac_f32_e32 v30, v40, v154
	v_fmac_f32_e32 v30, v41, v155
	ds_read_b128 v[38:41], v43 offset:59408
	s_waitcnt lgkmcnt(3)
	v_fmac_f32_e32 v31, v2, v152
	v_fmac_f32_e32 v31, v3, v153
	v_fmac_f32_e32 v31, v4, v154
	v_fmac_f32_e32 v31, v5, v155
	ds_read_b128 v[2:5], v43 offset:63504
	s_waitcnt lgkmcnt(3)
	v_fmac_f32_e32 v32, v6, v152
	v_fmac_f32_e32 v32, v7, v153
	v_fmac_f32_e32 v32, v8, v154
	v_fmac_f32_e32 v32, v9, v155
	ds_read_b128 v[6:9], v37 offset:2064
	s_waitcnt lgkmcnt(3)
	v_fmac_f32_e32 v33, v10, v152
	v_fmac_f32_e32 v33, v11, v153
	v_fmac_f32_e32 v33, v12, v154
	v_fmac_f32_e32 v33, v13, v155
	ds_read_b128 v[10:13], v43 offset:2080
	s_waitcnt lgkmcnt(3)
	v_fmac_f32_e32 v34, v38, v152
	v_fmac_f32_e32 v34, v39, v153
	v_fmac_f32_e32 v34, v40, v154
	v_fmac_f32_e32 v34, v41, v155
	ds_read_b128 v[38:41], v43 offset:6176
	s_waitcnt lgkmcnt(3)
	v_fmac_f32_e32 v35, v2, v152
	v_fmac_f32_e32 v35, v3, v153
	v_fmac_f32_e32 v35, v4, v154
	v_fmac_f32_e32 v35, v5, v155
	ds_read_b128 v[2:5], v43 offset:10272
	s_waitcnt lgkmcnt(3)
	v_fmac_f32_e32 v36, v6, v152
	v_fmac_f32_e32 v36, v7, v153
	v_fmac_f32_e32 v36, v8, v154
	v_fmac_f32_e32 v36, v9, v155
	ds_read_b128 v[6:9], v43 offset:14368
	s_waitcnt vmcnt(52)
	s_waitcnt lgkmcnt(3)
	v_fmac_f32_e32 v20, v10, v156
	v_fmac_f32_e32 v20, v11, v157
	v_fmac_f32_e32 v20, v12, v158
	v_fmac_f32_e32 v20, v13, v159
	ds_read_b128 v[10:13], v43 offset:18464
	s_waitcnt lgkmcnt(3)
	v_fmac_f32_e32 v21, v38, v156
	v_fmac_f32_e32 v21, v39, v157
	v_fmac_f32_e32 v21, v40, v158
	v_fmac_f32_e32 v21, v41, v159
	ds_read_b128 v[38:41], v43 offset:22560
	s_waitcnt lgkmcnt(3)
	v_fmac_f32_e32 v22, v2, v156
	v_fmac_f32_e32 v22, v3, v157
	v_fmac_f32_e32 v22, v4, v158
	v_fmac_f32_e32 v22, v5, v159
	ds_read_b128 v[2:5], v43 offset:26656
	s_waitcnt lgkmcnt(3)
	v_fmac_f32_e32 v23, v6, v156
	v_fmac_f32_e32 v23, v7, v157
	v_fmac_f32_e32 v23, v8, v158
	v_fmac_f32_e32 v23, v9, v159
	ds_read_b128 v[6:9], v43 offset:30752
	s_waitcnt lgkmcnt(3)
	v_fmac_f32_e32 v24, v10, v156
	v_fmac_f32_e32 v24, v11, v157
	v_fmac_f32_e32 v24, v12, v158
	v_fmac_f32_e32 v24, v13, v159
	ds_read_b128 v[10:13], v43 offset:34848
	s_waitcnt lgkmcnt(3)
	v_fmac_f32_e32 v25, v38, v156
	v_fmac_f32_e32 v25, v39, v157
	v_fmac_f32_e32 v25, v40, v158
	v_fmac_f32_e32 v25, v41, v159
	ds_read_b128 v[38:41], v43 offset:38944
	s_waitcnt lgkmcnt(3)
	v_fmac_f32_e32 v26, v2, v156
	v_fmac_f32_e32 v26, v3, v157
	v_fmac_f32_e32 v26, v4, v158
	v_fmac_f32_e32 v26, v5, v159
	ds_read_b128 v[2:5], v43 offset:43040
	s_waitcnt lgkmcnt(3)
	v_fmac_f32_e32 v27, v6, v156
	v_fmac_f32_e32 v27, v7, v157
	v_fmac_f32_e32 v27, v8, v158
	v_fmac_f32_e32 v27, v9, v159
	ds_read_b128 v[6:9], v43 offset:47136
	s_waitcnt lgkmcnt(3)
	v_fmac_f32_e32 v28, v10, v156
	v_fmac_f32_e32 v28, v11, v157
	v_fmac_f32_e32 v28, v12, v158
	v_fmac_f32_e32 v28, v13, v159
	ds_read_b128 v[10:13], v43 offset:51232
	s_waitcnt lgkmcnt(3)
	v_fmac_f32_e32 v29, v38, v156
	v_fmac_f32_e32 v29, v39, v157
	v_fmac_f32_e32 v29, v40, v158
	v_fmac_f32_e32 v29, v41, v159
	ds_read_b128 v[38:41], v43 offset:55328
	s_waitcnt lgkmcnt(3)
	v_fmac_f32_e32 v30, v2, v156
	v_fmac_f32_e32 v30, v3, v157
	v_fmac_f32_e32 v30, v4, v158
	v_fmac_f32_e32 v30, v5, v159
	ds_read_b128 v[2:5], v43 offset:59424
	s_waitcnt lgkmcnt(3)
	v_fmac_f32_e32 v31, v6, v156
	v_fmac_f32_e32 v31, v7, v157
	v_fmac_f32_e32 v31, v8, v158
	v_fmac_f32_e32 v31, v9, v159
	ds_read_b128 v[6:9], v43 offset:63520
	s_waitcnt lgkmcnt(3)
	v_fmac_f32_e32 v32, v10, v156
	v_fmac_f32_e32 v32, v11, v157
	v_fmac_f32_e32 v32, v12, v158
	v_fmac_f32_e32 v32, v13, v159
	ds_read_b128 v[10:13], v37 offset:2080
	s_waitcnt lgkmcnt(3)
	v_fmac_f32_e32 v33, v38, v156
	v_fmac_f32_e32 v33, v39, v157
	v_fmac_f32_e32 v33, v40, v158
	v_fmac_f32_e32 v33, v41, v159
	ds_read_b128 v[38:41], v43 offset:2096
	s_waitcnt lgkmcnt(3)
	v_fmac_f32_e32 v34, v2, v156
	v_fmac_f32_e32 v34, v3, v157
	v_fmac_f32_e32 v34, v4, v158
	v_fmac_f32_e32 v34, v5, v159
	ds_read_b128 v[2:5], v43 offset:6192
	s_waitcnt lgkmcnt(3)
	v_fmac_f32_e32 v35, v6, v156
	v_fmac_f32_e32 v35, v7, v157
	v_fmac_f32_e32 v35, v8, v158
	v_fmac_f32_e32 v35, v9, v159
	ds_read_b128 v[6:9], v43 offset:10288
	s_waitcnt lgkmcnt(3)
	v_fmac_f32_e32 v36, v10, v156
	v_fmac_f32_e32 v36, v11, v157
	v_fmac_f32_e32 v36, v12, v158
	v_fmac_f32_e32 v36, v13, v159
	ds_read_b128 v[10:13], v43 offset:14384
	s_waitcnt vmcnt(48)
	s_waitcnt lgkmcnt(3)
	v_fmac_f32_e32 v20, v38, v160
	v_fmac_f32_e32 v20, v39, v161
	v_fmac_f32_e32 v20, v40, v162
	v_fmac_f32_e32 v20, v41, v163
	ds_read_b128 v[38:41], v43 offset:18480
	s_waitcnt lgkmcnt(3)
	v_fmac_f32_e32 v21, v2, v160
	v_fmac_f32_e32 v21, v3, v161
	v_fmac_f32_e32 v21, v4, v162
	v_fmac_f32_e32 v21, v5, v163
	ds_read_b128 v[2:5], v43 offset:22576
	s_waitcnt lgkmcnt(3)
	v_fmac_f32_e32 v22, v6, v160
	v_fmac_f32_e32 v22, v7, v161
	v_fmac_f32_e32 v22, v8, v162
	v_fmac_f32_e32 v22, v9, v163
	ds_read_b128 v[6:9], v43 offset:26672
	s_waitcnt lgkmcnt(3)
	v_fmac_f32_e32 v23, v10, v160
	v_fmac_f32_e32 v23, v11, v161
	v_fmac_f32_e32 v23, v12, v162
	v_fmac_f32_e32 v23, v13, v163
	ds_read_b128 v[10:13], v43 offset:30768
	s_waitcnt lgkmcnt(3)
	v_fmac_f32_e32 v24, v38, v160
	v_fmac_f32_e32 v24, v39, v161
	v_fmac_f32_e32 v24, v40, v162
	v_fmac_f32_e32 v24, v41, v163
	ds_read_b128 v[38:41], v43 offset:34864
	s_waitcnt lgkmcnt(3)
	v_fmac_f32_e32 v25, v2, v160
	v_fmac_f32_e32 v25, v3, v161
	v_fmac_f32_e32 v25, v4, v162
	v_fmac_f32_e32 v25, v5, v163
	ds_read_b128 v[2:5], v43 offset:38960
	s_waitcnt lgkmcnt(3)
	v_fmac_f32_e32 v26, v6, v160
	v_fmac_f32_e32 v26, v7, v161
	v_fmac_f32_e32 v26, v8, v162
	v_fmac_f32_e32 v26, v9, v163
	ds_read_b128 v[6:9], v43 offset:43056
	s_waitcnt lgkmcnt(3)
	v_fmac_f32_e32 v27, v10, v160
	v_fmac_f32_e32 v27, v11, v161
	v_fmac_f32_e32 v27, v12, v162
	v_fmac_f32_e32 v27, v13, v163
	ds_read_b128 v[10:13], v43 offset:47152
	s_waitcnt lgkmcnt(3)
	v_fmac_f32_e32 v28, v38, v160
	v_fmac_f32_e32 v28, v39, v161
	v_fmac_f32_e32 v28, v40, v162
	v_fmac_f32_e32 v28, v41, v163
	ds_read_b128 v[38:41], v43 offset:51248
	s_waitcnt lgkmcnt(3)
	v_fmac_f32_e32 v29, v2, v160
	v_fmac_f32_e32 v29, v3, v161
	v_fmac_f32_e32 v29, v4, v162
	v_fmac_f32_e32 v29, v5, v163
	ds_read_b128 v[2:5], v43 offset:55344
	s_waitcnt lgkmcnt(3)
	v_fmac_f32_e32 v30, v6, v160
	v_fmac_f32_e32 v30, v7, v161
	v_fmac_f32_e32 v30, v8, v162
	v_fmac_f32_e32 v30, v9, v163
	ds_read_b128 v[6:9], v43 offset:59440
	s_waitcnt lgkmcnt(3)
	v_fmac_f32_e32 v31, v10, v160
	v_fmac_f32_e32 v31, v11, v161
	v_fmac_f32_e32 v31, v12, v162
	v_fmac_f32_e32 v31, v13, v163
	ds_read_b128 v[10:13], v43 offset:63536
	s_waitcnt lgkmcnt(3)
	v_fmac_f32_e32 v32, v38, v160
	v_fmac_f32_e32 v32, v39, v161
	v_fmac_f32_e32 v32, v40, v162
	v_fmac_f32_e32 v32, v41, v163
	ds_read_b128 v[38:41], v37 offset:2096
	s_waitcnt lgkmcnt(3)
	v_fmac_f32_e32 v33, v2, v160
	v_fmac_f32_e32 v33, v3, v161
	v_fmac_f32_e32 v33, v4, v162
	v_fmac_f32_e32 v33, v5, v163
	ds_read_b128 v[2:5], v43 offset:2112
	s_waitcnt lgkmcnt(3)
	v_fmac_f32_e32 v34, v6, v160
	v_fmac_f32_e32 v34, v7, v161
	v_fmac_f32_e32 v34, v8, v162
	v_fmac_f32_e32 v34, v9, v163
	ds_read_b128 v[6:9], v43 offset:6208
	s_waitcnt lgkmcnt(3)
	v_fmac_f32_e32 v35, v10, v160
	v_fmac_f32_e32 v35, v11, v161
	v_fmac_f32_e32 v35, v12, v162
	v_fmac_f32_e32 v35, v13, v163
	ds_read_b128 v[10:13], v43 offset:10304
	s_waitcnt lgkmcnt(3)
	v_fmac_f32_e32 v36, v38, v160
	v_fmac_f32_e32 v36, v39, v161
	v_fmac_f32_e32 v36, v40, v162
	v_fmac_f32_e32 v36, v41, v163
	ds_read_b128 v[38:41], v43 offset:14400
	s_waitcnt vmcnt(44)
	s_waitcnt lgkmcnt(3)
	v_fmac_f32_e32 v20, v2, v164
	v_fmac_f32_e32 v20, v3, v165
	v_fmac_f32_e32 v20, v4, v166
	v_fmac_f32_e32 v20, v5, v167
	ds_read_b128 v[2:5], v43 offset:18496
	s_waitcnt lgkmcnt(3)
	v_fmac_f32_e32 v21, v6, v164
	v_fmac_f32_e32 v21, v7, v165
	v_fmac_f32_e32 v21, v8, v166
	v_fmac_f32_e32 v21, v9, v167
	ds_read_b128 v[6:9], v43 offset:22592
	s_waitcnt lgkmcnt(3)
	v_fmac_f32_e32 v22, v10, v164
	v_fmac_f32_e32 v22, v11, v165
	v_fmac_f32_e32 v22, v12, v166
	v_fmac_f32_e32 v22, v13, v167
	ds_read_b128 v[10:13], v43 offset:26688
	s_waitcnt lgkmcnt(3)
	v_fmac_f32_e32 v23, v38, v164
	v_fmac_f32_e32 v23, v39, v165
	v_fmac_f32_e32 v23, v40, v166
	v_fmac_f32_e32 v23, v41, v167
	ds_read_b128 v[38:41], v43 offset:30784
	s_waitcnt lgkmcnt(3)
	v_fmac_f32_e32 v24, v2, v164
	v_fmac_f32_e32 v24, v3, v165
	v_fmac_f32_e32 v24, v4, v166
	v_fmac_f32_e32 v24, v5, v167
	ds_read_b128 v[2:5], v43 offset:34880
	s_waitcnt lgkmcnt(3)
	v_fmac_f32_e32 v25, v6, v164
	v_fmac_f32_e32 v25, v7, v165
	v_fmac_f32_e32 v25, v8, v166
	v_fmac_f32_e32 v25, v9, v167
	ds_read_b128 v[6:9], v43 offset:38976
	s_waitcnt lgkmcnt(3)
	v_fmac_f32_e32 v26, v10, v164
	v_fmac_f32_e32 v26, v11, v165
	v_fmac_f32_e32 v26, v12, v166
	v_fmac_f32_e32 v26, v13, v167
	ds_read_b128 v[10:13], v43 offset:43072
	s_waitcnt lgkmcnt(3)
	v_fmac_f32_e32 v27, v38, v164
	v_fmac_f32_e32 v27, v39, v165
	v_fmac_f32_e32 v27, v40, v166
	v_fmac_f32_e32 v27, v41, v167
	ds_read_b128 v[38:41], v43 offset:47168
	s_waitcnt lgkmcnt(3)
	v_fmac_f32_e32 v28, v2, v164
	v_fmac_f32_e32 v28, v3, v165
	v_fmac_f32_e32 v28, v4, v166
	v_fmac_f32_e32 v28, v5, v167
	ds_read_b128 v[2:5], v43 offset:51264
	s_waitcnt lgkmcnt(3)
	v_fmac_f32_e32 v29, v6, v164
	v_fmac_f32_e32 v29, v7, v165
	v_fmac_f32_e32 v29, v8, v166
	v_fmac_f32_e32 v29, v9, v167
	ds_read_b128 v[6:9], v43 offset:55360
	s_waitcnt lgkmcnt(3)
	v_fmac_f32_e32 v30, v10, v164
	v_fmac_f32_e32 v30, v11, v165
	v_fmac_f32_e32 v30, v12, v166
	v_fmac_f32_e32 v30, v13, v167
	ds_read_b128 v[10:13], v43 offset:59456
	s_waitcnt lgkmcnt(3)
	v_fmac_f32_e32 v31, v38, v164
	v_fmac_f32_e32 v31, v39, v165
	v_fmac_f32_e32 v31, v40, v166
	v_fmac_f32_e32 v31, v41, v167
	ds_read_b128 v[38:41], v43 offset:63552
	s_waitcnt lgkmcnt(3)
	v_fmac_f32_e32 v32, v2, v164
	v_fmac_f32_e32 v32, v3, v165
	v_fmac_f32_e32 v32, v4, v166
	v_fmac_f32_e32 v32, v5, v167
	ds_read_b128 v[2:5], v37 offset:2112
	s_waitcnt lgkmcnt(3)
	v_fmac_f32_e32 v33, v6, v164
	v_fmac_f32_e32 v33, v7, v165
	v_fmac_f32_e32 v33, v8, v166
	v_fmac_f32_e32 v33, v9, v167
	ds_read_b128 v[6:9], v43 offset:2128
	s_waitcnt lgkmcnt(3)
	v_fmac_f32_e32 v34, v10, v164
	v_fmac_f32_e32 v34, v11, v165
	v_fmac_f32_e32 v34, v12, v166
	v_fmac_f32_e32 v34, v13, v167
	ds_read_b128 v[10:13], v43 offset:6224
	s_waitcnt lgkmcnt(3)
	v_fmac_f32_e32 v35, v38, v164
	v_fmac_f32_e32 v35, v39, v165
	v_fmac_f32_e32 v35, v40, v166
	v_fmac_f32_e32 v35, v41, v167
	ds_read_b128 v[38:41], v43 offset:10320
	s_waitcnt lgkmcnt(3)
	v_fmac_f32_e32 v36, v2, v164
	v_fmac_f32_e32 v36, v3, v165
	v_fmac_f32_e32 v36, v4, v166
	v_fmac_f32_e32 v36, v5, v167
	ds_read_b128 v[2:5], v43 offset:14416
	s_waitcnt vmcnt(40)
	s_waitcnt lgkmcnt(3)
	v_fmac_f32_e32 v20, v6, v168
	v_fmac_f32_e32 v20, v7, v169
	v_fmac_f32_e32 v20, v8, v170
	v_fmac_f32_e32 v20, v9, v171
	ds_read_b128 v[6:9], v43 offset:18512
	s_waitcnt lgkmcnt(3)
	v_fmac_f32_e32 v21, v10, v168
	v_fmac_f32_e32 v21, v11, v169
	v_fmac_f32_e32 v21, v12, v170
	v_fmac_f32_e32 v21, v13, v171
	ds_read_b128 v[10:13], v43 offset:22608
	s_waitcnt lgkmcnt(3)
	v_fmac_f32_e32 v22, v38, v168
	v_fmac_f32_e32 v22, v39, v169
	v_fmac_f32_e32 v22, v40, v170
	v_fmac_f32_e32 v22, v41, v171
	ds_read_b128 v[38:41], v43 offset:26704
	s_waitcnt lgkmcnt(3)
	v_fmac_f32_e32 v23, v2, v168
	v_fmac_f32_e32 v23, v3, v169
	v_fmac_f32_e32 v23, v4, v170
	v_fmac_f32_e32 v23, v5, v171
	ds_read_b128 v[2:5], v43 offset:30800
	s_waitcnt lgkmcnt(3)
	v_fmac_f32_e32 v24, v6, v168
	v_fmac_f32_e32 v24, v7, v169
	v_fmac_f32_e32 v24, v8, v170
	v_fmac_f32_e32 v24, v9, v171
	ds_read_b128 v[6:9], v43 offset:34896
	s_waitcnt lgkmcnt(3)
	v_fmac_f32_e32 v25, v10, v168
	v_fmac_f32_e32 v25, v11, v169
	v_fmac_f32_e32 v25, v12, v170
	v_fmac_f32_e32 v25, v13, v171
	ds_read_b128 v[10:13], v43 offset:38992
	s_waitcnt lgkmcnt(3)
	v_fmac_f32_e32 v26, v38, v168
	v_fmac_f32_e32 v26, v39, v169
	v_fmac_f32_e32 v26, v40, v170
	v_fmac_f32_e32 v26, v41, v171
	ds_read_b128 v[38:41], v43 offset:43088
	s_waitcnt lgkmcnt(3)
	v_fmac_f32_e32 v27, v2, v168
	v_fmac_f32_e32 v27, v3, v169
	v_fmac_f32_e32 v27, v4, v170
	v_fmac_f32_e32 v27, v5, v171
	ds_read_b128 v[2:5], v43 offset:47184
	s_waitcnt lgkmcnt(3)
	v_fmac_f32_e32 v28, v6, v168
	v_fmac_f32_e32 v28, v7, v169
	v_fmac_f32_e32 v28, v8, v170
	v_fmac_f32_e32 v28, v9, v171
	ds_read_b128 v[6:9], v43 offset:51280
	s_waitcnt lgkmcnt(3)
	v_fmac_f32_e32 v29, v10, v168
	v_fmac_f32_e32 v29, v11, v169
	v_fmac_f32_e32 v29, v12, v170
	v_fmac_f32_e32 v29, v13, v171
	ds_read_b128 v[10:13], v43 offset:55376
	s_waitcnt lgkmcnt(3)
	v_fmac_f32_e32 v30, v38, v168
	v_fmac_f32_e32 v30, v39, v169
	v_fmac_f32_e32 v30, v40, v170
	v_fmac_f32_e32 v30, v41, v171
	ds_read_b128 v[38:41], v43 offset:59472
	s_waitcnt lgkmcnt(3)
	v_fmac_f32_e32 v31, v2, v168
	v_fmac_f32_e32 v31, v3, v169
	v_fmac_f32_e32 v31, v4, v170
	v_fmac_f32_e32 v31, v5, v171
	ds_read_b128 v[2:5], v43 offset:63568
	s_waitcnt lgkmcnt(3)
	v_fmac_f32_e32 v32, v6, v168
	v_fmac_f32_e32 v32, v7, v169
	v_fmac_f32_e32 v32, v8, v170
	v_fmac_f32_e32 v32, v9, v171
	ds_read_b128 v[6:9], v37 offset:2128
	s_waitcnt lgkmcnt(3)
	v_fmac_f32_e32 v33, v10, v168
	v_fmac_f32_e32 v33, v11, v169
	v_fmac_f32_e32 v33, v12, v170
	v_fmac_f32_e32 v33, v13, v171
	ds_read_b128 v[10:13], v43 offset:2144
	s_waitcnt lgkmcnt(3)
	v_fmac_f32_e32 v34, v38, v168
	v_fmac_f32_e32 v34, v39, v169
	v_fmac_f32_e32 v34, v40, v170
	v_fmac_f32_e32 v34, v41, v171
	ds_read_b128 v[38:41], v43 offset:6240
	s_waitcnt lgkmcnt(3)
	v_fmac_f32_e32 v35, v2, v168
	v_fmac_f32_e32 v35, v3, v169
	v_fmac_f32_e32 v35, v4, v170
	v_fmac_f32_e32 v35, v5, v171
	ds_read_b128 v[2:5], v43 offset:10336
	s_waitcnt lgkmcnt(3)
	v_fmac_f32_e32 v36, v6, v168
	v_fmac_f32_e32 v36, v7, v169
	v_fmac_f32_e32 v36, v8, v170
	v_fmac_f32_e32 v36, v9, v171
	ds_read_b128 v[6:9], v43 offset:14432
	s_waitcnt vmcnt(36)
	s_waitcnt lgkmcnt(3)
	v_fmac_f32_e32 v20, v10, v172
	v_fmac_f32_e32 v20, v11, v173
	v_fmac_f32_e32 v20, v12, v174
	v_fmac_f32_e32 v20, v13, v175
	ds_read_b128 v[10:13], v43 offset:18528
	s_waitcnt lgkmcnt(3)
	v_fmac_f32_e32 v21, v38, v172
	v_fmac_f32_e32 v21, v39, v173
	v_fmac_f32_e32 v21, v40, v174
	v_fmac_f32_e32 v21, v41, v175
	ds_read_b128 v[38:41], v43 offset:22624
	s_waitcnt lgkmcnt(3)
	v_fmac_f32_e32 v22, v2, v172
	v_fmac_f32_e32 v22, v3, v173
	v_fmac_f32_e32 v22, v4, v174
	v_fmac_f32_e32 v22, v5, v175
	ds_read_b128 v[2:5], v43 offset:26720
	s_waitcnt lgkmcnt(3)
	v_fmac_f32_e32 v23, v6, v172
	v_fmac_f32_e32 v23, v7, v173
	v_fmac_f32_e32 v23, v8, v174
	v_fmac_f32_e32 v23, v9, v175
	ds_read_b128 v[6:9], v43 offset:30816
	s_waitcnt lgkmcnt(3)
	v_fmac_f32_e32 v24, v10, v172
	v_fmac_f32_e32 v24, v11, v173
	v_fmac_f32_e32 v24, v12, v174
	v_fmac_f32_e32 v24, v13, v175
	ds_read_b128 v[10:13], v43 offset:34912
	s_waitcnt lgkmcnt(3)
	v_fmac_f32_e32 v25, v38, v172
	v_fmac_f32_e32 v25, v39, v173
	v_fmac_f32_e32 v25, v40, v174
	v_fmac_f32_e32 v25, v41, v175
	ds_read_b128 v[38:41], v43 offset:39008
	s_waitcnt lgkmcnt(3)
	v_fmac_f32_e32 v26, v2, v172
	v_fmac_f32_e32 v26, v3, v173
	v_fmac_f32_e32 v26, v4, v174
	v_fmac_f32_e32 v26, v5, v175
	ds_read_b128 v[2:5], v43 offset:43104
	s_waitcnt lgkmcnt(3)
	v_fmac_f32_e32 v27, v6, v172
	v_fmac_f32_e32 v27, v7, v173
	v_fmac_f32_e32 v27, v8, v174
	v_fmac_f32_e32 v27, v9, v175
	ds_read_b128 v[6:9], v43 offset:47200
	s_waitcnt lgkmcnt(3)
	v_fmac_f32_e32 v28, v10, v172
	v_fmac_f32_e32 v28, v11, v173
	v_fmac_f32_e32 v28, v12, v174
	v_fmac_f32_e32 v28, v13, v175
	ds_read_b128 v[10:13], v43 offset:51296
	s_waitcnt lgkmcnt(3)
	v_fmac_f32_e32 v29, v38, v172
	v_fmac_f32_e32 v29, v39, v173
	v_fmac_f32_e32 v29, v40, v174
	v_fmac_f32_e32 v29, v41, v175
	ds_read_b128 v[38:41], v43 offset:55392
	s_waitcnt lgkmcnt(3)
	v_fmac_f32_e32 v30, v2, v172
	v_fmac_f32_e32 v30, v3, v173
	v_fmac_f32_e32 v30, v4, v174
	v_fmac_f32_e32 v30, v5, v175
	ds_read_b128 v[2:5], v43 offset:59488
	s_waitcnt lgkmcnt(3)
	v_fmac_f32_e32 v31, v6, v172
	v_fmac_f32_e32 v31, v7, v173
	v_fmac_f32_e32 v31, v8, v174
	v_fmac_f32_e32 v31, v9, v175
	ds_read_b128 v[6:9], v43 offset:63584
	s_waitcnt lgkmcnt(3)
	v_fmac_f32_e32 v32, v10, v172
	v_fmac_f32_e32 v32, v11, v173
	v_fmac_f32_e32 v32, v12, v174
	v_fmac_f32_e32 v32, v13, v175
	ds_read_b128 v[10:13], v37 offset:2144
	s_waitcnt lgkmcnt(3)
	v_fmac_f32_e32 v33, v38, v172
	v_fmac_f32_e32 v33, v39, v173
	v_fmac_f32_e32 v33, v40, v174
	v_fmac_f32_e32 v33, v41, v175
	ds_read_b128 v[38:41], v43 offset:2160
	s_waitcnt lgkmcnt(3)
	v_fmac_f32_e32 v34, v2, v172
	v_fmac_f32_e32 v34, v3, v173
	v_fmac_f32_e32 v34, v4, v174
	v_fmac_f32_e32 v34, v5, v175
	ds_read_b128 v[2:5], v43 offset:6256
	s_waitcnt lgkmcnt(3)
	v_fmac_f32_e32 v35, v6, v172
	v_fmac_f32_e32 v35, v7, v173
	v_fmac_f32_e32 v35, v8, v174
	v_fmac_f32_e32 v35, v9, v175
	ds_read_b128 v[6:9], v43 offset:10352
	s_waitcnt lgkmcnt(3)
	v_fmac_f32_e32 v36, v10, v172
	v_fmac_f32_e32 v36, v11, v173
	v_fmac_f32_e32 v36, v12, v174
	v_fmac_f32_e32 v36, v13, v175
	ds_read_b128 v[10:13], v43 offset:14448
	s_waitcnt vmcnt(32)
	s_waitcnt lgkmcnt(3)
	v_fmac_f32_e32 v20, v38, v176
	v_fmac_f32_e32 v20, v39, v177
	v_fmac_f32_e32 v20, v40, v178
	v_fmac_f32_e32 v20, v41, v179
	ds_read_b128 v[38:41], v43 offset:18544
	s_waitcnt lgkmcnt(3)
	v_fmac_f32_e32 v21, v2, v176
	v_fmac_f32_e32 v21, v3, v177
	v_fmac_f32_e32 v21, v4, v178
	v_fmac_f32_e32 v21, v5, v179
	ds_read_b128 v[2:5], v43 offset:22640
	s_waitcnt lgkmcnt(3)
	v_fmac_f32_e32 v22, v6, v176
	v_fmac_f32_e32 v22, v7, v177
	v_fmac_f32_e32 v22, v8, v178
	v_fmac_f32_e32 v22, v9, v179
	ds_read_b128 v[6:9], v43 offset:26736
	s_waitcnt lgkmcnt(3)
	v_fmac_f32_e32 v23, v10, v176
	v_fmac_f32_e32 v23, v11, v177
	v_fmac_f32_e32 v23, v12, v178
	v_fmac_f32_e32 v23, v13, v179
	ds_read_b128 v[10:13], v43 offset:30832
	s_waitcnt lgkmcnt(3)
	v_fmac_f32_e32 v24, v38, v176
	v_fmac_f32_e32 v24, v39, v177
	v_fmac_f32_e32 v24, v40, v178
	v_fmac_f32_e32 v24, v41, v179
	ds_read_b128 v[38:41], v43 offset:34928
	s_waitcnt lgkmcnt(3)
	v_fmac_f32_e32 v25, v2, v176
	v_fmac_f32_e32 v25, v3, v177
	v_fmac_f32_e32 v25, v4, v178
	v_fmac_f32_e32 v25, v5, v179
	ds_read_b128 v[2:5], v43 offset:39024
	s_waitcnt lgkmcnt(3)
	v_fmac_f32_e32 v26, v6, v176
	v_fmac_f32_e32 v26, v7, v177
	v_fmac_f32_e32 v26, v8, v178
	v_fmac_f32_e32 v26, v9, v179
	ds_read_b128 v[6:9], v43 offset:43120
	s_waitcnt lgkmcnt(3)
	v_fmac_f32_e32 v27, v10, v176
	v_fmac_f32_e32 v27, v11, v177
	v_fmac_f32_e32 v27, v12, v178
	v_fmac_f32_e32 v27, v13, v179
	ds_read_b128 v[10:13], v43 offset:47216
	s_waitcnt lgkmcnt(3)
	v_fmac_f32_e32 v28, v38, v176
	v_fmac_f32_e32 v28, v39, v177
	v_fmac_f32_e32 v28, v40, v178
	v_fmac_f32_e32 v28, v41, v179
	ds_read_b128 v[38:41], v43 offset:51312
	s_waitcnt lgkmcnt(3)
	v_fmac_f32_e32 v29, v2, v176
	v_fmac_f32_e32 v29, v3, v177
	v_fmac_f32_e32 v29, v4, v178
	v_fmac_f32_e32 v29, v5, v179
	ds_read_b128 v[2:5], v43 offset:55408
	s_waitcnt lgkmcnt(3)
	v_fmac_f32_e32 v30, v6, v176
	v_fmac_f32_e32 v30, v7, v177
	v_fmac_f32_e32 v30, v8, v178
	v_fmac_f32_e32 v30, v9, v179
	ds_read_b128 v[6:9], v43 offset:59504
	s_waitcnt lgkmcnt(3)
	v_fmac_f32_e32 v31, v10, v176
	v_fmac_f32_e32 v31, v11, v177
	v_fmac_f32_e32 v31, v12, v178
	v_fmac_f32_e32 v31, v13, v179
	ds_read_b128 v[10:13], v43 offset:63600
	s_waitcnt lgkmcnt(3)
	v_fmac_f32_e32 v32, v38, v176
	v_fmac_f32_e32 v32, v39, v177
	v_fmac_f32_e32 v32, v40, v178
	v_fmac_f32_e32 v32, v41, v179
	ds_read_b128 v[38:41], v37 offset:2160
	s_waitcnt lgkmcnt(3)
	v_fmac_f32_e32 v33, v2, v176
	v_fmac_f32_e32 v33, v3, v177
	v_fmac_f32_e32 v33, v4, v178
	v_fmac_f32_e32 v33, v5, v179
	ds_read_b128 v[2:5], v43 offset:3072
	s_waitcnt lgkmcnt(3)
	v_fmac_f32_e32 v34, v6, v176
	v_fmac_f32_e32 v34, v7, v177
	v_fmac_f32_e32 v34, v8, v178
	v_fmac_f32_e32 v34, v9, v179
	ds_read_b128 v[6:9], v43 offset:7168
	s_waitcnt lgkmcnt(3)
	v_fmac_f32_e32 v35, v10, v176
	v_fmac_f32_e32 v35, v11, v177
	v_fmac_f32_e32 v35, v12, v178
	v_fmac_f32_e32 v35, v13, v179
	ds_read_b128 v[10:13], v43 offset:11264
	s_waitcnt lgkmcnt(3)
	v_fmac_f32_e32 v36, v38, v176
	v_fmac_f32_e32 v36, v39, v177
	v_fmac_f32_e32 v36, v40, v178
	v_fmac_f32_e32 v36, v41, v179
	ds_read_b128 v[38:41], v43 offset:15360
	s_waitcnt vmcnt(28)
	s_waitcnt lgkmcnt(3)
	v_fmac_f32_e32 v20, v2, v180
	v_fmac_f32_e32 v20, v3, v181
	v_fmac_f32_e32 v20, v4, v182
	v_fmac_f32_e32 v20, v5, v183
	ds_read_b128 v[2:5], v43 offset:19456
	s_waitcnt lgkmcnt(3)
	v_fmac_f32_e32 v21, v6, v180
	v_fmac_f32_e32 v21, v7, v181
	v_fmac_f32_e32 v21, v8, v182
	v_fmac_f32_e32 v21, v9, v183
	ds_read_b128 v[6:9], v43 offset:23552
	s_waitcnt lgkmcnt(3)
	v_fmac_f32_e32 v22, v10, v180
	v_fmac_f32_e32 v22, v11, v181
	v_fmac_f32_e32 v22, v12, v182
	v_fmac_f32_e32 v22, v13, v183
	ds_read_b128 v[10:13], v43 offset:27648
	s_waitcnt lgkmcnt(3)
	v_fmac_f32_e32 v23, v38, v180
	v_fmac_f32_e32 v23, v39, v181
	v_fmac_f32_e32 v23, v40, v182
	v_fmac_f32_e32 v23, v41, v183
	ds_read_b128 v[38:41], v43 offset:31744
	s_waitcnt lgkmcnt(3)
	v_fmac_f32_e32 v24, v2, v180
	v_fmac_f32_e32 v24, v3, v181
	v_fmac_f32_e32 v24, v4, v182
	v_fmac_f32_e32 v24, v5, v183
	ds_read_b128 v[2:5], v43 offset:35840
	s_waitcnt lgkmcnt(3)
	v_fmac_f32_e32 v25, v6, v180
	v_fmac_f32_e32 v25, v7, v181
	v_fmac_f32_e32 v25, v8, v182
	v_fmac_f32_e32 v25, v9, v183
	ds_read_b128 v[6:9], v43 offset:39936
	s_waitcnt lgkmcnt(3)
	v_fmac_f32_e32 v26, v10, v180
	v_fmac_f32_e32 v26, v11, v181
	v_fmac_f32_e32 v26, v12, v182
	v_fmac_f32_e32 v26, v13, v183
	ds_read_b128 v[10:13], v43 offset:44032
	s_waitcnt lgkmcnt(3)
	v_fmac_f32_e32 v27, v38, v180
	v_fmac_f32_e32 v27, v39, v181
	v_fmac_f32_e32 v27, v40, v182
	v_fmac_f32_e32 v27, v41, v183
	ds_read_b128 v[38:41], v43 offset:48128
	s_waitcnt lgkmcnt(3)
	v_fmac_f32_e32 v28, v2, v180
	v_fmac_f32_e32 v28, v3, v181
	v_fmac_f32_e32 v28, v4, v182
	v_fmac_f32_e32 v28, v5, v183
	ds_read_b128 v[2:5], v43 offset:52224
	s_waitcnt lgkmcnt(3)
	v_fmac_f32_e32 v29, v6, v180
	v_fmac_f32_e32 v29, v7, v181
	v_fmac_f32_e32 v29, v8, v182
	v_fmac_f32_e32 v29, v9, v183
	ds_read_b128 v[6:9], v43 offset:56320
	s_waitcnt lgkmcnt(3)
	v_fmac_f32_e32 v30, v10, v180
	v_fmac_f32_e32 v30, v11, v181
	v_fmac_f32_e32 v30, v12, v182
	v_fmac_f32_e32 v30, v13, v183
	ds_read_b128 v[10:13], v43 offset:60416
	s_waitcnt lgkmcnt(3)
	v_fmac_f32_e32 v31, v38, v180
	v_fmac_f32_e32 v31, v39, v181
	v_fmac_f32_e32 v31, v40, v182
	v_fmac_f32_e32 v31, v41, v183
	ds_read_b128 v[38:41], v43 offset:64512
	s_waitcnt lgkmcnt(3)
	v_fmac_f32_e32 v32, v2, v180
	v_fmac_f32_e32 v32, v3, v181
	v_fmac_f32_e32 v32, v4, v182
	v_fmac_f32_e32 v32, v5, v183
	ds_read_b128 v[2:5], v37 offset:3072
	s_waitcnt lgkmcnt(3)
	v_fmac_f32_e32 v33, v6, v180
	v_fmac_f32_e32 v33, v7, v181
	v_fmac_f32_e32 v33, v8, v182
	v_fmac_f32_e32 v33, v9, v183
	ds_read_b128 v[6:9], v43 offset:3088
	s_waitcnt lgkmcnt(3)
	v_fmac_f32_e32 v34, v10, v180
	v_fmac_f32_e32 v34, v11, v181
	v_fmac_f32_e32 v34, v12, v182
	v_fmac_f32_e32 v34, v13, v183
	ds_read_b128 v[10:13], v43 offset:7184
	s_waitcnt lgkmcnt(3)
	v_fmac_f32_e32 v35, v38, v180
	v_fmac_f32_e32 v35, v39, v181
	v_fmac_f32_e32 v35, v40, v182
	v_fmac_f32_e32 v35, v41, v183
	ds_read_b128 v[38:41], v43 offset:11280
	s_waitcnt lgkmcnt(3)
	v_fmac_f32_e32 v36, v2, v180
	v_fmac_f32_e32 v36, v3, v181
	v_fmac_f32_e32 v36, v4, v182
	v_fmac_f32_e32 v36, v5, v183
	ds_read_b128 v[2:5], v43 offset:15376
	s_waitcnt vmcnt(24)
	s_waitcnt lgkmcnt(3)
	v_fmac_f32_e32 v20, v6, v184
	v_fmac_f32_e32 v20, v7, v185
	v_fmac_f32_e32 v20, v8, v186
	v_fmac_f32_e32 v20, v9, v187
	ds_read_b128 v[6:9], v43 offset:19472
	s_waitcnt lgkmcnt(3)
	v_fmac_f32_e32 v21, v10, v184
	v_fmac_f32_e32 v21, v11, v185
	v_fmac_f32_e32 v21, v12, v186
	v_fmac_f32_e32 v21, v13, v187
	ds_read_b128 v[10:13], v43 offset:23568
	s_waitcnt lgkmcnt(3)
	v_fmac_f32_e32 v22, v38, v184
	v_fmac_f32_e32 v22, v39, v185
	v_fmac_f32_e32 v22, v40, v186
	v_fmac_f32_e32 v22, v41, v187
	ds_read_b128 v[38:41], v43 offset:27664
	s_waitcnt lgkmcnt(3)
	v_fmac_f32_e32 v23, v2, v184
	v_fmac_f32_e32 v23, v3, v185
	v_fmac_f32_e32 v23, v4, v186
	v_fmac_f32_e32 v23, v5, v187
	ds_read_b128 v[2:5], v43 offset:31760
	s_waitcnt lgkmcnt(3)
	v_fmac_f32_e32 v24, v6, v184
	v_fmac_f32_e32 v24, v7, v185
	v_fmac_f32_e32 v24, v8, v186
	v_fmac_f32_e32 v24, v9, v187
	ds_read_b128 v[6:9], v43 offset:35856
	s_waitcnt lgkmcnt(3)
	v_fmac_f32_e32 v25, v10, v184
	v_fmac_f32_e32 v25, v11, v185
	v_fmac_f32_e32 v25, v12, v186
	v_fmac_f32_e32 v25, v13, v187
	ds_read_b128 v[10:13], v43 offset:39952
	s_waitcnt lgkmcnt(3)
	v_fmac_f32_e32 v26, v38, v184
	v_fmac_f32_e32 v26, v39, v185
	v_fmac_f32_e32 v26, v40, v186
	v_fmac_f32_e32 v26, v41, v187
	ds_read_b128 v[38:41], v43 offset:44048
	s_waitcnt lgkmcnt(3)
	v_fmac_f32_e32 v27, v2, v184
	v_fmac_f32_e32 v27, v3, v185
	v_fmac_f32_e32 v27, v4, v186
	v_fmac_f32_e32 v27, v5, v187
	ds_read_b128 v[2:5], v43 offset:48144
	s_waitcnt lgkmcnt(3)
	v_fmac_f32_e32 v28, v6, v184
	v_fmac_f32_e32 v28, v7, v185
	v_fmac_f32_e32 v28, v8, v186
	v_fmac_f32_e32 v28, v9, v187
	ds_read_b128 v[6:9], v43 offset:52240
	s_waitcnt lgkmcnt(3)
	v_fmac_f32_e32 v29, v10, v184
	v_fmac_f32_e32 v29, v11, v185
	v_fmac_f32_e32 v29, v12, v186
	v_fmac_f32_e32 v29, v13, v187
	ds_read_b128 v[10:13], v43 offset:56336
	s_waitcnt lgkmcnt(3)
	v_fmac_f32_e32 v30, v38, v184
	v_fmac_f32_e32 v30, v39, v185
	v_fmac_f32_e32 v30, v40, v186
	v_fmac_f32_e32 v30, v41, v187
	ds_read_b128 v[38:41], v43 offset:60432
	s_waitcnt lgkmcnt(3)
	v_fmac_f32_e32 v31, v2, v184
	v_fmac_f32_e32 v31, v3, v185
	v_fmac_f32_e32 v31, v4, v186
	v_fmac_f32_e32 v31, v5, v187
	ds_read_b128 v[2:5], v43 offset:64528
	s_waitcnt lgkmcnt(3)
	v_fmac_f32_e32 v32, v6, v184
	v_fmac_f32_e32 v32, v7, v185
	v_fmac_f32_e32 v32, v8, v186
	v_fmac_f32_e32 v32, v9, v187
	ds_read_b128 v[6:9], v37 offset:3088
	s_waitcnt lgkmcnt(3)
	v_fmac_f32_e32 v33, v10, v184
	v_fmac_f32_e32 v33, v11, v185
	v_fmac_f32_e32 v33, v12, v186
	v_fmac_f32_e32 v33, v13, v187
	ds_read_b128 v[10:13], v43 offset:3104
	s_waitcnt lgkmcnt(3)
	v_fmac_f32_e32 v34, v38, v184
	v_fmac_f32_e32 v34, v39, v185
	v_fmac_f32_e32 v34, v40, v186
	v_fmac_f32_e32 v34, v41, v187
	ds_read_b128 v[38:41], v43 offset:7200
	s_waitcnt lgkmcnt(3)
	v_fmac_f32_e32 v35, v2, v184
	v_fmac_f32_e32 v35, v3, v185
	v_fmac_f32_e32 v35, v4, v186
	v_fmac_f32_e32 v35, v5, v187
	ds_read_b128 v[2:5], v43 offset:11296
	s_waitcnt lgkmcnt(3)
	v_fmac_f32_e32 v36, v6, v184
	v_fmac_f32_e32 v36, v7, v185
	v_fmac_f32_e32 v36, v8, v186
	v_fmac_f32_e32 v36, v9, v187
	ds_read_b128 v[6:9], v43 offset:15392
	s_waitcnt vmcnt(20)
	s_waitcnt lgkmcnt(3)
	v_fmac_f32_e32 v20, v10, v188
	v_fmac_f32_e32 v20, v11, v189
	v_fmac_f32_e32 v20, v12, v190
	v_fmac_f32_e32 v20, v13, v191
	ds_read_b128 v[10:13], v43 offset:19488
	s_waitcnt lgkmcnt(3)
	v_fmac_f32_e32 v21, v38, v188
	v_fmac_f32_e32 v21, v39, v189
	v_fmac_f32_e32 v21, v40, v190
	v_fmac_f32_e32 v21, v41, v191
	ds_read_b128 v[38:41], v43 offset:23584
	s_waitcnt lgkmcnt(3)
	v_fmac_f32_e32 v22, v2, v188
	v_fmac_f32_e32 v22, v3, v189
	v_fmac_f32_e32 v22, v4, v190
	v_fmac_f32_e32 v22, v5, v191
	ds_read_b128 v[2:5], v43 offset:27680
	s_waitcnt lgkmcnt(3)
	v_fmac_f32_e32 v23, v6, v188
	v_fmac_f32_e32 v23, v7, v189
	v_fmac_f32_e32 v23, v8, v190
	v_fmac_f32_e32 v23, v9, v191
	ds_read_b128 v[6:9], v43 offset:31776
	s_waitcnt lgkmcnt(3)
	v_fmac_f32_e32 v24, v10, v188
	v_fmac_f32_e32 v24, v11, v189
	v_fmac_f32_e32 v24, v12, v190
	v_fmac_f32_e32 v24, v13, v191
	ds_read_b128 v[10:13], v43 offset:35872
	s_waitcnt lgkmcnt(3)
	v_fmac_f32_e32 v25, v38, v188
	v_fmac_f32_e32 v25, v39, v189
	v_fmac_f32_e32 v25, v40, v190
	v_fmac_f32_e32 v25, v41, v191
	ds_read_b128 v[38:41], v43 offset:39968
	s_waitcnt lgkmcnt(3)
	v_fmac_f32_e32 v26, v2, v188
	v_fmac_f32_e32 v26, v3, v189
	v_fmac_f32_e32 v26, v4, v190
	v_fmac_f32_e32 v26, v5, v191
	ds_read_b128 v[2:5], v43 offset:44064
	s_waitcnt lgkmcnt(3)
	v_fmac_f32_e32 v27, v6, v188
	v_fmac_f32_e32 v27, v7, v189
	v_fmac_f32_e32 v27, v8, v190
	v_fmac_f32_e32 v27, v9, v191
	ds_read_b128 v[6:9], v43 offset:48160
	s_waitcnt lgkmcnt(3)
	v_fmac_f32_e32 v28, v10, v188
	v_fmac_f32_e32 v28, v11, v189
	v_fmac_f32_e32 v28, v12, v190
	v_fmac_f32_e32 v28, v13, v191
	ds_read_b128 v[10:13], v43 offset:52256
	s_waitcnt lgkmcnt(3)
	v_fmac_f32_e32 v29, v38, v188
	v_fmac_f32_e32 v29, v39, v189
	v_fmac_f32_e32 v29, v40, v190
	v_fmac_f32_e32 v29, v41, v191
	ds_read_b128 v[38:41], v43 offset:56352
	s_waitcnt lgkmcnt(3)
	v_fmac_f32_e32 v30, v2, v188
	v_fmac_f32_e32 v30, v3, v189
	v_fmac_f32_e32 v30, v4, v190
	v_fmac_f32_e32 v30, v5, v191
	ds_read_b128 v[2:5], v43 offset:60448
	s_waitcnt lgkmcnt(3)
	v_fmac_f32_e32 v31, v6, v188
	v_fmac_f32_e32 v31, v7, v189
	v_fmac_f32_e32 v31, v8, v190
	v_fmac_f32_e32 v31, v9, v191
	ds_read_b128 v[6:9], v43 offset:64544
	s_waitcnt lgkmcnt(3)
	v_fmac_f32_e32 v32, v10, v188
	v_fmac_f32_e32 v32, v11, v189
	v_fmac_f32_e32 v32, v12, v190
	v_fmac_f32_e32 v32, v13, v191
	ds_read_b128 v[10:13], v37 offset:3104
	s_waitcnt lgkmcnt(3)
	v_fmac_f32_e32 v33, v38, v188
	v_fmac_f32_e32 v33, v39, v189
	v_fmac_f32_e32 v33, v40, v190
	v_fmac_f32_e32 v33, v41, v191
	ds_read_b128 v[38:41], v43 offset:3120
	s_waitcnt lgkmcnt(3)
	v_fmac_f32_e32 v34, v2, v188
	v_fmac_f32_e32 v34, v3, v189
	v_fmac_f32_e32 v34, v4, v190
	v_fmac_f32_e32 v34, v5, v191
	ds_read_b128 v[2:5], v43 offset:7216
	s_waitcnt lgkmcnt(3)
	v_fmac_f32_e32 v35, v6, v188
	v_fmac_f32_e32 v35, v7, v189
	v_fmac_f32_e32 v35, v8, v190
	v_fmac_f32_e32 v35, v9, v191
	ds_read_b128 v[6:9], v43 offset:11312
	s_waitcnt lgkmcnt(3)
	v_fmac_f32_e32 v36, v10, v188
	v_fmac_f32_e32 v36, v11, v189
	v_fmac_f32_e32 v36, v12, v190
	v_fmac_f32_e32 v36, v13, v191
	ds_read_b128 v[10:13], v43 offset:15408
	s_waitcnt vmcnt(16)
	s_waitcnt lgkmcnt(3)
	v_fmac_f32_e32 v20, v38, v192
	v_fmac_f32_e32 v20, v39, v193
	v_fmac_f32_e32 v20, v40, v194
	v_fmac_f32_e32 v20, v41, v195
	ds_read_b128 v[38:41], v43 offset:19504
	s_waitcnt lgkmcnt(3)
	v_fmac_f32_e32 v21, v2, v192
	v_fmac_f32_e32 v21, v3, v193
	v_fmac_f32_e32 v21, v4, v194
	v_fmac_f32_e32 v21, v5, v195
	ds_read_b128 v[2:5], v43 offset:23600
	s_waitcnt lgkmcnt(3)
	v_fmac_f32_e32 v22, v6, v192
	v_fmac_f32_e32 v22, v7, v193
	v_fmac_f32_e32 v22, v8, v194
	v_fmac_f32_e32 v22, v9, v195
	ds_read_b128 v[6:9], v43 offset:27696
	s_waitcnt lgkmcnt(3)
	v_fmac_f32_e32 v23, v10, v192
	v_fmac_f32_e32 v23, v11, v193
	v_fmac_f32_e32 v23, v12, v194
	v_fmac_f32_e32 v23, v13, v195
	ds_read_b128 v[10:13], v43 offset:31792
	s_waitcnt lgkmcnt(3)
	v_fmac_f32_e32 v24, v38, v192
	v_fmac_f32_e32 v24, v39, v193
	v_fmac_f32_e32 v24, v40, v194
	v_fmac_f32_e32 v24, v41, v195
	ds_read_b128 v[38:41], v43 offset:35888
	s_waitcnt lgkmcnt(3)
	v_fmac_f32_e32 v25, v2, v192
	v_fmac_f32_e32 v25, v3, v193
	v_fmac_f32_e32 v25, v4, v194
	v_fmac_f32_e32 v25, v5, v195
	ds_read_b128 v[2:5], v43 offset:39984
	s_waitcnt lgkmcnt(3)
	v_fmac_f32_e32 v26, v6, v192
	v_fmac_f32_e32 v26, v7, v193
	v_fmac_f32_e32 v26, v8, v194
	v_fmac_f32_e32 v26, v9, v195
	ds_read_b128 v[6:9], v43 offset:44080
	s_waitcnt lgkmcnt(3)
	v_fmac_f32_e32 v27, v10, v192
	v_fmac_f32_e32 v27, v11, v193
	v_fmac_f32_e32 v27, v12, v194
	v_fmac_f32_e32 v27, v13, v195
	ds_read_b128 v[10:13], v43 offset:48176
	s_waitcnt lgkmcnt(3)
	v_fmac_f32_e32 v28, v38, v192
	v_fmac_f32_e32 v28, v39, v193
	v_fmac_f32_e32 v28, v40, v194
	v_fmac_f32_e32 v28, v41, v195
	ds_read_b128 v[38:41], v43 offset:52272
	s_waitcnt lgkmcnt(3)
	v_fmac_f32_e32 v29, v2, v192
	v_fmac_f32_e32 v29, v3, v193
	v_fmac_f32_e32 v29, v4, v194
	v_fmac_f32_e32 v29, v5, v195
	ds_read_b128 v[2:5], v43 offset:56368
	s_waitcnt lgkmcnt(3)
	v_fmac_f32_e32 v30, v6, v192
	v_fmac_f32_e32 v30, v7, v193
	v_fmac_f32_e32 v30, v8, v194
	v_fmac_f32_e32 v30, v9, v195
	ds_read_b128 v[6:9], v43 offset:60464
	s_waitcnt lgkmcnt(3)
	v_fmac_f32_e32 v31, v10, v192
	v_fmac_f32_e32 v31, v11, v193
	v_fmac_f32_e32 v31, v12, v194
	v_fmac_f32_e32 v31, v13, v195
	ds_read_b128 v[10:13], v43 offset:64560
	s_waitcnt lgkmcnt(3)
	v_fmac_f32_e32 v32, v38, v192
	v_fmac_f32_e32 v32, v39, v193
	v_fmac_f32_e32 v32, v40, v194
	v_fmac_f32_e32 v32, v41, v195
	ds_read_b128 v[38:41], v37 offset:3120
	s_waitcnt lgkmcnt(3)
	v_fmac_f32_e32 v33, v2, v192
	v_fmac_f32_e32 v33, v3, v193
	v_fmac_f32_e32 v33, v4, v194
	v_fmac_f32_e32 v33, v5, v195
	ds_read_b128 v[2:5], v43 offset:3136
	s_waitcnt lgkmcnt(3)
	v_fmac_f32_e32 v34, v6, v192
	v_fmac_f32_e32 v34, v7, v193
	v_fmac_f32_e32 v34, v8, v194
	v_fmac_f32_e32 v34, v9, v195
	ds_read_b128 v[6:9], v43 offset:7232
	s_waitcnt lgkmcnt(3)
	v_fmac_f32_e32 v35, v10, v192
	v_fmac_f32_e32 v35, v11, v193
	v_fmac_f32_e32 v35, v12, v194
	v_fmac_f32_e32 v35, v13, v195
	ds_read_b128 v[10:13], v43 offset:11328
	s_waitcnt lgkmcnt(3)
	v_fmac_f32_e32 v36, v38, v192
	v_fmac_f32_e32 v36, v39, v193
	v_fmac_f32_e32 v36, v40, v194
	v_fmac_f32_e32 v36, v41, v195
	ds_read_b128 v[38:41], v43 offset:15424
	s_waitcnt vmcnt(12)
	s_waitcnt lgkmcnt(3)
	v_fmac_f32_e32 v20, v2, v196
	v_fmac_f32_e32 v20, v3, v197
	v_fmac_f32_e32 v20, v4, v198
	v_fmac_f32_e32 v20, v5, v199
	ds_read_b128 v[2:5], v43 offset:19520
	s_waitcnt lgkmcnt(3)
	v_fmac_f32_e32 v21, v6, v196
	v_fmac_f32_e32 v21, v7, v197
	v_fmac_f32_e32 v21, v8, v198
	v_fmac_f32_e32 v21, v9, v199
	ds_read_b128 v[6:9], v43 offset:23616
	s_waitcnt lgkmcnt(3)
	v_fmac_f32_e32 v22, v10, v196
	v_fmac_f32_e32 v22, v11, v197
	v_fmac_f32_e32 v22, v12, v198
	v_fmac_f32_e32 v22, v13, v199
	ds_read_b128 v[10:13], v43 offset:27712
	s_waitcnt lgkmcnt(3)
	v_fmac_f32_e32 v23, v38, v196
	v_fmac_f32_e32 v23, v39, v197
	v_fmac_f32_e32 v23, v40, v198
	v_fmac_f32_e32 v23, v41, v199
	ds_read_b128 v[38:41], v43 offset:31808
	s_waitcnt lgkmcnt(3)
	v_fmac_f32_e32 v24, v2, v196
	v_fmac_f32_e32 v24, v3, v197
	v_fmac_f32_e32 v24, v4, v198
	v_fmac_f32_e32 v24, v5, v199
	ds_read_b128 v[2:5], v43 offset:35904
	s_waitcnt lgkmcnt(3)
	v_fmac_f32_e32 v25, v6, v196
	v_fmac_f32_e32 v25, v7, v197
	v_fmac_f32_e32 v25, v8, v198
	v_fmac_f32_e32 v25, v9, v199
	ds_read_b128 v[6:9], v43 offset:40000
	s_waitcnt lgkmcnt(3)
	v_fmac_f32_e32 v26, v10, v196
	v_fmac_f32_e32 v26, v11, v197
	v_fmac_f32_e32 v26, v12, v198
	v_fmac_f32_e32 v26, v13, v199
	ds_read_b128 v[10:13], v43 offset:44096
	s_waitcnt lgkmcnt(3)
	v_fmac_f32_e32 v27, v38, v196
	v_fmac_f32_e32 v27, v39, v197
	v_fmac_f32_e32 v27, v40, v198
	v_fmac_f32_e32 v27, v41, v199
	ds_read_b128 v[38:41], v43 offset:48192
	s_waitcnt lgkmcnt(3)
	v_fmac_f32_e32 v28, v2, v196
	v_fmac_f32_e32 v28, v3, v197
	v_fmac_f32_e32 v28, v4, v198
	v_fmac_f32_e32 v28, v5, v199
	ds_read_b128 v[2:5], v43 offset:52288
	s_waitcnt lgkmcnt(3)
	v_fmac_f32_e32 v29, v6, v196
	v_fmac_f32_e32 v29, v7, v197
	v_fmac_f32_e32 v29, v8, v198
	v_fmac_f32_e32 v29, v9, v199
	ds_read_b128 v[6:9], v43 offset:56384
	s_waitcnt lgkmcnt(3)
	v_fmac_f32_e32 v30, v10, v196
	v_fmac_f32_e32 v30, v11, v197
	v_fmac_f32_e32 v30, v12, v198
	v_fmac_f32_e32 v30, v13, v199
	ds_read_b128 v[10:13], v43 offset:60480
	s_waitcnt lgkmcnt(3)
	v_fmac_f32_e32 v31, v38, v196
	v_fmac_f32_e32 v31, v39, v197
	v_fmac_f32_e32 v31, v40, v198
	v_fmac_f32_e32 v31, v41, v199
	ds_read_b128 v[38:41], v43 offset:64576
	s_waitcnt lgkmcnt(3)
	v_fmac_f32_e32 v32, v2, v196
	v_fmac_f32_e32 v32, v3, v197
	v_fmac_f32_e32 v32, v4, v198
	v_fmac_f32_e32 v32, v5, v199
	ds_read_b128 v[2:5], v37 offset:3136
	s_waitcnt lgkmcnt(3)
	v_fmac_f32_e32 v33, v6, v196
	v_fmac_f32_e32 v33, v7, v197
	v_fmac_f32_e32 v33, v8, v198
	v_fmac_f32_e32 v33, v9, v199
	ds_read_b128 v[6:9], v43 offset:3152
	s_waitcnt lgkmcnt(3)
	v_fmac_f32_e32 v34, v10, v196
	v_fmac_f32_e32 v34, v11, v197
	v_fmac_f32_e32 v34, v12, v198
	v_fmac_f32_e32 v34, v13, v199
	ds_read_b128 v[10:13], v43 offset:7248
	s_waitcnt lgkmcnt(3)
	v_fmac_f32_e32 v35, v38, v196
	v_fmac_f32_e32 v35, v39, v197
	v_fmac_f32_e32 v35, v40, v198
	v_fmac_f32_e32 v35, v41, v199
	ds_read_b128 v[38:41], v43 offset:11344
	s_waitcnt lgkmcnt(3)
	v_fmac_f32_e32 v36, v2, v196
	v_fmac_f32_e32 v36, v3, v197
	v_fmac_f32_e32 v36, v4, v198
	v_fmac_f32_e32 v36, v5, v199
	ds_read_b128 v[2:5], v43 offset:15440
	s_waitcnt vmcnt(8)
	s_waitcnt lgkmcnt(3)
	v_fmac_f32_e32 v20, v6, v200
	v_fmac_f32_e32 v20, v7, v201
	v_fmac_f32_e32 v20, v8, v202
	v_fmac_f32_e32 v20, v9, v203
	ds_read_b128 v[6:9], v43 offset:19536
	s_waitcnt lgkmcnt(3)
	v_fmac_f32_e32 v21, v10, v200
	v_fmac_f32_e32 v21, v11, v201
	v_fmac_f32_e32 v21, v12, v202
	v_fmac_f32_e32 v21, v13, v203
	ds_read_b128 v[10:13], v43 offset:23632
	s_waitcnt lgkmcnt(3)
	v_fmac_f32_e32 v22, v38, v200
	v_fmac_f32_e32 v22, v39, v201
	v_fmac_f32_e32 v22, v40, v202
	v_fmac_f32_e32 v22, v41, v203
	ds_read_b128 v[38:41], v43 offset:27728
	s_waitcnt lgkmcnt(3)
	v_fmac_f32_e32 v23, v2, v200
	v_fmac_f32_e32 v23, v3, v201
	v_fmac_f32_e32 v23, v4, v202
	v_fmac_f32_e32 v23, v5, v203
	ds_read_b128 v[2:5], v43 offset:31824
	s_waitcnt lgkmcnt(3)
	v_fmac_f32_e32 v24, v6, v200
	v_fmac_f32_e32 v24, v7, v201
	v_fmac_f32_e32 v24, v8, v202
	v_fmac_f32_e32 v24, v9, v203
	ds_read_b128 v[6:9], v43 offset:35920
	s_waitcnt lgkmcnt(3)
	v_fmac_f32_e32 v25, v10, v200
	v_fmac_f32_e32 v25, v11, v201
	v_fmac_f32_e32 v25, v12, v202
	v_fmac_f32_e32 v25, v13, v203
	ds_read_b128 v[10:13], v43 offset:40016
	s_waitcnt lgkmcnt(3)
	v_fmac_f32_e32 v26, v38, v200
	v_fmac_f32_e32 v26, v39, v201
	v_fmac_f32_e32 v26, v40, v202
	v_fmac_f32_e32 v26, v41, v203
	ds_read_b128 v[38:41], v43 offset:44112
	s_waitcnt lgkmcnt(3)
	v_fmac_f32_e32 v27, v2, v200
	v_fmac_f32_e32 v27, v3, v201
	v_fmac_f32_e32 v27, v4, v202
	v_fmac_f32_e32 v27, v5, v203
	ds_read_b128 v[2:5], v43 offset:48208
	s_waitcnt lgkmcnt(3)
	v_fmac_f32_e32 v28, v6, v200
	v_fmac_f32_e32 v28, v7, v201
	v_fmac_f32_e32 v28, v8, v202
	v_fmac_f32_e32 v28, v9, v203
	ds_read_b128 v[6:9], v43 offset:52304
	s_waitcnt lgkmcnt(3)
	v_fmac_f32_e32 v29, v10, v200
	v_fmac_f32_e32 v29, v11, v201
	v_fmac_f32_e32 v29, v12, v202
	v_fmac_f32_e32 v29, v13, v203
	ds_read_b128 v[10:13], v43 offset:56400
	s_waitcnt lgkmcnt(3)
	v_fmac_f32_e32 v30, v38, v200
	v_fmac_f32_e32 v30, v39, v201
	v_fmac_f32_e32 v30, v40, v202
	v_fmac_f32_e32 v30, v41, v203
	ds_read_b128 v[38:41], v43 offset:60496
	s_waitcnt lgkmcnt(3)
	v_fmac_f32_e32 v31, v2, v200
	v_fmac_f32_e32 v31, v3, v201
	v_fmac_f32_e32 v31, v4, v202
	v_fmac_f32_e32 v31, v5, v203
	ds_read_b128 v[2:5], v43 offset:64592
	s_waitcnt lgkmcnt(3)
	v_fmac_f32_e32 v32, v6, v200
	v_fmac_f32_e32 v32, v7, v201
	v_fmac_f32_e32 v32, v8, v202
	v_fmac_f32_e32 v32, v9, v203
	ds_read_b128 v[6:9], v37 offset:3152
	s_waitcnt lgkmcnt(3)
	v_fmac_f32_e32 v33, v10, v200
	v_fmac_f32_e32 v33, v11, v201
	v_fmac_f32_e32 v33, v12, v202
	v_fmac_f32_e32 v33, v13, v203
	ds_read_b128 v[10:13], v43 offset:3168
	s_waitcnt lgkmcnt(3)
	v_fmac_f32_e32 v34, v38, v200
	v_fmac_f32_e32 v34, v39, v201
	v_fmac_f32_e32 v34, v40, v202
	v_fmac_f32_e32 v34, v41, v203
	ds_read_b128 v[38:41], v43 offset:7264
	s_waitcnt lgkmcnt(3)
	v_fmac_f32_e32 v35, v2, v200
	v_fmac_f32_e32 v35, v3, v201
	v_fmac_f32_e32 v35, v4, v202
	v_fmac_f32_e32 v35, v5, v203
	ds_read_b128 v[2:5], v43 offset:11360
	s_waitcnt lgkmcnt(3)
	v_fmac_f32_e32 v36, v6, v200
	v_fmac_f32_e32 v36, v7, v201
	v_fmac_f32_e32 v36, v8, v202
	v_fmac_f32_e32 v36, v9, v203
	ds_read_b128 v[6:9], v43 offset:15456
	s_waitcnt vmcnt(4)
	s_waitcnt lgkmcnt(3)
	v_fmac_f32_e32 v20, v10, v204
	v_fmac_f32_e32 v20, v11, v205
	v_fmac_f32_e32 v20, v12, v206
	v_fmac_f32_e32 v20, v13, v207
	ds_read_b128 v[10:13], v43 offset:19552
	s_waitcnt lgkmcnt(3)
	v_fmac_f32_e32 v21, v38, v204
	v_fmac_f32_e32 v21, v39, v205
	v_fmac_f32_e32 v21, v40, v206
	v_fmac_f32_e32 v21, v41, v207
	ds_read_b128 v[38:41], v43 offset:23648
	s_waitcnt lgkmcnt(3)
	v_fmac_f32_e32 v22, v2, v204
	v_fmac_f32_e32 v22, v3, v205
	v_fmac_f32_e32 v22, v4, v206
	v_fmac_f32_e32 v22, v5, v207
	ds_read_b128 v[2:5], v43 offset:27744
	s_waitcnt lgkmcnt(3)
	v_fmac_f32_e32 v23, v6, v204
	v_fmac_f32_e32 v23, v7, v205
	v_fmac_f32_e32 v23, v8, v206
	v_fmac_f32_e32 v23, v9, v207
	ds_read_b128 v[6:9], v43 offset:31840
	s_waitcnt lgkmcnt(3)
	v_fmac_f32_e32 v24, v10, v204
	v_fmac_f32_e32 v24, v11, v205
	v_fmac_f32_e32 v24, v12, v206
	v_fmac_f32_e32 v24, v13, v207
	ds_read_b128 v[10:13], v43 offset:35936
	s_waitcnt lgkmcnt(3)
	v_fmac_f32_e32 v25, v38, v204
	v_fmac_f32_e32 v25, v39, v205
	v_fmac_f32_e32 v25, v40, v206
	v_fmac_f32_e32 v25, v41, v207
	ds_read_b128 v[38:41], v43 offset:40032
	s_waitcnt lgkmcnt(3)
	v_fmac_f32_e32 v26, v2, v204
	v_fmac_f32_e32 v26, v3, v205
	v_fmac_f32_e32 v26, v4, v206
	v_fmac_f32_e32 v26, v5, v207
	ds_read_b128 v[2:5], v43 offset:44128
	s_waitcnt lgkmcnt(3)
	v_fmac_f32_e32 v27, v6, v204
	v_fmac_f32_e32 v27, v7, v205
	v_fmac_f32_e32 v27, v8, v206
	v_fmac_f32_e32 v27, v9, v207
	ds_read_b128 v[6:9], v43 offset:48224
	s_waitcnt lgkmcnt(3)
	v_fmac_f32_e32 v28, v10, v204
	v_fmac_f32_e32 v28, v11, v205
	v_fmac_f32_e32 v28, v12, v206
	v_fmac_f32_e32 v28, v13, v207
	ds_read_b128 v[10:13], v43 offset:52320
	s_waitcnt lgkmcnt(3)
	v_fmac_f32_e32 v29, v38, v204
	v_fmac_f32_e32 v29, v39, v205
	v_fmac_f32_e32 v29, v40, v206
	v_fmac_f32_e32 v29, v41, v207
	ds_read_b128 v[38:41], v43 offset:56416
	s_waitcnt lgkmcnt(3)
	v_fmac_f32_e32 v30, v2, v204
	v_fmac_f32_e32 v30, v3, v205
	v_fmac_f32_e32 v30, v4, v206
	v_fmac_f32_e32 v30, v5, v207
	ds_read_b128 v[2:5], v43 offset:60512
	s_waitcnt lgkmcnt(3)
	v_fmac_f32_e32 v31, v6, v204
	v_fmac_f32_e32 v31, v7, v205
	v_fmac_f32_e32 v31, v8, v206
	v_fmac_f32_e32 v31, v9, v207
	ds_read_b128 v[6:9], v43 offset:64608
	s_waitcnt lgkmcnt(3)
	v_fmac_f32_e32 v32, v10, v204
	v_fmac_f32_e32 v32, v11, v205
	v_fmac_f32_e32 v32, v12, v206
	v_fmac_f32_e32 v32, v13, v207
	ds_read_b128 v[10:13], v37 offset:3168
	s_waitcnt lgkmcnt(3)
	v_fmac_f32_e32 v33, v38, v204
	v_fmac_f32_e32 v33, v39, v205
	v_fmac_f32_e32 v33, v40, v206
	v_fmac_f32_e32 v33, v41, v207
	ds_read_b128 v[38:41], v43 offset:3184
	s_waitcnt lgkmcnt(3)
	v_fmac_f32_e32 v34, v2, v204
	v_fmac_f32_e32 v34, v3, v205
	v_fmac_f32_e32 v34, v4, v206
	v_fmac_f32_e32 v34, v5, v207
	ds_read_b128 v[2:5], v43 offset:7280
	s_waitcnt lgkmcnt(3)
	v_fmac_f32_e32 v35, v6, v204
	v_fmac_f32_e32 v35, v7, v205
	v_fmac_f32_e32 v35, v8, v206
	v_fmac_f32_e32 v35, v9, v207
	ds_read_b128 v[6:9], v43 offset:11376
	s_waitcnt lgkmcnt(3)
	v_fmac_f32_e32 v36, v10, v204
	v_fmac_f32_e32 v36, v11, v205
	v_fmac_f32_e32 v36, v12, v206
	v_fmac_f32_e32 v36, v13, v207
	ds_read_b128 v[10:13], v43 offset:15472
	s_waitcnt vmcnt(0)
	s_waitcnt lgkmcnt(3)
	v_fmac_f32_e32 v20, v38, v208
	v_fmac_f32_e32 v20, v39, v209
	v_fmac_f32_e32 v20, v40, v210
	v_fmac_f32_e32 v20, v41, v211
	ds_read_b128 v[38:41], v43 offset:19568
	s_waitcnt lgkmcnt(3)
	v_fmac_f32_e32 v21, v2, v208
	v_fmac_f32_e32 v21, v3, v209
	v_fmac_f32_e32 v21, v4, v210
	v_fmac_f32_e32 v21, v5, v211
	ds_read_b128 v[2:5], v43 offset:23664
	s_waitcnt lgkmcnt(3)
	v_fmac_f32_e32 v22, v6, v208
	v_fmac_f32_e32 v22, v7, v209
	v_fmac_f32_e32 v22, v8, v210
	v_fmac_f32_e32 v22, v9, v211
	ds_read_b128 v[6:9], v43 offset:27760
	s_waitcnt lgkmcnt(3)
	v_fmac_f32_e32 v23, v10, v208
	v_fmac_f32_e32 v23, v11, v209
	v_fmac_f32_e32 v23, v12, v210
	v_fmac_f32_e32 v23, v13, v211
	ds_read_b128 v[10:13], v43 offset:31856
	s_waitcnt lgkmcnt(3)
	v_fmac_f32_e32 v24, v38, v208
	v_fmac_f32_e32 v24, v39, v209
	v_fmac_f32_e32 v24, v40, v210
	v_fmac_f32_e32 v24, v41, v211
	ds_read_b128 v[38:41], v43 offset:35952
	s_waitcnt lgkmcnt(3)
	v_fmac_f32_e32 v25, v2, v208
	v_fmac_f32_e32 v25, v3, v209
	v_fmac_f32_e32 v25, v4, v210
	v_fmac_f32_e32 v25, v5, v211
	ds_read_b128 v[2:5], v43 offset:40048
	s_waitcnt lgkmcnt(3)
	v_fmac_f32_e32 v26, v6, v208
	v_fmac_f32_e32 v26, v7, v209
	v_fmac_f32_e32 v26, v8, v210
	v_fmac_f32_e32 v26, v9, v211
	ds_read_b128 v[6:9], v43 offset:44144
	s_waitcnt lgkmcnt(3)
	v_fmac_f32_e32 v27, v10, v208
	v_fmac_f32_e32 v27, v11, v209
	v_fmac_f32_e32 v27, v12, v210
	v_fmac_f32_e32 v27, v13, v211
	ds_read_b128 v[10:13], v43 offset:48240
	s_waitcnt lgkmcnt(3)
	v_fmac_f32_e32 v28, v38, v208
	v_fmac_f32_e32 v28, v39, v209
	v_fmac_f32_e32 v28, v40, v210
	v_fmac_f32_e32 v28, v41, v211
	ds_read_b128 v[38:41], v43 offset:52336
	s_waitcnt lgkmcnt(3)
	v_fmac_f32_e32 v29, v2, v208
	v_fmac_f32_e32 v29, v3, v209
	v_fmac_f32_e32 v29, v4, v210
	v_fmac_f32_e32 v29, v5, v211
	ds_read_b128 v[2:5], v43 offset:56432
	s_waitcnt lgkmcnt(3)
	v_fmac_f32_e32 v30, v6, v208
	v_fmac_f32_e32 v30, v7, v209
	v_fmac_f32_e32 v30, v8, v210
	v_fmac_f32_e32 v30, v9, v211
	ds_read_b128 v[6:9], v43 offset:60528
	s_waitcnt lgkmcnt(3)
	v_fmac_f32_e32 v31, v10, v208
	v_fmac_f32_e32 v31, v11, v209
	v_fmac_f32_e32 v31, v12, v210
	v_fmac_f32_e32 v31, v13, v211
	ds_read_b128 v[10:13], v43 offset:64624
	s_waitcnt lgkmcnt(3)
	v_fmac_f32_e32 v32, v38, v208
	v_fmac_f32_e32 v32, v39, v209
	v_fmac_f32_e32 v32, v40, v210
	v_fmac_f32_e32 v32, v41, v211
	ds_read_b128 v[38:41], v37 offset:3184
	s_waitcnt lgkmcnt(3)
	v_fmac_f32_e32 v33, v2, v208
	v_fmac_f32_e32 v33, v3, v209
	v_fmac_f32_e32 v33, v4, v210
	v_fmac_f32_e32 v33, v5, v211
	s_waitcnt lgkmcnt(2)
	v_fmac_f32_e32 v34, v6, v208
	v_fmac_f32_e32 v34, v7, v209
	v_fmac_f32_e32 v34, v8, v210
	v_fmac_f32_e32 v34, v9, v211
	s_waitcnt lgkmcnt(1)
	v_fmac_f32_e32 v35, v10, v208
	v_fmac_f32_e32 v35, v11, v209
	v_fmac_f32_e32 v35, v12, v210
	v_fmac_f32_e32 v35, v13, v211
	s_waitcnt lgkmcnt(0)
	v_fmac_f32_e32 v36, v38, v208
	v_fmac_f32_e32 v36, v39, v209
	v_fmac_f32_e32 v36, v40, v210
	v_fmac_f32_e32 v36, v41, v211
	v_mul_u32_u24_e32 v2, 0x1100, v18
	v_lshl_add_u32 v2, v17, 2, v2
	v_add_u32_e32 v2, 0x11000, v2
	ds_write_b32 v2, v20 offset:0
	ds_write_b32 v2, v21 offset:256
	ds_write_b32 v2, v22 offset:512
	ds_write_b32 v2, v23 offset:768
	ds_write_b32 v2, v24 offset:1024
	ds_write_b32 v2, v25 offset:1280
	ds_write_b32 v2, v26 offset:1536
	ds_write_b32 v2, v27 offset:1792
	ds_write_b32 v2, v28 offset:2048
	ds_write_b32 v2, v29 offset:2304
	ds_write_b32 v2, v30 offset:2560
	ds_write_b32 v2, v31 offset:2816
	ds_write_b32 v2, v32 offset:3072
	ds_write_b32 v2, v33 offset:3328
	ds_write_b32 v2, v34 offset:3584
	ds_write_b32 v2, v35 offset:3840
	ds_write_b32 v2, v36 offset:4096
	s_waitcnt lgkmcnt(0)
	s_barrier
	v_readlane_b32 s78, v254, 47
	v_readlane_b32 s79, v254, 48
	v_readlane_b32 s82, v254, 14
	v_readlane_b32 s83, v254, 15
	s_mul_i32 s7, s5, 0x6000
	s_add_i32 s7, s7, s6
	s_add_u32 s78, s78, s7
	s_addc_u32 s79, s79, 0
	s_mul_i32 s7, s5, 0x66000
	s_add_i32 s7, s7, s6
	s_add_u32 s82, s82, s7
	s_addc_u32 s83, s83, 0
	v_lshlrev_b32_e32 v3, 2, v17
	global_load_dword v4, v3, s[78:79]
	v_readfirstlane_b32 s4, v18
	v_add_u32_e32 v5, 0x11000, v16
	ds_read_b32 v6, v5 offset:0
	ds_read_b32 v7, v5 offset:4352
	ds_read_b32 v8, v5 offset:8704
	ds_read_b32 v9, v5 offset:13056
	ds_read_b32 v10, v5 offset:17408
	ds_read_b32 v11, v5 offset:21760
	ds_read_b32 v12, v5 offset:26112
	ds_read_b32 v13, v5 offset:30464
	v_add_u32_e32 v38, 0, v18
	v_mul_u32_u24_e32 v38, 0x6000, v38
	v_add_u32_e32 v38, v38, v3
	s_waitcnt lgkmcnt(0)
	v_add_f32_e32 v6, 0, v6
	v_add_f32_e32 v6, v6, v7
	v_add_f32_e32 v6, v6, v8
	v_add_f32_e32 v6, v6, v9
	v_add_f32_e32 v6, v6, v10
	v_add_f32_e32 v6, v6, v11
	v_add_f32_e32 v6, v6, v12
	v_add_f32_e32 v6, v6, v13
	s_waitcnt vmcnt(0)
	v_add_f32_e32 v6, v6, v4
	global_store_dword v38, v6, s[82:83]
	v_add_u32_e32 v5, 0x11800, v16
	ds_read_b32 v6, v5 offset:0
	ds_read_b32 v7, v5 offset:4352
	ds_read_b32 v8, v5 offset:8704
	ds_read_b32 v9, v5 offset:13056
	ds_read_b32 v10, v5 offset:17408
	ds_read_b32 v11, v5 offset:21760
	ds_read_b32 v12, v5 offset:26112
	ds_read_b32 v13, v5 offset:30464
	v_add_u32_e32 v38, 8, v18
	v_mul_u32_u24_e32 v38, 0x6000, v38
	v_add_u32_e32 v38, v38, v3
	s_waitcnt lgkmcnt(0)
	v_add_f32_e32 v6, 0, v6
	v_add_f32_e32 v6, v6, v7
	v_add_f32_e32 v6, v6, v8
	v_add_f32_e32 v6, v6, v9
	v_add_f32_e32 v6, v6, v10
	v_add_f32_e32 v6, v6, v11
	v_add_f32_e32 v6, v6, v12
	v_add_f32_e32 v6, v6, v13
	v_add_f32_e32 v6, v6, v4
	global_store_dword v38, v6, s[82:83]
	s_cmp_lg_u32 s4, 0
	s_cbranch_scc1 .Ladaln_done
	v_add_u32_e32 v5, 0x12000, v16
	ds_read_b32 v6, v5 offset:0
	ds_read_b32 v7, v5 offset:4352
	ds_read_b32 v8, v5 offset:8704
	ds_read_b32 v9, v5 offset:13056
	ds_read_b32 v10, v5 offset:17408
	ds_read_b32 v11, v5 offset:21760
	ds_read_b32 v12, v5 offset:26112
	ds_read_b32 v13, v5 offset:30464
	v_add_u32_e32 v38, 16, v18
	v_mul_u32_u24_e32 v38, 0x6000, v38
	v_add_u32_e32 v38, v38, v3
	s_waitcnt lgkmcnt(0)
	v_add_f32_e32 v6, 0, v6
	v_add_f32_e32 v6, v6, v7
	v_add_f32_e32 v6, v6, v8
	v_add_f32_e32 v6, v6, v9
	v_add_f32_e32 v6, v6, v10
	v_add_f32_e32 v6, v6, v11
	v_add_f32_e32 v6, v6, v12
	v_add_f32_e32 v6, v6, v13
	v_add_f32_e32 v6, v6, v4
	global_store_dword v38, v6, s[82:83]
.Ladaln_done:
	s_waitcnt vmcnt(0)
	v_readlane_b32 s68, v254, 37
	v_readlane_b32 s69, v254, 38
	v_readlane_b32 s70, v254, 39
	v_readlane_b32 s71, v254, 40
	v_readlane_b32 s72, v254, 41
	v_readlane_b32 s73, v254, 42
	v_readlane_b32 s74, v254, 43
	v_readlane_b32 s75, v254, 44
	v_readlane_b32 s76, v254, 45
	v_readlane_b32 s77, v254, 46
	v_readlane_b32 s78, v254, 47
	v_readlane_b32 s79, v254, 48
	v_readlane_b32 s80, v254, 49
	v_readlane_b32 s81, v254, 50
	v_readlane_b32 s82, v254, 51
	v_readlane_b32 s83, v254, 52
	s_mov_b64 s[0:1], -1
	s_branch .LBB0_8
